# asymmetric workgroup priorities only in the GEMM phases with 8-9 tiles per workgroup (1, 8, 11, 17); symmetric stage-top priority toggle in the 1-2 tile phases
# baseline (speedup 1.0000x reference)
; #define LWRITE(S, buf) do { bf16_t* sA_ = sbase + (buf) * BUF; bf16_t* sB_ = sA_ + 256 * PITCH; \
;     _Pragma("unroll") for (int i_ = 0; i_ < 4; ++i_) *(u32x4*)(sA_ + (sr + i_ * 64) * PITCH + scv * 8) = ra[S][i_]; \
;     _Pragma("unroll") for (int i_ = 0; i_ < 2; ++i_) *(u32x4*)(sB_ + (sr + i_ * 64) * PITCH + scv * 8) = rb[S][i_]; } while (0)
; template <class Epi>
; DI void gemm_tile(char* smem, const bf16_t* __restrict__ A0, int lda0, int ksplit, const bf16_t* __restrict__ A1, int lda1,
;                   const bf16_t* __restrict__ Bt, int K, int row0, int col0, const Epi& epi, int tid) {
;   constexpr int BK = 32, PITCH = 40, BUF = (256 + 128) * PITCH;
;   bf16_t* sbase = (bf16_t*)smem;
;   const int lane = tid & 63, wid = tid >> 6, wr = wid >> 1, wc = wid & 1, fr = lane & 15, fq = lane >> 4;
;   f32x4 acc[8][4];
; #pragma unroll
;   for (int m = 0; m < 8; ++m)
; #pragma unroll
;     for (int n = 0; n < 4; ++n) acc[m][n] = (f32x4){0.f, 0.f, 0.f, 0.f};
;   u32x4 ra[2][4], rb[2][2];
;   const int nk = K / BK;
;   const int sr = tid >> 2, scv = tid & 3;
;     ...
;   __syncthreads();
;   {
;     const int last = nk - 1;
;     GLOAD(0, 0);
;     __builtin_amdgcn_sched_barrier(0);
;     GLOAD(1, 1);
;     __builtin_amdgcn_sched_barrier(0);
;     LWRITE(0, 0);
;     __builtin_amdgcn_sched_barrier(0);
;     GLOAD(0, (2 < last ? 2 : last));
;     __builtin_amdgcn_sched_barrier(0);
;     __syncthreads();
; template <class Epi>
; DI void gemm_phase(char* smem, const bf16_t* A0, int lda0, int ksplit, const bf16_t* A1, int lda1, const bf16_t* Bt, int K, int nN, const Epi& epi, int tid) {
;     ...
;     const int x = blockIdx.x & 7, l = blockIdx.x >> 3, L = G >> 3, per = 8 * nN, tot = 2 * per;
;     for (int q = l; q < tot; q += L) { const int rgl = q / per, rem = q % per, ct = rem >> 3, rt = (x * 2 + rgl) * 8 + (rem & 7);
;       gemm_tile(smem, A0, lda0, ksplit, A1, lda1, Bt, K, rt * 256, ct * 128, epi, tid); }
.Lg3a_tile:
	s_cmpk_ge_u32 s15, 64
	s_cbranch_scc1 .Lg3a_done
	s_cmpk_ge_u32 s15, 32
	s_cselect_b32 s27, 1, 0
	s_cselect_b32 s26, 32, 0
	s_sub_u32 s26, s15, s26
	s_add_u32 s27, s27, s101
	s_lshl_b32 s27, s27, 3
	s_and_b32 s29, s26, 7
	s_add_u32 s29, s29, s27
	s_lshl_b32 s29, s29, 8
	s_lshr_b32 s28, s26, 3
	s_lshl_b32 s28, s28, 7
	s_mul_i32 s27, s29, 512
	s_add_u32 s27, s27, 0x1ea00000
	s_add_u32 s0, s92, s27
	s_addc_u32 s1, s93, 0
	s_mul_i32 s27, s28, 128
	s_add_u32 s27, s27, 0x34a0000
	s_add_u32 s2, s92, s27
	s_addc_u32 s3, s93, 0
	s_waitcnt lgkmcnt(0)
	s_barrier
	s_mov_b32 s99, 0
	s_mov_b32 s30, 0
	s_add_u32 s26, s30, s100
	s_add_u32 m0, s26, 0
	s_nop 0
	global_load_lds_dwordx4 v224, s[0:1]
	s_add_u32 m0, s26, 4096
	s_nop 0
	global_load_lds_dwordx4 v225, s[0:1]
	s_add_u32 m0, s26, 8192
	s_nop 0
	global_load_lds_dwordx4 v226, s[0:1]
	s_add_u32 m0, s26, 12288
	s_nop 0
	global_load_lds_dwordx4 v227, s[0:1]
	s_add_u32 m0, s26, 16384
	s_nop 0
	global_load_lds_dwordx4 v228, s[2:3]
	s_add_u32 m0, s26, 20480
	s_nop 0
	global_load_lds_dwordx4 v229, s[2:3]
	s_add_u32 s0, s0, 64
	s_addc_u32 s1, s1, 0
	s_add_u32 s2, s2, 64
	s_addc_u32 s3, s3, 0
	s_add_u32 s99, s99, 1
	s_add_u32 s30, s30, 24576
	s_cmp_eq_u32 s30, 73728
	s_cselect_b32 s30, 0, s30
	s_add_u32 s26, s30, s100
	s_add_u32 m0, s26, 0
	s_nop 0
	global_load_lds_dwordx4 v224, s[0:1]
	s_add_u32 m0, s26, 4096
	s_nop 0
	global_load_lds_dwordx4 v225, s[0:1]
	s_add_u32 m0, s26, 8192
	s_nop 0
	global_load_lds_dwordx4 v226, s[0:1]
	s_add_u32 m0, s26, 12288
	s_nop 0
	global_load_lds_dwordx4 v227, s[0:1]
	s_add_u32 m0, s26, 16384
	s_nop 0
	global_load_lds_dwordx4 v228, s[2:3]
	s_add_u32 m0, s26, 20480
	s_nop 0
	global_load_lds_dwordx4 v229, s[2:3]
	s_add_u32 s0, s0, 64
	s_addc_u32 s1, s1, 0
	s_add_u32 s2, s2, 64
	s_addc_u32 s3, s3, 0
	s_add_u32 s99, s99, 1
	s_add_u32 s30, s30, 24576
	s_cmp_eq_u32 s30, 73728
	s_cselect_b32 s30, 0, s30
	v_mov_b32_e32 v0, 0
	v_mov_b32_e32 v1, 0
	v_mov_b32_e32 v2, 0
	v_mov_b32_e32 v3, 0
	v_mov_b32_e32 v4, 0
	v_mov_b32_e32 v5, 0
	v_mov_b32_e32 v6, 0
	v_mov_b32_e32 v7, 0
	v_mov_b32_e32 v8, 0
	v_mov_b32_e32 v9, 0
	v_mov_b32_e32 v10, 0
	v_mov_b32_e32 v11, 0
	v_mov_b32_e32 v12, 0
	v_mov_b32_e32 v13, 0
	v_mov_b32_e32 v14, 0
	v_mov_b32_e32 v15, 0
	v_mov_b32_e32 v16, 0
	v_mov_b32_e32 v17, 0
	v_mov_b32_e32 v18, 0
	v_mov_b32_e32 v19, 0
	v_mov_b32_e32 v20, 0
	v_mov_b32_e32 v21, 0
	v_mov_b32_e32 v22, 0
	v_mov_b32_e32 v23, 0
	v_mov_b32_e32 v24, 0
	v_mov_b32_e32 v25, 0
	v_mov_b32_e32 v26, 0
	v_mov_b32_e32 v27, 0
	v_mov_b32_e32 v28, 0
	v_mov_b32_e32 v29, 0
	v_mov_b32_e32 v30, 0
	v_mov_b32_e32 v31, 0
	v_mov_b32_e32 v32, 0
	v_mov_b32_e32 v33, 0
	v_mov_b32_e32 v34, 0
	v_mov_b32_e32 v35, 0
	v_mov_b32_e32 v36, 0
	v_mov_b32_e32 v37, 0
	v_mov_b32_e32 v38, 0
	v_mov_b32_e32 v39, 0
	v_mov_b32_e32 v40, 0
	v_mov_b32_e32 v41, 0
	v_mov_b32_e32 v42, 0
	v_mov_b32_e32 v43, 0
	v_mov_b32_e32 v44, 0
	v_mov_b32_e32 v45, 0
	v_mov_b32_e32 v46, 0
	v_mov_b32_e32 v47, 0
	v_mov_b32_e32 v48, 0
	v_mov_b32_e32 v49, 0
	v_mov_b32_e32 v50, 0
	v_mov_b32_e32 v51, 0
	v_mov_b32_e32 v52, 0
	v_mov_b32_e32 v53, 0
	v_mov_b32_e32 v54, 0
	v_mov_b32_e32 v55, 0
	v_mov_b32_e32 v56, 0
	v_mov_b32_e32 v57, 0
	v_mov_b32_e32 v58, 0
	v_mov_b32_e32 v59, 0
	v_mov_b32_e32 v60, 0
	v_mov_b32_e32 v61, 0
	v_mov_b32_e32 v62, 0
	v_mov_b32_e32 v63, 0
	v_mov_b32_e32 v64, 0
	v_mov_b32_e32 v65, 0
	v_mov_b32_e32 v66, 0
	v_mov_b32_e32 v67, 0
	v_mov_b32_e32 v68, 0
	v_mov_b32_e32 v69, 0
	v_mov_b32_e32 v70, 0
	v_mov_b32_e32 v71, 0
	v_mov_b32_e32 v72, 0
	v_mov_b32_e32 v73, 0
	v_mov_b32_e32 v74, 0
	v_mov_b32_e32 v75, 0
	v_mov_b32_e32 v76, 0
	v_mov_b32_e32 v77, 0
	v_mov_b32_e32 v78, 0
	v_mov_b32_e32 v79, 0
	v_mov_b32_e32 v80, 0
	v_mov_b32_e32 v81, 0
	v_mov_b32_e32 v82, 0
	v_mov_b32_e32 v83, 0
	v_mov_b32_e32 v84, 0
	v_mov_b32_e32 v85, 0
	v_mov_b32_e32 v86, 0
	v_mov_b32_e32 v87, 0
	v_mov_b32_e32 v88, 0
	v_mov_b32_e32 v89, 0
	v_mov_b32_e32 v90, 0
	v_mov_b32_e32 v91, 0
	v_mov_b32_e32 v92, 0
	v_mov_b32_e32 v93, 0
	v_mov_b32_e32 v94, 0
	v_mov_b32_e32 v95, 0
	v_mov_b32_e32 v96, 0
	v_mov_b32_e32 v97, 0
	v_mov_b32_e32 v98, 0
	v_mov_b32_e32 v99, 0
	v_mov_b32_e32 v100, 0
	v_mov_b32_e32 v101, 0
	v_mov_b32_e32 v102, 0
	v_mov_b32_e32 v103, 0
	v_mov_b32_e32 v104, 0
	v_mov_b32_e32 v105, 0
	v_mov_b32_e32 v106, 0
	v_mov_b32_e32 v107, 0
	v_mov_b32_e32 v108, 0
	v_mov_b32_e32 v109, 0
	v_mov_b32_e32 v110, 0
	v_mov_b32_e32 v111, 0
	v_mov_b32_e32 v112, 0
	v_mov_b32_e32 v113, 0
	v_mov_b32_e32 v114, 0
	v_mov_b32_e32 v115, 0
	v_mov_b32_e32 v116, 0
	v_mov_b32_e32 v117, 0
	v_mov_b32_e32 v118, 0
	v_mov_b32_e32 v119, 0
	v_mov_b32_e32 v120, 0
	v_mov_b32_e32 v121, 0
	v_mov_b32_e32 v122, 0
	v_mov_b32_e32 v123, 0
	v_mov_b32_e32 v124, 0
	v_mov_b32_e32 v125, 0
	v_mov_b32_e32 v126, 0
	v_mov_b32_e32 v127, 0
	s_mov_b32 s98, 0
	s_mov_b32 s31, 24576
	s_waitcnt vmcnt(6)
	s_barrier
	ds_read_b128 v[128:131], v231 offset:0
	ds_read_b128 v[132:135], v231 offset:1024
	ds_read_b128 v[136:139], v231 offset:2048
	ds_read_b128 v[140:143], v231 offset:3072
	ds_read_b128 v[144:147], v230 offset:0
	ds_read_b128 v[148:151], v230 offset:1024
	ds_read_b128 v[152:155], v230 offset:2048
	ds_read_b128 v[156:159], v230 offset:3072
	ds_read_b128 v[160:163], v230 offset:4096
	ds_read_b128 v[164:167], v230 offset:5120
	ds_read_b128 v[168:171], v230 offset:6144
	ds_read_b128 v[172:175], v230 offset:7168
	s_waitcnt vmcnt(0)
	s_waitcnt lgkmcnt(0)
	s_barrier
; #define LWRITE(S, buf) do { bf16_t* sA_ = sbase + (buf) * BUF; bf16_t* sB_ = sA_ + 256 * PITCH; \
;     _Pragma("unroll") for (int i_ = 0; i_ < 4; ++i_) *(u32x4*)(sA_ + (sr + i_ * 64) * PITCH + scv * 8) = ra[S][i_]; \
;     _Pragma("unroll") for (int i_ = 0; i_ < 2; ++i_) *(u32x4*)(sB_ + (sr + i_ * 64) * PITCH + scv * 8) = rb[S][i_]; } while (0)
; template <class Epi>
; DI void gemm_tile(char* smem, const bf16_t* __restrict__ A0, int lda0, int ksplit, const bf16_t* __restrict__ A1, int lda1,
;                   const bf16_t* __restrict__ Bt, int K, int row0, int col0, const Epi& epi, int tid) {
;     ...
;   __syncthreads();
;   {
;     const int last = nk - 1;
;     GLOAD(0, 0);
;     __builtin_amdgcn_sched_barrier(0);
;     GLOAD(1, 1);
;     __builtin_amdgcn_sched_barrier(0);
;     LWRITE(0, 0);
;     __builtin_amdgcn_sched_barrier(0);
;     GLOAD(0, (2 < last ? 2 : last));
;     __builtin_amdgcn_sched_barrier(0);
;     __syncthreads();
;     for (int kt = 0; kt < nk; kt += 2) {
;       LWRITE(1, 1);
;       __builtin_amdgcn_sched_barrier(0);
;       GLOAD(1, (kt + 3 < last ? kt + 3 : last));
;       __builtin_amdgcn_sched_barrier(0);
;       COMPUTE(0);
;       __syncthreads();
;       LWRITE(0, 0);
;       __builtin_amdgcn_sched_barrier(0);
;       GLOAD(0, (kt + 4 < last ? kt + 4 : last));
;       __builtin_amdgcn_sched_barrier(0);
;       COMPUTE(1);
;       __syncthreads();
;     }
	v_add_u32_e32 v232, s31, v230
	v_add_u32_e32 v233, s31, v231
	s_setprio 1
	v_mfma_f32_16x16x32_bf16 v[0:3], v[128:131], v[144:147], v[0:3]
	v_mfma_f32_16x16x32_bf16 v[4:7], v[132:135], v[144:147], v[4:7]
	v_mfma_f32_16x16x32_bf16 v[8:11], v[136:139], v[144:147], v[8:11]
	v_mfma_f32_16x16x32_bf16 v[12:15], v[140:143], v[144:147], v[12:15]
	ds_read_b128 v[176:179], v233 offset:0
	ds_read_b128 v[180:183], v233 offset:1024
	v_mfma_f32_16x16x32_bf16 v[16:19], v[128:131], v[148:151], v[16:19]
	v_mfma_f32_16x16x32_bf16 v[20:23], v[132:135], v[148:151], v[20:23]
	v_mfma_f32_16x16x32_bf16 v[24:27], v[136:139], v[148:151], v[24:27]
	v_mfma_f32_16x16x32_bf16 v[28:31], v[140:143], v[148:151], v[28:31]
	ds_read_b128 v[184:187], v233 offset:2048
	ds_read_b128 v[188:191], v233 offset:3072
	v_mfma_f32_16x16x32_bf16 v[32:35], v[128:131], v[152:155], v[32:35]
	v_mfma_f32_16x16x32_bf16 v[36:39], v[132:135], v[152:155], v[36:39]
	v_mfma_f32_16x16x32_bf16 v[40:43], v[136:139], v[152:155], v[40:43]
	v_mfma_f32_16x16x32_bf16 v[44:47], v[140:143], v[152:155], v[44:47]
	ds_read_b128 v[192:195], v232 offset:0
	ds_read_b128 v[196:199], v232 offset:1024
	v_mfma_f32_16x16x32_bf16 v[48:51], v[128:131], v[156:159], v[48:51]
	v_mfma_f32_16x16x32_bf16 v[52:55], v[132:135], v[156:159], v[52:55]
	v_mfma_f32_16x16x32_bf16 v[56:59], v[136:139], v[156:159], v[56:59]
	v_mfma_f32_16x16x32_bf16 v[60:63], v[140:143], v[156:159], v[60:63]
	ds_read_b128 v[200:203], v232 offset:2048
	ds_read_b128 v[204:207], v232 offset:3072
	v_mfma_f32_16x16x32_bf16 v[64:67], v[128:131], v[160:163], v[64:67]
	v_mfma_f32_16x16x32_bf16 v[68:71], v[132:135], v[160:163], v[68:71]
	v_mfma_f32_16x16x32_bf16 v[72:75], v[136:139], v[160:163], v[72:75]
	v_mfma_f32_16x16x32_bf16 v[76:79], v[140:143], v[160:163], v[76:79]
	ds_read_b128 v[208:211], v232 offset:4096
	v_mfma_f32_16x16x32_bf16 v[80:83], v[128:131], v[164:167], v[80:83]
	v_mfma_f32_16x16x32_bf16 v[84:87], v[132:135], v[164:167], v[84:87]
	v_mfma_f32_16x16x32_bf16 v[88:91], v[136:139], v[164:167], v[88:91]
	v_mfma_f32_16x16x32_bf16 v[92:95], v[140:143], v[164:167], v[92:95]
	ds_read_b128 v[212:215], v232 offset:5120
	s_setprio 0
	v_mfma_f32_16x16x32_bf16 v[96:99], v[128:131], v[168:171], v[96:99]
	v_mfma_f32_16x16x32_bf16 v[100:103], v[132:135], v[168:171], v[100:103]
	v_mfma_f32_16x16x32_bf16 v[104:107], v[136:139], v[168:171], v[104:107]
	v_mfma_f32_16x16x32_bf16 v[108:111], v[140:143], v[168:171], v[108:111]
	ds_read_b128 v[216:219], v232 offset:6144
	s_add_u32 s31, s31, 24576
	s_cmp_eq_u32 s31, 73728
	s_cselect_b32 s31, 0, s31
	v_mfma_f32_16x16x32_bf16 v[112:115], v[128:131], v[172:175], v[112:115]
	v_mfma_f32_16x16x32_bf16 v[116:119], v[132:135], v[172:175], v[116:119]
	v_mfma_f32_16x16x32_bf16 v[120:123], v[136:139], v[172:175], v[120:123]
	v_mfma_f32_16x16x32_bf16 v[124:127], v[140:143], v[172:175], v[124:127]
	ds_read_b128 v[220:223], v232 offset:7168
	s_waitcnt lgkmcnt(0)
	s_barrier
	s_setprio 1
	v_mfma_f32_16x16x32_bf16 v[0:3], v[176:179], v[192:195], v[0:3]
	v_mfma_f32_16x16x32_bf16 v[4:7], v[180:183], v[192:195], v[4:7]
	v_mfma_f32_16x16x32_bf16 v[8:11], v[184:187], v[192:195], v[8:11]
	v_mfma_f32_16x16x32_bf16 v[12:15], v[188:191], v[192:195], v[12:15]
	v_mfma_f32_16x16x32_bf16 v[16:19], v[176:179], v[196:199], v[16:19]
	v_mfma_f32_16x16x32_bf16 v[20:23], v[180:183], v[196:199], v[20:23]
	v_mfma_f32_16x16x32_bf16 v[24:27], v[184:187], v[196:199], v[24:27]
	v_mfma_f32_16x16x32_bf16 v[28:31], v[188:191], v[196:199], v[28:31]
	v_mfma_f32_16x16x32_bf16 v[32:35], v[176:179], v[200:203], v[32:35]
	v_mfma_f32_16x16x32_bf16 v[36:39], v[180:183], v[200:203], v[36:39]
	v_mfma_f32_16x16x32_bf16 v[40:43], v[184:187], v[200:203], v[40:43]
	v_mfma_f32_16x16x32_bf16 v[44:47], v[188:191], v[200:203], v[44:47]
	v_mfma_f32_16x16x32_bf16 v[48:51], v[176:179], v[204:207], v[48:51]
	v_mfma_f32_16x16x32_bf16 v[52:55], v[180:183], v[204:207], v[52:55]
	v_mfma_f32_16x16x32_bf16 v[56:59], v[184:187], v[204:207], v[56:59]
	v_mfma_f32_16x16x32_bf16 v[60:63], v[188:191], v[204:207], v[60:63]
	v_mfma_f32_16x16x32_bf16 v[64:67], v[176:179], v[208:211], v[64:67]
	v_mfma_f32_16x16x32_bf16 v[68:71], v[180:183], v[208:211], v[68:71]
	v_mfma_f32_16x16x32_bf16 v[72:75], v[184:187], v[208:211], v[72:75]
	v_mfma_f32_16x16x32_bf16 v[76:79], v[188:191], v[208:211], v[76:79]
	v_mfma_f32_16x16x32_bf16 v[80:83], v[176:179], v[212:215], v[80:83]
	v_mfma_f32_16x16x32_bf16 v[84:87], v[180:183], v[212:215], v[84:87]
	v_mfma_f32_16x16x32_bf16 v[88:91], v[184:187], v[212:215], v[88:91]
	v_mfma_f32_16x16x32_bf16 v[92:95], v[188:191], v[212:215], v[92:95]
	s_setprio 0
	v_mfma_f32_16x16x32_bf16 v[96:99], v[176:179], v[216:219], v[96:99]
	v_mfma_f32_16x16x32_bf16 v[100:103], v[180:183], v[216:219], v[100:103]
	v_mfma_f32_16x16x32_bf16 v[104:107], v[184:187], v[216:219], v[104:107]
	v_mfma_f32_16x16x32_bf16 v[108:111], v[188:191], v[216:219], v[108:111]
	v_mfma_f32_16x16x32_bf16 v[112:115], v[176:179], v[220:223], v[112:115]
	v_mfma_f32_16x16x32_bf16 v[116:119], v[180:183], v[220:223], v[116:119]
	v_mfma_f32_16x16x32_bf16 v[120:123], v[184:187], v[220:223], v[120:123]
	v_mfma_f32_16x16x32_bf16 v[124:127], v[188:191], v[220:223], v[124:127]
	s_branch .Lg3a_epi

; #define LWRITE(S, buf) do { bf16_t* sA_ = sbase + (buf) * BUF; bf16_t* sB_ = sA_ + 256 * PITCH; \
;     _Pragma("unroll") for (int i_ = 0; i_ < 4; ++i_) *(u32x4*)(sA_ + (sr + i_ * 64) * PITCH + scv * 8) = ra[S][i_]; \
;     _Pragma("unroll") for (int i_ = 0; i_ < 2; ++i_) *(u32x4*)(sB_ + (sr + i_ * 64) * PITCH + scv * 8) = rb[S][i_]; } while (0)
; template <class Epi>
; DI void gemm_tile(char* smem, const bf16_t* __restrict__ A0, int lda0, int ksplit, const bf16_t* __restrict__ A1, int lda1,
;                   const bf16_t* __restrict__ Bt, int K, int row0, int col0, const Epi& epi, int tid) {
;   constexpr int BK = 32, PITCH = 40, BUF = (256 + 128) * PITCH;
;   bf16_t* sbase = (bf16_t*)smem;
;   const int lane = tid & 63, wid = tid >> 6, wr = wid >> 1, wc = wid & 1, fr = lane & 15, fq = lane >> 4;
;   f32x4 acc[8][4];
; #pragma unroll
;   for (int m = 0; m < 8; ++m)
; #pragma unroll
;     for (int n = 0; n < 4; ++n) acc[m][n] = (f32x4){0.f, 0.f, 0.f, 0.f};
;   u32x4 ra[2][4], rb[2][2];
;   const int nk = K / BK;
;   const int sr = tid >> 2, scv = tid & 3;
;     ...
;   __syncthreads();
;   {
;     const int last = nk - 1;
;     GLOAD(0, 0);
;     __builtin_amdgcn_sched_barrier(0);
;     GLOAD(1, 1);
;     __builtin_amdgcn_sched_barrier(0);
;     LWRITE(0, 0);
;     __builtin_amdgcn_sched_barrier(0);
;     GLOAD(0, (2 < last ? 2 : last));
;     __builtin_amdgcn_sched_barrier(0);
;     __syncthreads();
; template <class Epi>
; DI void gemm_phase(char* smem, const bf16_t* A0, int lda0, int ksplit, const bf16_t* A1, int lda1, const bf16_t* Bt, int K, int nN, const Epi& epi, int tid) {
;     ...
;     const int x = blockIdx.x & 7, l = blockIdx.x >> 3, L = G >> 3, per = 8 * nN, tot = 2 * per;
;     for (int q = l; q < tot; q += L) { const int rgl = q / per, rem = q % per, ct = rem >> 3, rt = (x * 2 + rgl) * 8 + (rem & 7);
;       gemm_tile(smem, A0, lda0, ksplit, A1, lda1, Bt, K, rt * 256, ct * 128, epi, tid); }
.Lg3b_tile:
	s_cmpk_ge_u32 s15, 64
	s_cbranch_scc1 .Lg3b_done
	s_cmpk_ge_u32 s15, 32
	s_cselect_b32 s27, 1, 0
	s_cselect_b32 s26, 32, 0
	s_sub_u32 s26, s15, s26
	s_add_u32 s27, s27, s101
	s_lshl_b32 s27, s27, 3
	s_and_b32 s29, s26, 7
	s_add_u32 s29, s29, s27
	s_lshl_b32 s29, s29, 8
	s_lshr_b32 s28, s26, 3
	s_lshl_b32 s28, s28, 7
	s_mul_i32 s27, s29, 512
	s_add_u32 s27, s27, 0x1ea00000
	s_add_u32 s0, s92, s27
	s_addc_u32 s1, s93, 0
	s_mul_i32 s27, s28, 128
	s_add_u32 s27, s27, 0x34b0000
	s_add_u32 s2, s92, s27
	s_addc_u32 s3, s93, 0
	s_waitcnt lgkmcnt(0)
	s_barrier
	s_mov_b32 s99, 0
	s_mov_b32 s30, 0
	s_add_u32 s26, s30, s100
	s_add_u32 m0, s26, 0
	s_nop 0
	global_load_lds_dwordx4 v224, s[0:1]
	s_add_u32 m0, s26, 4096
	s_nop 0
	global_load_lds_dwordx4 v225, s[0:1]
	s_add_u32 m0, s26, 8192
	s_nop 0
	global_load_lds_dwordx4 v226, s[0:1]
	s_add_u32 m0, s26, 12288
	s_nop 0
	global_load_lds_dwordx4 v227, s[0:1]
	s_add_u32 m0, s26, 16384
	s_nop 0
	global_load_lds_dwordx4 v228, s[2:3]
	s_add_u32 m0, s26, 20480
	s_nop 0
	global_load_lds_dwordx4 v229, s[2:3]
	s_add_u32 s0, s0, 64
	s_addc_u32 s1, s1, 0
	s_add_u32 s2, s2, 64
	s_addc_u32 s3, s3, 0
	s_add_u32 s99, s99, 1
	s_add_u32 s30, s30, 24576
	s_cmp_eq_u32 s30, 73728
	s_cselect_b32 s30, 0, s30
	s_add_u32 s26, s30, s100
	s_add_u32 m0, s26, 0
	s_nop 0
	global_load_lds_dwordx4 v224, s[0:1]
	s_add_u32 m0, s26, 4096
	s_nop 0
	global_load_lds_dwordx4 v225, s[0:1]
	s_add_u32 m0, s26, 8192
	s_nop 0
	global_load_lds_dwordx4 v226, s[0:1]
	s_add_u32 m0, s26, 12288
	s_nop 0
	global_load_lds_dwordx4 v227, s[0:1]
	s_add_u32 m0, s26, 16384
	s_nop 0
	global_load_lds_dwordx4 v228, s[2:3]
	s_add_u32 m0, s26, 20480
	s_nop 0
	global_load_lds_dwordx4 v229, s[2:3]
	s_add_u32 s0, s0, 64
	s_addc_u32 s1, s1, 0
	s_add_u32 s2, s2, 64
	s_addc_u32 s3, s3, 0
	s_add_u32 s99, s99, 1
	s_add_u32 s30, s30, 24576
	s_cmp_eq_u32 s30, 73728
	s_cselect_b32 s30, 0, s30
	v_mov_b32_e32 v0, 0
	v_mov_b32_e32 v1, 0
	v_mov_b32_e32 v2, 0
	v_mov_b32_e32 v3, 0
	v_mov_b32_e32 v4, 0
	v_mov_b32_e32 v5, 0
	v_mov_b32_e32 v6, 0
	v_mov_b32_e32 v7, 0
	v_mov_b32_e32 v8, 0
	v_mov_b32_e32 v9, 0
	v_mov_b32_e32 v10, 0
	v_mov_b32_e32 v11, 0
	v_mov_b32_e32 v12, 0
	v_mov_b32_e32 v13, 0
	v_mov_b32_e32 v14, 0
	v_mov_b32_e32 v15, 0
	v_mov_b32_e32 v16, 0
	v_mov_b32_e32 v17, 0
	v_mov_b32_e32 v18, 0
	v_mov_b32_e32 v19, 0
	v_mov_b32_e32 v20, 0
	v_mov_b32_e32 v21, 0
	v_mov_b32_e32 v22, 0
	v_mov_b32_e32 v23, 0
	v_mov_b32_e32 v24, 0
	v_mov_b32_e32 v25, 0
	v_mov_b32_e32 v26, 0
	v_mov_b32_e32 v27, 0
	v_mov_b32_e32 v28, 0
	v_mov_b32_e32 v29, 0
	v_mov_b32_e32 v30, 0
	v_mov_b32_e32 v31, 0
	v_mov_b32_e32 v32, 0
	v_mov_b32_e32 v33, 0
	v_mov_b32_e32 v34, 0
	v_mov_b32_e32 v35, 0
	v_mov_b32_e32 v36, 0
	v_mov_b32_e32 v37, 0
	v_mov_b32_e32 v38, 0
	v_mov_b32_e32 v39, 0
	v_mov_b32_e32 v40, 0
	v_mov_b32_e32 v41, 0
	v_mov_b32_e32 v42, 0
	v_mov_b32_e32 v43, 0
	v_mov_b32_e32 v44, 0
	v_mov_b32_e32 v45, 0
	v_mov_b32_e32 v46, 0
	v_mov_b32_e32 v47, 0
	v_mov_b32_e32 v48, 0
	v_mov_b32_e32 v49, 0
	v_mov_b32_e32 v50, 0
	v_mov_b32_e32 v51, 0
	v_mov_b32_e32 v52, 0
	v_mov_b32_e32 v53, 0
	v_mov_b32_e32 v54, 0
	v_mov_b32_e32 v55, 0
	v_mov_b32_e32 v56, 0
	v_mov_b32_e32 v57, 0
	v_mov_b32_e32 v58, 0
	v_mov_b32_e32 v59, 0
	v_mov_b32_e32 v60, 0
	v_mov_b32_e32 v61, 0
	v_mov_b32_e32 v62, 0
	v_mov_b32_e32 v63, 0
	v_mov_b32_e32 v64, 0
	v_mov_b32_e32 v65, 0
	v_mov_b32_e32 v66, 0
	v_mov_b32_e32 v67, 0
	v_mov_b32_e32 v68, 0
	v_mov_b32_e32 v69, 0
	v_mov_b32_e32 v70, 0
	v_mov_b32_e32 v71, 0
	v_mov_b32_e32 v72, 0
	v_mov_b32_e32 v73, 0
	v_mov_b32_e32 v74, 0
	v_mov_b32_e32 v75, 0
	v_mov_b32_e32 v76, 0
	v_mov_b32_e32 v77, 0
	v_mov_b32_e32 v78, 0
	v_mov_b32_e32 v79, 0
	v_mov_b32_e32 v80, 0
	v_mov_b32_e32 v81, 0
	v_mov_b32_e32 v82, 0
	v_mov_b32_e32 v83, 0
	v_mov_b32_e32 v84, 0
	v_mov_b32_e32 v85, 0
	v_mov_b32_e32 v86, 0
	v_mov_b32_e32 v87, 0
	v_mov_b32_e32 v88, 0
	v_mov_b32_e32 v89, 0
	v_mov_b32_e32 v90, 0
	v_mov_b32_e32 v91, 0
	v_mov_b32_e32 v92, 0
	v_mov_b32_e32 v93, 0
	v_mov_b32_e32 v94, 0
	v_mov_b32_e32 v95, 0
	v_mov_b32_e32 v96, 0
	v_mov_b32_e32 v97, 0
	v_mov_b32_e32 v98, 0
	v_mov_b32_e32 v99, 0
	v_mov_b32_e32 v100, 0
	v_mov_b32_e32 v101, 0
	v_mov_b32_e32 v102, 0
	v_mov_b32_e32 v103, 0
	v_mov_b32_e32 v104, 0
	v_mov_b32_e32 v105, 0
	v_mov_b32_e32 v106, 0
	v_mov_b32_e32 v107, 0
	v_mov_b32_e32 v108, 0
	v_mov_b32_e32 v109, 0
	v_mov_b32_e32 v110, 0
	v_mov_b32_e32 v111, 0
	v_mov_b32_e32 v112, 0
	v_mov_b32_e32 v113, 0
	v_mov_b32_e32 v114, 0
	v_mov_b32_e32 v115, 0
	v_mov_b32_e32 v116, 0
	v_mov_b32_e32 v117, 0
	v_mov_b32_e32 v118, 0
	v_mov_b32_e32 v119, 0
	v_mov_b32_e32 v120, 0
	v_mov_b32_e32 v121, 0
	v_mov_b32_e32 v122, 0
	v_mov_b32_e32 v123, 0
	v_mov_b32_e32 v124, 0
	v_mov_b32_e32 v125, 0
	v_mov_b32_e32 v126, 0
	v_mov_b32_e32 v127, 0
	s_mov_b32 s98, 0
	s_mov_b32 s31, 24576
	s_waitcnt vmcnt(6)
	s_barrier
	ds_read_b128 v[128:131], v231 offset:0
	ds_read_b128 v[132:135], v231 offset:1024
	ds_read_b128 v[136:139], v231 offset:2048
	ds_read_b128 v[140:143], v231 offset:3072
	ds_read_b128 v[144:147], v230 offset:0
	ds_read_b128 v[148:151], v230 offset:1024
	ds_read_b128 v[152:155], v230 offset:2048
	ds_read_b128 v[156:159], v230 offset:3072
	ds_read_b128 v[160:163], v230 offset:4096
	ds_read_b128 v[164:167], v230 offset:5120
	ds_read_b128 v[168:171], v230 offset:6144
	ds_read_b128 v[172:175], v230 offset:7168
	s_waitcnt vmcnt(0)
	s_waitcnt lgkmcnt(0)
	s_barrier
; #define LWRITE(S, buf) do { bf16_t* sA_ = sbase + (buf) * BUF; bf16_t* sB_ = sA_ + 256 * PITCH; \
;     _Pragma("unroll") for (int i_ = 0; i_ < 4; ++i_) *(u32x4*)(sA_ + (sr + i_ * 64) * PITCH + scv * 8) = ra[S][i_]; \
;     _Pragma("unroll") for (int i_ = 0; i_ < 2; ++i_) *(u32x4*)(sB_ + (sr + i_ * 64) * PITCH + scv * 8) = rb[S][i_]; } while (0)
; template <class Epi>
; DI void gemm_tile(char* smem, const bf16_t* __restrict__ A0, int lda0, int ksplit, const bf16_t* __restrict__ A1, int lda1,
;                   const bf16_t* __restrict__ Bt, int K, int row0, int col0, const Epi& epi, int tid) {
;     ...
;   __syncthreads();
;   {
;     const int last = nk - 1;
;     GLOAD(0, 0);
;     __builtin_amdgcn_sched_barrier(0);
;     GLOAD(1, 1);
;     __builtin_amdgcn_sched_barrier(0);
;     LWRITE(0, 0);
;     __builtin_amdgcn_sched_barrier(0);
;     GLOAD(0, (2 < last ? 2 : last));
;     __builtin_amdgcn_sched_barrier(0);
;     __syncthreads();
;     for (int kt = 0; kt < nk; kt += 2) {
;       LWRITE(1, 1);
;       __builtin_amdgcn_sched_barrier(0);
;       GLOAD(1, (kt + 3 < last ? kt + 3 : last));
;       __builtin_amdgcn_sched_barrier(0);
;       COMPUTE(0);
;       __syncthreads();
;       LWRITE(0, 0);
;       __builtin_amdgcn_sched_barrier(0);
;       GLOAD(0, (kt + 4 < last ? kt + 4 : last));
;       __builtin_amdgcn_sched_barrier(0);
;       COMPUTE(1);
;       __syncthreads();
;     }
	v_add_u32_e32 v232, s31, v230
	v_add_u32_e32 v233, s31, v231
	s_setprio 1
	v_mfma_f32_16x16x32_bf16 v[0:3], v[128:131], v[144:147], v[0:3]
	v_mfma_f32_16x16x32_bf16 v[4:7], v[132:135], v[144:147], v[4:7]
	v_mfma_f32_16x16x32_bf16 v[8:11], v[136:139], v[144:147], v[8:11]
	v_mfma_f32_16x16x32_bf16 v[12:15], v[140:143], v[144:147], v[12:15]
	ds_read_b128 v[176:179], v233 offset:0
	ds_read_b128 v[180:183], v233 offset:1024
	v_mfma_f32_16x16x32_bf16 v[16:19], v[128:131], v[148:151], v[16:19]
	v_mfma_f32_16x16x32_bf16 v[20:23], v[132:135], v[148:151], v[20:23]
	v_mfma_f32_16x16x32_bf16 v[24:27], v[136:139], v[148:151], v[24:27]
	v_mfma_f32_16x16x32_bf16 v[28:31], v[140:143], v[148:151], v[28:31]
	ds_read_b128 v[184:187], v233 offset:2048
	ds_read_b128 v[188:191], v233 offset:3072
	v_mfma_f32_16x16x32_bf16 v[32:35], v[128:131], v[152:155], v[32:35]
	v_mfma_f32_16x16x32_bf16 v[36:39], v[132:135], v[152:155], v[36:39]
	v_mfma_f32_16x16x32_bf16 v[40:43], v[136:139], v[152:155], v[40:43]
	v_mfma_f32_16x16x32_bf16 v[44:47], v[140:143], v[152:155], v[44:47]
	ds_read_b128 v[192:195], v232 offset:0
	ds_read_b128 v[196:199], v232 offset:1024
	v_mfma_f32_16x16x32_bf16 v[48:51], v[128:131], v[156:159], v[48:51]
	v_mfma_f32_16x16x32_bf16 v[52:55], v[132:135], v[156:159], v[52:55]
	v_mfma_f32_16x16x32_bf16 v[56:59], v[136:139], v[156:159], v[56:59]
	v_mfma_f32_16x16x32_bf16 v[60:63], v[140:143], v[156:159], v[60:63]
	ds_read_b128 v[200:203], v232 offset:2048
	ds_read_b128 v[204:207], v232 offset:3072
	v_mfma_f32_16x16x32_bf16 v[64:67], v[128:131], v[160:163], v[64:67]
	v_mfma_f32_16x16x32_bf16 v[68:71], v[132:135], v[160:163], v[68:71]
	v_mfma_f32_16x16x32_bf16 v[72:75], v[136:139], v[160:163], v[72:75]
	v_mfma_f32_16x16x32_bf16 v[76:79], v[140:143], v[160:163], v[76:79]
	ds_read_b128 v[208:211], v232 offset:4096
	v_mfma_f32_16x16x32_bf16 v[80:83], v[128:131], v[164:167], v[80:83]
	v_mfma_f32_16x16x32_bf16 v[84:87], v[132:135], v[164:167], v[84:87]
	v_mfma_f32_16x16x32_bf16 v[88:91], v[136:139], v[164:167], v[88:91]
	v_mfma_f32_16x16x32_bf16 v[92:95], v[140:143], v[164:167], v[92:95]
	ds_read_b128 v[212:215], v232 offset:5120
	s_setprio 0
	v_mfma_f32_16x16x32_bf16 v[96:99], v[128:131], v[168:171], v[96:99]
	v_mfma_f32_16x16x32_bf16 v[100:103], v[132:135], v[168:171], v[100:103]
	v_mfma_f32_16x16x32_bf16 v[104:107], v[136:139], v[168:171], v[104:107]
	v_mfma_f32_16x16x32_bf16 v[108:111], v[140:143], v[168:171], v[108:111]
	ds_read_b128 v[216:219], v232 offset:6144
	s_add_u32 s31, s31, 24576
	s_cmp_eq_u32 s31, 73728
	s_cselect_b32 s31, 0, s31
	v_mfma_f32_16x16x32_bf16 v[112:115], v[128:131], v[172:175], v[112:115]
	v_mfma_f32_16x16x32_bf16 v[116:119], v[132:135], v[172:175], v[116:119]
	v_mfma_f32_16x16x32_bf16 v[120:123], v[136:139], v[172:175], v[120:123]
	v_mfma_f32_16x16x32_bf16 v[124:127], v[140:143], v[172:175], v[124:127]
	ds_read_b128 v[220:223], v232 offset:7168
	s_waitcnt lgkmcnt(0)
	s_barrier
	s_setprio 1
	v_mfma_f32_16x16x32_bf16 v[0:3], v[176:179], v[192:195], v[0:3]
	v_mfma_f32_16x16x32_bf16 v[4:7], v[180:183], v[192:195], v[4:7]
	v_mfma_f32_16x16x32_bf16 v[8:11], v[184:187], v[192:195], v[8:11]
	v_mfma_f32_16x16x32_bf16 v[12:15], v[188:191], v[192:195], v[12:15]
	v_mfma_f32_16x16x32_bf16 v[16:19], v[176:179], v[196:199], v[16:19]
	v_mfma_f32_16x16x32_bf16 v[20:23], v[180:183], v[196:199], v[20:23]
	v_mfma_f32_16x16x32_bf16 v[24:27], v[184:187], v[196:199], v[24:27]
	v_mfma_f32_16x16x32_bf16 v[28:31], v[188:191], v[196:199], v[28:31]
	v_mfma_f32_16x16x32_bf16 v[32:35], v[176:179], v[200:203], v[32:35]
	v_mfma_f32_16x16x32_bf16 v[36:39], v[180:183], v[200:203], v[36:39]
	v_mfma_f32_16x16x32_bf16 v[40:43], v[184:187], v[200:203], v[40:43]
	v_mfma_f32_16x16x32_bf16 v[44:47], v[188:191], v[200:203], v[44:47]
	v_mfma_f32_16x16x32_bf16 v[48:51], v[176:179], v[204:207], v[48:51]
	v_mfma_f32_16x16x32_bf16 v[52:55], v[180:183], v[204:207], v[52:55]
	v_mfma_f32_16x16x32_bf16 v[56:59], v[184:187], v[204:207], v[56:59]
	v_mfma_f32_16x16x32_bf16 v[60:63], v[188:191], v[204:207], v[60:63]
	v_mfma_f32_16x16x32_bf16 v[64:67], v[176:179], v[208:211], v[64:67]
	v_mfma_f32_16x16x32_bf16 v[68:71], v[180:183], v[208:211], v[68:71]
	v_mfma_f32_16x16x32_bf16 v[72:75], v[184:187], v[208:211], v[72:75]
	v_mfma_f32_16x16x32_bf16 v[76:79], v[188:191], v[208:211], v[76:79]
	v_mfma_f32_16x16x32_bf16 v[80:83], v[176:179], v[212:215], v[80:83]
	v_mfma_f32_16x16x32_bf16 v[84:87], v[180:183], v[212:215], v[84:87]
	v_mfma_f32_16x16x32_bf16 v[88:91], v[184:187], v[212:215], v[88:91]
	v_mfma_f32_16x16x32_bf16 v[92:95], v[188:191], v[212:215], v[92:95]
	s_setprio 0
	v_mfma_f32_16x16x32_bf16 v[96:99], v[176:179], v[216:219], v[96:99]
	v_mfma_f32_16x16x32_bf16 v[100:103], v[180:183], v[216:219], v[100:103]
	v_mfma_f32_16x16x32_bf16 v[104:107], v[184:187], v[216:219], v[104:107]
	v_mfma_f32_16x16x32_bf16 v[108:111], v[188:191], v[216:219], v[108:111]
	v_mfma_f32_16x16x32_bf16 v[112:115], v[176:179], v[220:223], v[112:115]
	v_mfma_f32_16x16x32_bf16 v[116:119], v[180:183], v[220:223], v[116:119]
	v_mfma_f32_16x16x32_bf16 v[120:123], v[184:187], v[220:223], v[120:123]
	v_mfma_f32_16x16x32_bf16 v[124:127], v[188:191], v[220:223], v[124:127]
	s_branch .Lg3b_epi

; #define LWRITE(S, buf) do { bf16_t* sA_ = sbase + (buf) * BUF; bf16_t* sB_ = sA_ + 256 * PITCH; \
;     _Pragma("unroll") for (int i_ = 0; i_ < 4; ++i_) *(u32x4*)(sA_ + (sr + i_ * 64) * PITCH + scv * 8) = ra[S][i_]; \
;     _Pragma("unroll") for (int i_ = 0; i_ < 2; ++i_) *(u32x4*)(sB_ + (sr + i_ * 64) * PITCH + scv * 8) = rb[S][i_]; } while (0)
; template <class Epi>
; DI void gemm_tile(char* smem, const bf16_t* __restrict__ A0, int lda0, int ksplit, const bf16_t* __restrict__ A1, int lda1,
;                   const bf16_t* __restrict__ Bt, int K, int row0, int col0, const Epi& epi, int tid) {
;   constexpr int BK = 32, PITCH = 40, BUF = (256 + 128) * PITCH;
;   bf16_t* sbase = (bf16_t*)smem;
;   const int lane = tid & 63, wid = tid >> 6, wr = wid >> 1, wc = wid & 1, fr = lane & 15, fq = lane >> 4;
;   f32x4 acc[8][4];
; #pragma unroll
;   for (int m = 0; m < 8; ++m)
; #pragma unroll
;     for (int n = 0; n < 4; ++n) acc[m][n] = (f32x4){0.f, 0.f, 0.f, 0.f};
;   u32x4 ra[2][4], rb[2][2];
;   const int nk = K / BK;
;   const int sr = tid >> 2, scv = tid & 3;
;     ...
;   __syncthreads();
;   {
;     const int last = nk - 1;
;     GLOAD(0, 0);
;     __builtin_amdgcn_sched_barrier(0);
;     GLOAD(1, 1);
;     __builtin_amdgcn_sched_barrier(0);
;     LWRITE(0, 0);
;     __builtin_amdgcn_sched_barrier(0);
;     GLOAD(0, (2 < last ? 2 : last));
;     __builtin_amdgcn_sched_barrier(0);
;     __syncthreads();
; template <class Epi>
; DI void gemm_phase(char* smem, const bf16_t* A0, int lda0, int ksplit, const bf16_t* A1, int lda1, const bf16_t* Bt, int K, int nN, const Epi& epi, int tid) {
;     ...
;     const int x = blockIdx.x & 7, l = blockIdx.x >> 3, L = G >> 3, per = 8 * nN, tot = 2 * per;
;     for (int q = l; q < tot; q += L) { const int rgl = q / per, rem = q % per, ct = rem >> 3, rt = (x * 2 + rgl) * 8 + (rem & 7);
;       gemm_tile(smem, A0, lda0, ksplit, A1, lda1, Bt, K, rt * 256, ct * 128, epi, tid); }
.Lg3c_tile:
	s_cmpk_ge_u32 s15, 64
	s_cbranch_scc1 .Lg3c_done
	s_cmpk_ge_u32 s15, 32
	s_cselect_b32 s27, 1, 0
	s_cselect_b32 s26, 32, 0
	s_sub_u32 s26, s15, s26
	s_add_u32 s27, s27, s101
	s_lshl_b32 s27, s27, 3
	s_and_b32 s29, s26, 7
	s_add_u32 s29, s29, s27
	s_lshl_b32 s29, s29, 8
	s_lshr_b32 s28, s26, 3
	s_lshl_b32 s28, s28, 7
	s_mul_i32 s27, s29, 512
	s_add_u32 s27, s27, 0x1ea00080
	s_add_u32 s0, s92, s27
	s_addc_u32 s1, s93, 0
	s_mul_i32 s27, s28, 128
	s_add_u32 s27, s27, 0x34c0000
	s_add_u32 s2, s92, s27
	s_addc_u32 s3, s93, 0
	s_waitcnt lgkmcnt(0)
	s_barrier
	s_mov_b32 s99, 0
	s_mov_b32 s30, 0
	s_add_u32 s26, s30, s100
	s_add_u32 m0, s26, 0
	s_nop 0
	global_load_lds_dwordx4 v224, s[0:1]
	s_add_u32 m0, s26, 4096
	s_nop 0
	global_load_lds_dwordx4 v225, s[0:1]
	s_add_u32 m0, s26, 8192
	s_nop 0
	global_load_lds_dwordx4 v226, s[0:1]
	s_add_u32 m0, s26, 12288
	s_nop 0
	global_load_lds_dwordx4 v227, s[0:1]
	s_add_u32 m0, s26, 16384
	s_nop 0
	global_load_lds_dwordx4 v228, s[2:3]
	s_add_u32 m0, s26, 20480
	s_nop 0
	global_load_lds_dwordx4 v229, s[2:3]
	s_add_u32 s0, s0, 64
	s_addc_u32 s1, s1, 0
	s_add_u32 s2, s2, 64
	s_addc_u32 s3, s3, 0
	s_add_u32 s99, s99, 1
	s_add_u32 s30, s30, 24576
	s_cmp_eq_u32 s30, 73728
	s_cselect_b32 s30, 0, s30
	s_add_u32 s26, s30, s100
	s_add_u32 m0, s26, 0
	s_nop 0
	global_load_lds_dwordx4 v224, s[0:1]
	s_add_u32 m0, s26, 4096
	s_nop 0
	global_load_lds_dwordx4 v225, s[0:1]
	s_add_u32 m0, s26, 8192
	s_nop 0
	global_load_lds_dwordx4 v226, s[0:1]
	s_add_u32 m0, s26, 12288
	s_nop 0
	global_load_lds_dwordx4 v227, s[0:1]
	s_add_u32 m0, s26, 16384
	s_nop 0
	global_load_lds_dwordx4 v228, s[2:3]
	s_add_u32 m0, s26, 20480
	s_nop 0
	global_load_lds_dwordx4 v229, s[2:3]
	s_add_u32 s0, s0, 64
	s_addc_u32 s1, s1, 0
	s_add_u32 s2, s2, 64
	s_addc_u32 s3, s3, 0
	s_add_u32 s99, s99, 1
	s_add_u32 s30, s30, 24576
	s_cmp_eq_u32 s30, 73728
	s_cselect_b32 s30, 0, s30
	v_mov_b32_e32 v0, 0
	v_mov_b32_e32 v1, 0
	v_mov_b32_e32 v2, 0
	v_mov_b32_e32 v3, 0
	v_mov_b32_e32 v4, 0
	v_mov_b32_e32 v5, 0
	v_mov_b32_e32 v6, 0
	v_mov_b32_e32 v7, 0
	v_mov_b32_e32 v8, 0
	v_mov_b32_e32 v9, 0
	v_mov_b32_e32 v10, 0
	v_mov_b32_e32 v11, 0
	v_mov_b32_e32 v12, 0
	v_mov_b32_e32 v13, 0
	v_mov_b32_e32 v14, 0
	v_mov_b32_e32 v15, 0
	v_mov_b32_e32 v16, 0
	v_mov_b32_e32 v17, 0
	v_mov_b32_e32 v18, 0
	v_mov_b32_e32 v19, 0
	v_mov_b32_e32 v20, 0
	v_mov_b32_e32 v21, 0
	v_mov_b32_e32 v22, 0
	v_mov_b32_e32 v23, 0
	v_mov_b32_e32 v24, 0
	v_mov_b32_e32 v25, 0
	v_mov_b32_e32 v26, 0
	v_mov_b32_e32 v27, 0
	v_mov_b32_e32 v28, 0
	v_mov_b32_e32 v29, 0
	v_mov_b32_e32 v30, 0
	v_mov_b32_e32 v31, 0
	v_mov_b32_e32 v32, 0
	v_mov_b32_e32 v33, 0
	v_mov_b32_e32 v34, 0
	v_mov_b32_e32 v35, 0
	v_mov_b32_e32 v36, 0
	v_mov_b32_e32 v37, 0
	v_mov_b32_e32 v38, 0
	v_mov_b32_e32 v39, 0
	v_mov_b32_e32 v40, 0
	v_mov_b32_e32 v41, 0
	v_mov_b32_e32 v42, 0
	v_mov_b32_e32 v43, 0
	v_mov_b32_e32 v44, 0
	v_mov_b32_e32 v45, 0
	v_mov_b32_e32 v46, 0
	v_mov_b32_e32 v47, 0
	v_mov_b32_e32 v48, 0
	v_mov_b32_e32 v49, 0
	v_mov_b32_e32 v50, 0
	v_mov_b32_e32 v51, 0
	v_mov_b32_e32 v52, 0
	v_mov_b32_e32 v53, 0
	v_mov_b32_e32 v54, 0
	v_mov_b32_e32 v55, 0
	v_mov_b32_e32 v56, 0
	v_mov_b32_e32 v57, 0
	v_mov_b32_e32 v58, 0
	v_mov_b32_e32 v59, 0
	v_mov_b32_e32 v60, 0
	v_mov_b32_e32 v61, 0
	v_mov_b32_e32 v62, 0
	v_mov_b32_e32 v63, 0
	v_mov_b32_e32 v64, 0
	v_mov_b32_e32 v65, 0
	v_mov_b32_e32 v66, 0
	v_mov_b32_e32 v67, 0
	v_mov_b32_e32 v68, 0
	v_mov_b32_e32 v69, 0
	v_mov_b32_e32 v70, 0
	v_mov_b32_e32 v71, 0
	v_mov_b32_e32 v72, 0
	v_mov_b32_e32 v73, 0
	v_mov_b32_e32 v74, 0
	v_mov_b32_e32 v75, 0
	v_mov_b32_e32 v76, 0
	v_mov_b32_e32 v77, 0
	v_mov_b32_e32 v78, 0
	v_mov_b32_e32 v79, 0
	v_mov_b32_e32 v80, 0
	v_mov_b32_e32 v81, 0
	v_mov_b32_e32 v82, 0
	v_mov_b32_e32 v83, 0
	v_mov_b32_e32 v84, 0
	v_mov_b32_e32 v85, 0
	v_mov_b32_e32 v86, 0
	v_mov_b32_e32 v87, 0
	v_mov_b32_e32 v88, 0
	v_mov_b32_e32 v89, 0
	v_mov_b32_e32 v90, 0
	v_mov_b32_e32 v91, 0
	v_mov_b32_e32 v92, 0
	v_mov_b32_e32 v93, 0
	v_mov_b32_e32 v94, 0
	v_mov_b32_e32 v95, 0
	v_mov_b32_e32 v96, 0
	v_mov_b32_e32 v97, 0
	v_mov_b32_e32 v98, 0
	v_mov_b32_e32 v99, 0
	v_mov_b32_e32 v100, 0
	v_mov_b32_e32 v101, 0
	v_mov_b32_e32 v102, 0
	v_mov_b32_e32 v103, 0
	v_mov_b32_e32 v104, 0
	v_mov_b32_e32 v105, 0
	v_mov_b32_e32 v106, 0
	v_mov_b32_e32 v107, 0
	v_mov_b32_e32 v108, 0
	v_mov_b32_e32 v109, 0
	v_mov_b32_e32 v110, 0
	v_mov_b32_e32 v111, 0
	v_mov_b32_e32 v112, 0
	v_mov_b32_e32 v113, 0
	v_mov_b32_e32 v114, 0
	v_mov_b32_e32 v115, 0
	v_mov_b32_e32 v116, 0
	v_mov_b32_e32 v117, 0
	v_mov_b32_e32 v118, 0
	v_mov_b32_e32 v119, 0
	v_mov_b32_e32 v120, 0
	v_mov_b32_e32 v121, 0
	v_mov_b32_e32 v122, 0
	v_mov_b32_e32 v123, 0
	v_mov_b32_e32 v124, 0
	v_mov_b32_e32 v125, 0
	v_mov_b32_e32 v126, 0
	v_mov_b32_e32 v127, 0
	s_mov_b32 s98, 0
	s_mov_b32 s31, 24576
	s_waitcnt vmcnt(6)
	s_barrier
	ds_read_b128 v[128:131], v231 offset:0
	ds_read_b128 v[132:135], v231 offset:1024
	ds_read_b128 v[136:139], v231 offset:2048
	ds_read_b128 v[140:143], v231 offset:3072
	ds_read_b128 v[144:147], v230 offset:0
	ds_read_b128 v[148:151], v230 offset:1024
	ds_read_b128 v[152:155], v230 offset:2048
	ds_read_b128 v[156:159], v230 offset:3072
	ds_read_b128 v[160:163], v230 offset:4096
	ds_read_b128 v[164:167], v230 offset:5120
	ds_read_b128 v[168:171], v230 offset:6144
	ds_read_b128 v[172:175], v230 offset:7168
	s_waitcnt vmcnt(0)
	s_waitcnt lgkmcnt(0)
	s_barrier
; #define LWRITE(S, buf) do { bf16_t* sA_ = sbase + (buf) * BUF; bf16_t* sB_ = sA_ + 256 * PITCH; \
;     _Pragma("unroll") for (int i_ = 0; i_ < 4; ++i_) *(u32x4*)(sA_ + (sr + i_ * 64) * PITCH + scv * 8) = ra[S][i_]; \
;     _Pragma("unroll") for (int i_ = 0; i_ < 2; ++i_) *(u32x4*)(sB_ + (sr + i_ * 64) * PITCH + scv * 8) = rb[S][i_]; } while (0)
; template <class Epi>
; DI void gemm_tile(char* smem, const bf16_t* __restrict__ A0, int lda0, int ksplit, const bf16_t* __restrict__ A1, int lda1,
;                   const bf16_t* __restrict__ Bt, int K, int row0, int col0, const Epi& epi, int tid) {
;     ...
;   __syncthreads();
;   {
;     const int last = nk - 1;
;     GLOAD(0, 0);
;     __builtin_amdgcn_sched_barrier(0);
;     GLOAD(1, 1);
;     __builtin_amdgcn_sched_barrier(0);
;     LWRITE(0, 0);
;     __builtin_amdgcn_sched_barrier(0);
;     GLOAD(0, (2 < last ? 2 : last));
;     __builtin_amdgcn_sched_barrier(0);
;     __syncthreads();
;     for (int kt = 0; kt < nk; kt += 2) {
;       LWRITE(1, 1);
;       __builtin_amdgcn_sched_barrier(0);
;       GLOAD(1, (kt + 3 < last ? kt + 3 : last));
;       __builtin_amdgcn_sched_barrier(0);
;       COMPUTE(0);
;       __syncthreads();
;       LWRITE(0, 0);
;       __builtin_amdgcn_sched_barrier(0);
;       GLOAD(0, (kt + 4 < last ? kt + 4 : last));
;       __builtin_amdgcn_sched_barrier(0);
;       COMPUTE(1);
;       __syncthreads();
;     }
	v_add_u32_e32 v232, s31, v230
	v_add_u32_e32 v233, s31, v231
	s_setprio 1
	v_mfma_f32_16x16x32_bf16 v[0:3], v[128:131], v[144:147], v[0:3]
	v_mfma_f32_16x16x32_bf16 v[4:7], v[132:135], v[144:147], v[4:7]
	v_mfma_f32_16x16x32_bf16 v[8:11], v[136:139], v[144:147], v[8:11]
	v_mfma_f32_16x16x32_bf16 v[12:15], v[140:143], v[144:147], v[12:15]
	ds_read_b128 v[176:179], v233 offset:0
	ds_read_b128 v[180:183], v233 offset:1024
	v_mfma_f32_16x16x32_bf16 v[16:19], v[128:131], v[148:151], v[16:19]
	v_mfma_f32_16x16x32_bf16 v[20:23], v[132:135], v[148:151], v[20:23]
	v_mfma_f32_16x16x32_bf16 v[24:27], v[136:139], v[148:151], v[24:27]
	v_mfma_f32_16x16x32_bf16 v[28:31], v[140:143], v[148:151], v[28:31]
	ds_read_b128 v[184:187], v233 offset:2048
	ds_read_b128 v[188:191], v233 offset:3072
	v_mfma_f32_16x16x32_bf16 v[32:35], v[128:131], v[152:155], v[32:35]
	v_mfma_f32_16x16x32_bf16 v[36:39], v[132:135], v[152:155], v[36:39]
	v_mfma_f32_16x16x32_bf16 v[40:43], v[136:139], v[152:155], v[40:43]
	v_mfma_f32_16x16x32_bf16 v[44:47], v[140:143], v[152:155], v[44:47]
	ds_read_b128 v[192:195], v232 offset:0
	ds_read_b128 v[196:199], v232 offset:1024
	v_mfma_f32_16x16x32_bf16 v[48:51], v[128:131], v[156:159], v[48:51]
	v_mfma_f32_16x16x32_bf16 v[52:55], v[132:135], v[156:159], v[52:55]
	v_mfma_f32_16x16x32_bf16 v[56:59], v[136:139], v[156:159], v[56:59]
	v_mfma_f32_16x16x32_bf16 v[60:63], v[140:143], v[156:159], v[60:63]
	ds_read_b128 v[200:203], v232 offset:2048
	ds_read_b128 v[204:207], v232 offset:3072
	v_mfma_f32_16x16x32_bf16 v[64:67], v[128:131], v[160:163], v[64:67]
	v_mfma_f32_16x16x32_bf16 v[68:71], v[132:135], v[160:163], v[68:71]
	v_mfma_f32_16x16x32_bf16 v[72:75], v[136:139], v[160:163], v[72:75]
	v_mfma_f32_16x16x32_bf16 v[76:79], v[140:143], v[160:163], v[76:79]
	ds_read_b128 v[208:211], v232 offset:4096
	v_mfma_f32_16x16x32_bf16 v[80:83], v[128:131], v[164:167], v[80:83]
	v_mfma_f32_16x16x32_bf16 v[84:87], v[132:135], v[164:167], v[84:87]
	v_mfma_f32_16x16x32_bf16 v[88:91], v[136:139], v[164:167], v[88:91]
	v_mfma_f32_16x16x32_bf16 v[92:95], v[140:143], v[164:167], v[92:95]
	ds_read_b128 v[212:215], v232 offset:5120
	s_setprio 0
	v_mfma_f32_16x16x32_bf16 v[96:99], v[128:131], v[168:171], v[96:99]
	v_mfma_f32_16x16x32_bf16 v[100:103], v[132:135], v[168:171], v[100:103]
	v_mfma_f32_16x16x32_bf16 v[104:107], v[136:139], v[168:171], v[104:107]
	v_mfma_f32_16x16x32_bf16 v[108:111], v[140:143], v[168:171], v[108:111]
	ds_read_b128 v[216:219], v232 offset:6144
	s_add_u32 s31, s31, 24576
	s_cmp_eq_u32 s31, 73728
	s_cselect_b32 s31, 0, s31
	v_mfma_f32_16x16x32_bf16 v[112:115], v[128:131], v[172:175], v[112:115]
	v_mfma_f32_16x16x32_bf16 v[116:119], v[132:135], v[172:175], v[116:119]
	v_mfma_f32_16x16x32_bf16 v[120:123], v[136:139], v[172:175], v[120:123]
	v_mfma_f32_16x16x32_bf16 v[124:127], v[140:143], v[172:175], v[124:127]
	ds_read_b128 v[220:223], v232 offset:7168
	s_waitcnt lgkmcnt(0)
	s_barrier
	s_setprio 1
	v_mfma_f32_16x16x32_bf16 v[0:3], v[176:179], v[192:195], v[0:3]
	v_mfma_f32_16x16x32_bf16 v[4:7], v[180:183], v[192:195], v[4:7]
	v_mfma_f32_16x16x32_bf16 v[8:11], v[184:187], v[192:195], v[8:11]
	v_mfma_f32_16x16x32_bf16 v[12:15], v[188:191], v[192:195], v[12:15]
	v_mfma_f32_16x16x32_bf16 v[16:19], v[176:179], v[196:199], v[16:19]
	v_mfma_f32_16x16x32_bf16 v[20:23], v[180:183], v[196:199], v[20:23]
	v_mfma_f32_16x16x32_bf16 v[24:27], v[184:187], v[196:199], v[24:27]
	v_mfma_f32_16x16x32_bf16 v[28:31], v[188:191], v[196:199], v[28:31]
	v_mfma_f32_16x16x32_bf16 v[32:35], v[176:179], v[200:203], v[32:35]
	v_mfma_f32_16x16x32_bf16 v[36:39], v[180:183], v[200:203], v[36:39]
	v_mfma_f32_16x16x32_bf16 v[40:43], v[184:187], v[200:203], v[40:43]
	v_mfma_f32_16x16x32_bf16 v[44:47], v[188:191], v[200:203], v[44:47]
	v_mfma_f32_16x16x32_bf16 v[48:51], v[176:179], v[204:207], v[48:51]
	v_mfma_f32_16x16x32_bf16 v[52:55], v[180:183], v[204:207], v[52:55]
	v_mfma_f32_16x16x32_bf16 v[56:59], v[184:187], v[204:207], v[56:59]
	v_mfma_f32_16x16x32_bf16 v[60:63], v[188:191], v[204:207], v[60:63]
	v_mfma_f32_16x16x32_bf16 v[64:67], v[176:179], v[208:211], v[64:67]
	v_mfma_f32_16x16x32_bf16 v[68:71], v[180:183], v[208:211], v[68:71]
	v_mfma_f32_16x16x32_bf16 v[72:75], v[184:187], v[208:211], v[72:75]
	v_mfma_f32_16x16x32_bf16 v[76:79], v[188:191], v[208:211], v[76:79]
	v_mfma_f32_16x16x32_bf16 v[80:83], v[176:179], v[212:215], v[80:83]
	v_mfma_f32_16x16x32_bf16 v[84:87], v[180:183], v[212:215], v[84:87]
	v_mfma_f32_16x16x32_bf16 v[88:91], v[184:187], v[212:215], v[88:91]
	v_mfma_f32_16x16x32_bf16 v[92:95], v[188:191], v[212:215], v[92:95]
	s_setprio 0
	v_mfma_f32_16x16x32_bf16 v[96:99], v[176:179], v[216:219], v[96:99]
	v_mfma_f32_16x16x32_bf16 v[100:103], v[180:183], v[216:219], v[100:103]
	v_mfma_f32_16x16x32_bf16 v[104:107], v[184:187], v[216:219], v[104:107]
	v_mfma_f32_16x16x32_bf16 v[108:111], v[188:191], v[216:219], v[108:111]
	v_mfma_f32_16x16x32_bf16 v[112:115], v[176:179], v[220:223], v[112:115]
	v_mfma_f32_16x16x32_bf16 v[116:119], v[180:183], v[220:223], v[116:119]
	v_mfma_f32_16x16x32_bf16 v[120:123], v[184:187], v[220:223], v[120:123]
	v_mfma_f32_16x16x32_bf16 v[124:127], v[188:191], v[220:223], v[124:127]
	s_branch .Lg3c_epi

; #define LWRITE(S, buf) do { bf16_t* sA_ = sbase + (buf) * BUF; bf16_t* sB_ = sA_ + 256 * PITCH; \
;     _Pragma("unroll") for (int i_ = 0; i_ < 4; ++i_) *(u32x4*)(sA_ + (sr + i_ * 64) * PITCH + scv * 8) = ra[S][i_]; \
;     _Pragma("unroll") for (int i_ = 0; i_ < 2; ++i_) *(u32x4*)(sB_ + (sr + i_ * 64) * PITCH + scv * 8) = rb[S][i_]; } while (0)
; template <class Epi>
; DI void gemm_tile(char* smem, const bf16_t* __restrict__ A0, int lda0, int ksplit, const bf16_t* __restrict__ A1, int lda1,
;                   const bf16_t* __restrict__ Bt, int K, int row0, int col0, const Epi& epi, int tid) {
;   constexpr int BK = 32, PITCH = 40, BUF = (256 + 128) * PITCH;
;   bf16_t* sbase = (bf16_t*)smem;
;   const int lane = tid & 63, wid = tid >> 6, wr = wid >> 1, wc = wid & 1, fr = lane & 15, fq = lane >> 4;
;   f32x4 acc[8][4];
; #pragma unroll
;   for (int m = 0; m < 8; ++m)
; #pragma unroll
;     for (int n = 0; n < 4; ++n) acc[m][n] = (f32x4){0.f, 0.f, 0.f, 0.f};
;   u32x4 ra[2][4], rb[2][2];
;   const int nk = K / BK;
;   const int sr = tid >> 2, scv = tid & 3;
;     ...
;   __syncthreads();
;   {
;     const int last = nk - 1;
;     GLOAD(0, 0);
;     __builtin_amdgcn_sched_barrier(0);
;     GLOAD(1, 1);
;     __builtin_amdgcn_sched_barrier(0);
;     LWRITE(0, 0);
;     __builtin_amdgcn_sched_barrier(0);
;     GLOAD(0, (2 < last ? 2 : last));
;     __builtin_amdgcn_sched_barrier(0);
;     __syncthreads();
; template <class Epi>
; DI void gemm_phase(char* smem, const bf16_t* A0, int lda0, int ksplit, const bf16_t* A1, int lda1, const bf16_t* Bt, int K, int nN, const Epi& epi, int tid) {
;     ...
;     const int x = blockIdx.x & 7, l = blockIdx.x >> 3, L = G >> 3, per = 8 * nN, tot = 2 * per;
;     for (int q = l; q < tot; q += L) { const int rgl = q / per, rem = q % per, ct = rem >> 3, rt = (x * 2 + rgl) * 8 + (rem & 7);
;       gemm_tile(smem, A0, lda0, ksplit, A1, lda1, Bt, K, rt * 256, ct * 128, epi, tid); }
.Lg3d_tile:
	s_cmpk_ge_u32 s15, 64
	s_cbranch_scc1 .Lg3d_done
	s_cmpk_ge_u32 s15, 32
	s_cselect_b32 s27, 1, 0
	s_cselect_b32 s26, 32, 0
	s_sub_u32 s26, s15, s26
	s_add_u32 s27, s27, s101
	s_lshl_b32 s27, s27, 3
	s_and_b32 s29, s26, 7
	s_add_u32 s29, s29, s27
	s_lshl_b32 s29, s29, 8
	s_lshr_b32 s28, s26, 3
	s_lshl_b32 s28, s28, 7
	s_mul_i32 s27, s29, 512
	s_add_u32 s27, s27, 0x1ea00100
	s_add_u32 s0, s92, s27
	s_addc_u32 s1, s93, 0
	s_mul_i32 s27, s28, 256
	s_add_u32 s27, s27, 0x3480000
	s_add_u32 s2, s92, s27
	s_addc_u32 s3, s93, 0
	s_waitcnt lgkmcnt(0)
	s_barrier
	s_mov_b32 s99, 0
	s_mov_b32 s30, 0
	s_add_u32 s26, s30, s100
	s_add_u32 m0, s26, 0
	s_nop 0
	global_load_lds_dwordx4 v224, s[0:1]
	s_add_u32 m0, s26, 4096
	s_nop 0
	global_load_lds_dwordx4 v225, s[0:1]
	s_add_u32 m0, s26, 8192
	s_nop 0
	global_load_lds_dwordx4 v226, s[0:1]
	s_add_u32 m0, s26, 12288
	s_nop 0
	global_load_lds_dwordx4 v227, s[0:1]
	s_add_u32 m0, s26, 16384
	s_nop 0
	global_load_lds_dwordx4 v228, s[2:3]
	s_add_u32 m0, s26, 20480
	s_nop 0
	global_load_lds_dwordx4 v229, s[2:3]
	s_add_u32 s0, s0, 64
	s_addc_u32 s1, s1, 0
	s_add_u32 s2, s2, 64
	s_addc_u32 s3, s3, 0
	s_add_u32 s99, s99, 1
	s_add_u32 s30, s30, 24576
	s_cmp_eq_u32 s30, 73728
	s_cselect_b32 s30, 0, s30
	s_add_u32 s26, s30, s100
	s_add_u32 m0, s26, 0
	s_nop 0
	global_load_lds_dwordx4 v224, s[0:1]
	s_add_u32 m0, s26, 4096
	s_nop 0
	global_load_lds_dwordx4 v225, s[0:1]
	s_add_u32 m0, s26, 8192
	s_nop 0
	global_load_lds_dwordx4 v226, s[0:1]
	s_add_u32 m0, s26, 12288
	s_nop 0
	global_load_lds_dwordx4 v227, s[0:1]
	s_add_u32 m0, s26, 16384
	s_nop 0
	global_load_lds_dwordx4 v228, s[2:3]
	s_add_u32 m0, s26, 20480
	s_nop 0
	global_load_lds_dwordx4 v229, s[2:3]
	s_add_u32 s0, s0, 64
	s_addc_u32 s1, s1, 0
	s_add_u32 s2, s2, 64
	s_addc_u32 s3, s3, 0
	s_add_u32 s99, s99, 1
	s_add_u32 s30, s30, 24576
	s_cmp_eq_u32 s30, 73728
	s_cselect_b32 s30, 0, s30
	s_add_u32 s26, s30, s100
	s_add_u32 m0, s26, 0
	s_nop 0
	global_load_lds_dwordx4 v224, s[0:1]
	s_add_u32 m0, s26, 4096
	s_nop 0
	global_load_lds_dwordx4 v225, s[0:1]
	s_add_u32 m0, s26, 8192
	s_nop 0
	global_load_lds_dwordx4 v226, s[0:1]
	s_add_u32 m0, s26, 12288
	s_nop 0
	global_load_lds_dwordx4 v227, s[0:1]
	s_add_u32 m0, s26, 16384
	s_nop 0
	global_load_lds_dwordx4 v228, s[2:3]
	s_add_u32 m0, s26, 20480
	s_nop 0
	global_load_lds_dwordx4 v229, s[2:3]
	s_add_u32 s0, s0, 64
	s_addc_u32 s1, s1, 0
	s_add_u32 s2, s2, 64
	s_addc_u32 s3, s3, 0
	s_add_u32 s99, s99, 1
	s_add_u32 s30, s30, 24576
	s_cmp_eq_u32 s30, 73728
	s_cselect_b32 s30, 0, s30
	v_mov_b32_e32 v0, 0
	v_mov_b32_e32 v1, 0
	v_mov_b32_e32 v2, 0
	v_mov_b32_e32 v3, 0
	v_mov_b32_e32 v4, 0
	v_mov_b32_e32 v5, 0
	v_mov_b32_e32 v6, 0
	v_mov_b32_e32 v7, 0
	v_mov_b32_e32 v8, 0
	v_mov_b32_e32 v9, 0
	v_mov_b32_e32 v10, 0
	v_mov_b32_e32 v11, 0
	v_mov_b32_e32 v12, 0
	v_mov_b32_e32 v13, 0
	v_mov_b32_e32 v14, 0
	v_mov_b32_e32 v15, 0
	v_mov_b32_e32 v16, 0
	v_mov_b32_e32 v17, 0
	v_mov_b32_e32 v18, 0
	v_mov_b32_e32 v19, 0
	v_mov_b32_e32 v20, 0
	v_mov_b32_e32 v21, 0
	v_mov_b32_e32 v22, 0
	v_mov_b32_e32 v23, 0
	v_mov_b32_e32 v24, 0
	v_mov_b32_e32 v25, 0
	v_mov_b32_e32 v26, 0
	v_mov_b32_e32 v27, 0
	v_mov_b32_e32 v28, 0
	v_mov_b32_e32 v29, 0
	v_mov_b32_e32 v30, 0
	v_mov_b32_e32 v31, 0
	v_mov_b32_e32 v32, 0
	v_mov_b32_e32 v33, 0
	v_mov_b32_e32 v34, 0
	v_mov_b32_e32 v35, 0
	v_mov_b32_e32 v36, 0
	v_mov_b32_e32 v37, 0
	v_mov_b32_e32 v38, 0
	v_mov_b32_e32 v39, 0
	v_mov_b32_e32 v40, 0
	v_mov_b32_e32 v41, 0
	v_mov_b32_e32 v42, 0
	v_mov_b32_e32 v43, 0
	v_mov_b32_e32 v44, 0
	v_mov_b32_e32 v45, 0
	v_mov_b32_e32 v46, 0
	v_mov_b32_e32 v47, 0
	v_mov_b32_e32 v48, 0
	v_mov_b32_e32 v49, 0
	v_mov_b32_e32 v50, 0
	v_mov_b32_e32 v51, 0
	v_mov_b32_e32 v52, 0
	v_mov_b32_e32 v53, 0
	v_mov_b32_e32 v54, 0
	v_mov_b32_e32 v55, 0
	v_mov_b32_e32 v56, 0
	v_mov_b32_e32 v57, 0
	v_mov_b32_e32 v58, 0
	v_mov_b32_e32 v59, 0
	v_mov_b32_e32 v60, 0
	v_mov_b32_e32 v61, 0
	v_mov_b32_e32 v62, 0
	v_mov_b32_e32 v63, 0
	v_mov_b32_e32 v64, 0
	v_mov_b32_e32 v65, 0
	v_mov_b32_e32 v66, 0
	v_mov_b32_e32 v67, 0
	v_mov_b32_e32 v68, 0
	v_mov_b32_e32 v69, 0
	v_mov_b32_e32 v70, 0
	v_mov_b32_e32 v71, 0
	v_mov_b32_e32 v72, 0
	v_mov_b32_e32 v73, 0
	v_mov_b32_e32 v74, 0
	v_mov_b32_e32 v75, 0
	v_mov_b32_e32 v76, 0
	v_mov_b32_e32 v77, 0
	v_mov_b32_e32 v78, 0
	v_mov_b32_e32 v79, 0
	v_mov_b32_e32 v80, 0
	v_mov_b32_e32 v81, 0
	v_mov_b32_e32 v82, 0
	v_mov_b32_e32 v83, 0
	v_mov_b32_e32 v84, 0
	v_mov_b32_e32 v85, 0
	v_mov_b32_e32 v86, 0
	v_mov_b32_e32 v87, 0
	v_mov_b32_e32 v88, 0
	v_mov_b32_e32 v89, 0
	v_mov_b32_e32 v90, 0
	v_mov_b32_e32 v91, 0
	v_mov_b32_e32 v92, 0
	v_mov_b32_e32 v93, 0
	v_mov_b32_e32 v94, 0
	v_mov_b32_e32 v95, 0
	v_mov_b32_e32 v96, 0
	v_mov_b32_e32 v97, 0
	v_mov_b32_e32 v98, 0
	v_mov_b32_e32 v99, 0
	v_mov_b32_e32 v100, 0
	v_mov_b32_e32 v101, 0
	v_mov_b32_e32 v102, 0
	v_mov_b32_e32 v103, 0
	v_mov_b32_e32 v104, 0
	v_mov_b32_e32 v105, 0
	v_mov_b32_e32 v106, 0
	v_mov_b32_e32 v107, 0
	v_mov_b32_e32 v108, 0
	v_mov_b32_e32 v109, 0
	v_mov_b32_e32 v110, 0
	v_mov_b32_e32 v111, 0
	v_mov_b32_e32 v112, 0
	v_mov_b32_e32 v113, 0
	v_mov_b32_e32 v114, 0
	v_mov_b32_e32 v115, 0
	v_mov_b32_e32 v116, 0
	v_mov_b32_e32 v117, 0
	v_mov_b32_e32 v118, 0
	v_mov_b32_e32 v119, 0
	v_mov_b32_e32 v120, 0
	v_mov_b32_e32 v121, 0
	v_mov_b32_e32 v122, 0
	v_mov_b32_e32 v123, 0
	v_mov_b32_e32 v124, 0
	v_mov_b32_e32 v125, 0
	v_mov_b32_e32 v126, 0
	v_mov_b32_e32 v127, 0
	s_mov_b32 s98, 0
	s_mov_b32 s31, 24576
	s_waitcnt vmcnt(12)
	s_barrier
; #define LWRITE(S, buf) do { bf16_t* sA_ = sbase + (buf) * BUF; bf16_t* sB_ = sA_ + 256 * PITCH; \
;     _Pragma("unroll") for (int i_ = 0; i_ < 4; ++i_) *(u32x4*)(sA_ + (sr + i_ * 64) * PITCH + scv * 8) = ra[S][i_]; \
;     _Pragma("unroll") for (int i_ = 0; i_ < 2; ++i_) *(u32x4*)(sB_ + (sr + i_ * 64) * PITCH + scv * 8) = rb[S][i_]; } while (0)
; template <class Epi>
; DI void gemm_tile(char* smem, const bf16_t* __restrict__ A0, int lda0, int ksplit, const bf16_t* __restrict__ A1, int lda1,
;                   const bf16_t* __restrict__ Bt, int K, int row0, int col0, const Epi& epi, int tid) {
;     ...
;   __syncthreads();
;   {
;     const int last = nk - 1;
;     GLOAD(0, 0);
;     __builtin_amdgcn_sched_barrier(0);
;     GLOAD(1, 1);
;     __builtin_amdgcn_sched_barrier(0);
;     LWRITE(0, 0);
;     __builtin_amdgcn_sched_barrier(0);
;     GLOAD(0, (2 < last ? 2 : last));
;     __builtin_amdgcn_sched_barrier(0);
;     __syncthreads();
;     for (int kt = 0; kt < nk; kt += 2) {
;       LWRITE(1, 1);
;       __builtin_amdgcn_sched_barrier(0);
;       GLOAD(1, (kt + 3 < last ? kt + 3 : last));
;       __builtin_amdgcn_sched_barrier(0);
;       COMPUTE(0);
;       __syncthreads();
;       LWRITE(0, 0);
;       __builtin_amdgcn_sched_barrier(0);
;       GLOAD(0, (kt + 4 < last ? kt + 4 : last));
;       __builtin_amdgcn_sched_barrier(0);
;       COMPUTE(1);
;       __syncthreads();
;     }
	ds_read_b128 v[128:131], v231 offset:0
	ds_read_b128 v[132:135], v231 offset:1024
	ds_read_b128 v[136:139], v231 offset:2048
	ds_read_b128 v[140:143], v231 offset:3072
	ds_read_b128 v[144:147], v230 offset:0
	ds_read_b128 v[148:151], v230 offset:1024
	ds_read_b128 v[152:155], v230 offset:2048
	ds_read_b128 v[156:159], v230 offset:3072
	ds_read_b128 v[160:163], v230 offset:4096
	ds_read_b128 v[164:167], v230 offset:5120
	ds_read_b128 v[168:171], v230 offset:6144
	ds_read_b128 v[172:175], v230 offset:7168
	s_waitcnt vmcnt(6)
	s_waitcnt lgkmcnt(0)
	s_barrier
	v_add_u32_e32 v232, s31, v230
	v_add_u32_e32 v233, s31, v231
	s_add_u32 s26, s30, s100
	s_setprio 1
	v_mfma_f32_16x16x32_bf16 v[0:3], v[128:131], v[144:147], v[0:3]
	v_mfma_f32_16x16x32_bf16 v[4:7], v[132:135], v[144:147], v[4:7]
	v_mfma_f32_16x16x32_bf16 v[8:11], v[136:139], v[144:147], v[8:11]
	v_mfma_f32_16x16x32_bf16 v[12:15], v[140:143], v[144:147], v[12:15]
	ds_read_b128 v[176:179], v233 offset:0
	ds_read_b128 v[180:183], v233 offset:1024
	s_add_u32 m0, s26, 0
	s_nop 0
	global_load_lds_dwordx4 v224, s[0:1]
	v_mfma_f32_16x16x32_bf16 v[16:19], v[128:131], v[148:151], v[16:19]
	v_mfma_f32_16x16x32_bf16 v[20:23], v[132:135], v[148:151], v[20:23]
	v_mfma_f32_16x16x32_bf16 v[24:27], v[136:139], v[148:151], v[24:27]
	v_mfma_f32_16x16x32_bf16 v[28:31], v[140:143], v[148:151], v[28:31]
	ds_read_b128 v[184:187], v233 offset:2048
	ds_read_b128 v[188:191], v233 offset:3072
	s_add_u32 m0, s26, 4096
	s_nop 0
	global_load_lds_dwordx4 v225, s[0:1]
	v_mfma_f32_16x16x32_bf16 v[32:35], v[128:131], v[152:155], v[32:35]
	v_mfma_f32_16x16x32_bf16 v[36:39], v[132:135], v[152:155], v[36:39]
	v_mfma_f32_16x16x32_bf16 v[40:43], v[136:139], v[152:155], v[40:43]
	v_mfma_f32_16x16x32_bf16 v[44:47], v[140:143], v[152:155], v[44:47]
	ds_read_b128 v[192:195], v232 offset:0
	ds_read_b128 v[196:199], v232 offset:1024
	s_add_u32 m0, s26, 8192
	s_nop 0
	global_load_lds_dwordx4 v226, s[0:1]
	v_mfma_f32_16x16x32_bf16 v[48:51], v[128:131], v[156:159], v[48:51]
	v_mfma_f32_16x16x32_bf16 v[52:55], v[132:135], v[156:159], v[52:55]
	v_mfma_f32_16x16x32_bf16 v[56:59], v[136:139], v[156:159], v[56:59]
	v_mfma_f32_16x16x32_bf16 v[60:63], v[140:143], v[156:159], v[60:63]
	ds_read_b128 v[200:203], v232 offset:2048
	ds_read_b128 v[204:207], v232 offset:3072
	s_add_u32 m0, s26, 12288
	s_nop 0
	global_load_lds_dwordx4 v227, s[0:1]
	v_mfma_f32_16x16x32_bf16 v[64:67], v[128:131], v[160:163], v[64:67]
	v_mfma_f32_16x16x32_bf16 v[68:71], v[132:135], v[160:163], v[68:71]
	v_mfma_f32_16x16x32_bf16 v[72:75], v[136:139], v[160:163], v[72:75]
	v_mfma_f32_16x16x32_bf16 v[76:79], v[140:143], v[160:163], v[76:79]
	ds_read_b128 v[208:211], v232 offset:4096
	s_add_u32 m0, s26, 16384
	s_nop 0
	global_load_lds_dwordx4 v228, s[2:3]
	v_mfma_f32_16x16x32_bf16 v[80:83], v[128:131], v[164:167], v[80:83]
	v_mfma_f32_16x16x32_bf16 v[84:87], v[132:135], v[164:167], v[84:87]
	v_mfma_f32_16x16x32_bf16 v[88:91], v[136:139], v[164:167], v[88:91]
	v_mfma_f32_16x16x32_bf16 v[92:95], v[140:143], v[164:167], v[92:95]
	ds_read_b128 v[212:215], v232 offset:5120
	s_add_u32 m0, s26, 20480
	s_nop 0
	global_load_lds_dwordx4 v229, s[2:3]
	s_setprio 0
	v_mfma_f32_16x16x32_bf16 v[96:99], v[128:131], v[168:171], v[96:99]
	v_mfma_f32_16x16x32_bf16 v[100:103], v[132:135], v[168:171], v[100:103]
	v_mfma_f32_16x16x32_bf16 v[104:107], v[136:139], v[168:171], v[104:107]
	v_mfma_f32_16x16x32_bf16 v[108:111], v[140:143], v[168:171], v[108:111]
	ds_read_b128 v[216:219], v232 offset:6144
	s_add_u32 s0, s0, 64
	s_addc_u32 s1, s1, 0
	s_add_u32 s2, s2, 64
	s_addc_u32 s3, s3, 0
	s_add_u32 s99, s99, 1
	s_add_u32 s30, s30, 24576
	s_cmp_eq_u32 s30, 73728
	s_cselect_b32 s30, 0, s30
	s_add_u32 s31, s31, 24576
	s_cmp_eq_u32 s31, 73728
	s_cselect_b32 s31, 0, s31
	v_mfma_f32_16x16x32_bf16 v[112:115], v[128:131], v[172:175], v[112:115]
	v_mfma_f32_16x16x32_bf16 v[116:119], v[132:135], v[172:175], v[116:119]
	v_mfma_f32_16x16x32_bf16 v[120:123], v[136:139], v[172:175], v[120:123]
	v_mfma_f32_16x16x32_bf16 v[124:127], v[140:143], v[172:175], v[124:127]
	ds_read_b128 v[220:223], v232 offset:7168
	s_waitcnt vmcnt(6)
	s_waitcnt lgkmcnt(0)
	s_barrier
	v_add_u32_e32 v232, s31, v230
	v_add_u32_e32 v233, s31, v231
	s_setprio 1
	v_mfma_f32_16x16x32_bf16 v[0:3], v[176:179], v[192:195], v[0:3]
	v_mfma_f32_16x16x32_bf16 v[4:7], v[180:183], v[192:195], v[4:7]
	v_mfma_f32_16x16x32_bf16 v[8:11], v[184:187], v[192:195], v[8:11]
	v_mfma_f32_16x16x32_bf16 v[12:15], v[188:191], v[192:195], v[12:15]
	ds_read_b128 v[128:131], v233 offset:0
	ds_read_b128 v[132:135], v233 offset:1024
	v_mfma_f32_16x16x32_bf16 v[16:19], v[176:179], v[196:199], v[16:19]
	v_mfma_f32_16x16x32_bf16 v[20:23], v[180:183], v[196:199], v[20:23]
	v_mfma_f32_16x16x32_bf16 v[24:27], v[184:187], v[196:199], v[24:27]
	v_mfma_f32_16x16x32_bf16 v[28:31], v[188:191], v[196:199], v[28:31]
	ds_read_b128 v[136:139], v233 offset:2048
	ds_read_b128 v[140:143], v233 offset:3072
	v_mfma_f32_16x16x32_bf16 v[32:35], v[176:179], v[200:203], v[32:35]
	v_mfma_f32_16x16x32_bf16 v[36:39], v[180:183], v[200:203], v[36:39]
	v_mfma_f32_16x16x32_bf16 v[40:43], v[184:187], v[200:203], v[40:43]
	v_mfma_f32_16x16x32_bf16 v[44:47], v[188:191], v[200:203], v[44:47]
	ds_read_b128 v[144:147], v232 offset:0
	ds_read_b128 v[148:151], v232 offset:1024
	v_mfma_f32_16x16x32_bf16 v[48:51], v[176:179], v[204:207], v[48:51]
	v_mfma_f32_16x16x32_bf16 v[52:55], v[180:183], v[204:207], v[52:55]
	v_mfma_f32_16x16x32_bf16 v[56:59], v[184:187], v[204:207], v[56:59]
	v_mfma_f32_16x16x32_bf16 v[60:63], v[188:191], v[204:207], v[60:63]
	ds_read_b128 v[152:155], v232 offset:2048
; #define LWRITE(S, buf) do { bf16_t* sA_ = sbase + (buf) * BUF; bf16_t* sB_ = sA_ + 256 * PITCH; \
;     _Pragma("unroll") for (int i_ = 0; i_ < 4; ++i_) *(u32x4*)(sA_ + (sr + i_ * 64) * PITCH + scv * 8) = ra[S][i_]; \
;     _Pragma("unroll") for (int i_ = 0; i_ < 2; ++i_) *(u32x4*)(sB_ + (sr + i_ * 64) * PITCH + scv * 8) = rb[S][i_]; } while (0)
; template <class Epi>
; DI void gemm_tile(char* smem, const bf16_t* __restrict__ A0, int lda0, int ksplit, const bf16_t* __restrict__ A1, int lda1,
;                   const bf16_t* __restrict__ Bt, int K, int row0, int col0, const Epi& epi, int tid) {
;     ...
;   __syncthreads();
;   {
;     const int last = nk - 1;
;     GLOAD(0, 0);
;     __builtin_amdgcn_sched_barrier(0);
;     GLOAD(1, 1);
;     __builtin_amdgcn_sched_barrier(0);
;     LWRITE(0, 0);
;     __builtin_amdgcn_sched_barrier(0);
;     GLOAD(0, (2 < last ? 2 : last));
;     __builtin_amdgcn_sched_barrier(0);
;     __syncthreads();
;     for (int kt = 0; kt < nk; kt += 2) {
;       LWRITE(1, 1);
;       __builtin_amdgcn_sched_barrier(0);
;       GLOAD(1, (kt + 3 < last ? kt + 3 : last));
;       __builtin_amdgcn_sched_barrier(0);
;       COMPUTE(0);
;       __syncthreads();
;       LWRITE(0, 0);
;       __builtin_amdgcn_sched_barrier(0);
;       GLOAD(0, (kt + 4 < last ? kt + 4 : last));
;       __builtin_amdgcn_sched_barrier(0);
;       COMPUTE(1);
;       __syncthreads();
;     }
	ds_read_b128 v[156:159], v232 offset:3072
	v_mfma_f32_16x16x32_bf16 v[64:67], v[176:179], v[208:211], v[64:67]
	v_mfma_f32_16x16x32_bf16 v[68:71], v[180:183], v[208:211], v[68:71]
	v_mfma_f32_16x16x32_bf16 v[72:75], v[184:187], v[208:211], v[72:75]
	v_mfma_f32_16x16x32_bf16 v[76:79], v[188:191], v[208:211], v[76:79]
	ds_read_b128 v[160:163], v232 offset:4096
	v_mfma_f32_16x16x32_bf16 v[80:83], v[176:179], v[212:215], v[80:83]
	v_mfma_f32_16x16x32_bf16 v[84:87], v[180:183], v[212:215], v[84:87]
	v_mfma_f32_16x16x32_bf16 v[88:91], v[184:187], v[212:215], v[88:91]
	v_mfma_f32_16x16x32_bf16 v[92:95], v[188:191], v[212:215], v[92:95]
	ds_read_b128 v[164:167], v232 offset:5120
	s_setprio 0
	v_mfma_f32_16x16x32_bf16 v[96:99], v[176:179], v[216:219], v[96:99]
	v_mfma_f32_16x16x32_bf16 v[100:103], v[180:183], v[216:219], v[100:103]
	v_mfma_f32_16x16x32_bf16 v[104:107], v[184:187], v[216:219], v[104:107]
	v_mfma_f32_16x16x32_bf16 v[108:111], v[188:191], v[216:219], v[108:111]
	ds_read_b128 v[168:171], v232 offset:6144
	s_add_u32 s31, s31, 24576
	s_cmp_eq_u32 s31, 73728
	s_cselect_b32 s31, 0, s31
	v_mfma_f32_16x16x32_bf16 v[112:115], v[176:179], v[220:223], v[112:115]
	v_mfma_f32_16x16x32_bf16 v[116:119], v[180:183], v[220:223], v[116:119]
	v_mfma_f32_16x16x32_bf16 v[120:123], v[184:187], v[220:223], v[120:123]
	v_mfma_f32_16x16x32_bf16 v[124:127], v[188:191], v[220:223], v[124:127]
	ds_read_b128 v[172:175], v232 offset:7168
	s_waitcnt vmcnt(0)
	s_waitcnt lgkmcnt(0)
	s_barrier
	v_add_u32_e32 v232, s31, v230
	v_add_u32_e32 v233, s31, v231
	s_setprio 1
	v_mfma_f32_16x16x32_bf16 v[0:3], v[128:131], v[144:147], v[0:3]
	v_mfma_f32_16x16x32_bf16 v[4:7], v[132:135], v[144:147], v[4:7]
	v_mfma_f32_16x16x32_bf16 v[8:11], v[136:139], v[144:147], v[8:11]
	v_mfma_f32_16x16x32_bf16 v[12:15], v[140:143], v[144:147], v[12:15]
	ds_read_b128 v[176:179], v233 offset:0
	ds_read_b128 v[180:183], v233 offset:1024
	v_mfma_f32_16x16x32_bf16 v[16:19], v[128:131], v[148:151], v[16:19]
	v_mfma_f32_16x16x32_bf16 v[20:23], v[132:135], v[148:151], v[20:23]
	v_mfma_f32_16x16x32_bf16 v[24:27], v[136:139], v[148:151], v[24:27]
	v_mfma_f32_16x16x32_bf16 v[28:31], v[140:143], v[148:151], v[28:31]
	ds_read_b128 v[184:187], v233 offset:2048
	ds_read_b128 v[188:191], v233 offset:3072
	v_mfma_f32_16x16x32_bf16 v[32:35], v[128:131], v[152:155], v[32:35]
	v_mfma_f32_16x16x32_bf16 v[36:39], v[132:135], v[152:155], v[36:39]
	v_mfma_f32_16x16x32_bf16 v[40:43], v[136:139], v[152:155], v[40:43]
	v_mfma_f32_16x16x32_bf16 v[44:47], v[140:143], v[152:155], v[44:47]
	ds_read_b128 v[192:195], v232 offset:0
	ds_read_b128 v[196:199], v232 offset:1024
	v_mfma_f32_16x16x32_bf16 v[48:51], v[128:131], v[156:159], v[48:51]
	v_mfma_f32_16x16x32_bf16 v[52:55], v[132:135], v[156:159], v[52:55]
	v_mfma_f32_16x16x32_bf16 v[56:59], v[136:139], v[156:159], v[56:59]
	v_mfma_f32_16x16x32_bf16 v[60:63], v[140:143], v[156:159], v[60:63]
	ds_read_b128 v[200:203], v232 offset:2048
	ds_read_b128 v[204:207], v232 offset:3072
	v_mfma_f32_16x16x32_bf16 v[64:67], v[128:131], v[160:163], v[64:67]
	v_mfma_f32_16x16x32_bf16 v[68:71], v[132:135], v[160:163], v[68:71]
	v_mfma_f32_16x16x32_bf16 v[72:75], v[136:139], v[160:163], v[72:75]
	v_mfma_f32_16x16x32_bf16 v[76:79], v[140:143], v[160:163], v[76:79]
	ds_read_b128 v[208:211], v232 offset:4096
	v_mfma_f32_16x16x32_bf16 v[80:83], v[128:131], v[164:167], v[80:83]
	v_mfma_f32_16x16x32_bf16 v[84:87], v[132:135], v[164:167], v[84:87]
	v_mfma_f32_16x16x32_bf16 v[88:91], v[136:139], v[164:167], v[88:91]
	v_mfma_f32_16x16x32_bf16 v[92:95], v[140:143], v[164:167], v[92:95]
	ds_read_b128 v[212:215], v232 offset:5120
	s_setprio 0
	v_mfma_f32_16x16x32_bf16 v[96:99], v[128:131], v[168:171], v[96:99]
	v_mfma_f32_16x16x32_bf16 v[100:103], v[132:135], v[168:171], v[100:103]
	v_mfma_f32_16x16x32_bf16 v[104:107], v[136:139], v[168:171], v[104:107]
	v_mfma_f32_16x16x32_bf16 v[108:111], v[140:143], v[168:171], v[108:111]
	ds_read_b128 v[216:219], v232 offset:6144
	s_add_u32 s31, s31, 24576
	s_cmp_eq_u32 s31, 73728
	s_cselect_b32 s31, 0, s31
	v_mfma_f32_16x16x32_bf16 v[112:115], v[128:131], v[172:175], v[112:115]
	v_mfma_f32_16x16x32_bf16 v[116:119], v[132:135], v[172:175], v[116:119]
	v_mfma_f32_16x16x32_bf16 v[120:123], v[136:139], v[172:175], v[120:123]
	v_mfma_f32_16x16x32_bf16 v[124:127], v[140:143], v[172:175], v[124:127]
	ds_read_b128 v[220:223], v232 offset:7168
	s_waitcnt lgkmcnt(0)
	s_barrier
	s_setprio 1
	v_mfma_f32_16x16x32_bf16 v[0:3], v[176:179], v[192:195], v[0:3]
	v_mfma_f32_16x16x32_bf16 v[4:7], v[180:183], v[192:195], v[4:7]
	v_mfma_f32_16x16x32_bf16 v[8:11], v[184:187], v[192:195], v[8:11]
	v_mfma_f32_16x16x32_bf16 v[12:15], v[188:191], v[192:195], v[12:15]
	v_mfma_f32_16x16x32_bf16 v[16:19], v[176:179], v[196:199], v[16:19]
	v_mfma_f32_16x16x32_bf16 v[20:23], v[180:183], v[196:199], v[20:23]
	v_mfma_f32_16x16x32_bf16 v[24:27], v[184:187], v[196:199], v[24:27]
	v_mfma_f32_16x16x32_bf16 v[28:31], v[188:191], v[196:199], v[28:31]
	v_mfma_f32_16x16x32_bf16 v[32:35], v[176:179], v[200:203], v[32:35]
	v_mfma_f32_16x16x32_bf16 v[36:39], v[180:183], v[200:203], v[36:39]
	v_mfma_f32_16x16x32_bf16 v[40:43], v[184:187], v[200:203], v[40:43]
	v_mfma_f32_16x16x32_bf16 v[44:47], v[188:191], v[200:203], v[44:47]
	v_mfma_f32_16x16x32_bf16 v[48:51], v[176:179], v[204:207], v[48:51]
	v_mfma_f32_16x16x32_bf16 v[52:55], v[180:183], v[204:207], v[52:55]
	v_mfma_f32_16x16x32_bf16 v[56:59], v[184:187], v[204:207], v[56:59]
	v_mfma_f32_16x16x32_bf16 v[60:63], v[188:191], v[204:207], v[60:63]
	v_mfma_f32_16x16x32_bf16 v[64:67], v[176:179], v[208:211], v[64:67]
	v_mfma_f32_16x16x32_bf16 v[68:71], v[180:183], v[208:211], v[68:71]
	v_mfma_f32_16x16x32_bf16 v[72:75], v[184:187], v[208:211], v[72:75]
	v_mfma_f32_16x16x32_bf16 v[76:79], v[188:191], v[208:211], v[76:79]
	v_mfma_f32_16x16x32_bf16 v[80:83], v[176:179], v[212:215], v[80:83]
	v_mfma_f32_16x16x32_bf16 v[84:87], v[180:183], v[212:215], v[84:87]
	v_mfma_f32_16x16x32_bf16 v[88:91], v[184:187], v[212:215], v[88:91]
	v_mfma_f32_16x16x32_bf16 v[92:95], v[188:191], v[212:215], v[92:95]
	s_setprio 0
	v_mfma_f32_16x16x32_bf16 v[96:99], v[176:179], v[216:219], v[96:99]
	v_mfma_f32_16x16x32_bf16 v[100:103], v[180:183], v[216:219], v[100:103]
	v_mfma_f32_16x16x32_bf16 v[104:107], v[184:187], v[216:219], v[104:107]
	v_mfma_f32_16x16x32_bf16 v[108:111], v[188:191], v[216:219], v[108:111]
	v_mfma_f32_16x16x32_bf16 v[112:115], v[176:179], v[220:223], v[112:115]
	v_mfma_f32_16x16x32_bf16 v[116:119], v[180:183], v[220:223], v[116:119]
	v_mfma_f32_16x16x32_bf16 v[120:123], v[184:187], v[220:223], v[120:123]
	v_mfma_f32_16x16x32_bf16 v[124:127], v[188:191], v[220:223], v[124:127]
	s_branch .Lg3d_epi

; #define LWRITE(S, buf) do { bf16_t* sA_ = sbase + (buf) * BUF; bf16_t* sB_ = sA_ + 256 * PITCH; \
;     _Pragma("unroll") for (int i_ = 0; i_ < 4; ++i_) *(u32x4*)(sA_ + (sr + i_ * 64) * PITCH + scv * 8) = ra[S][i_]; \
;     _Pragma("unroll") for (int i_ = 0; i_ < 2; ++i_) *(u32x4*)(sB_ + (sr + i_ * 64) * PITCH + scv * 8) = rb[S][i_]; } while (0)
; template <class Epi>
; DI void gemm_tile(char* smem, const bf16_t* __restrict__ A0, int lda0, int ksplit, const bf16_t* __restrict__ A1, int lda1,
;                   const bf16_t* __restrict__ Bt, int K, int row0, int col0, const Epi& epi, int tid) {
;     ...
;     for (int kt = 0; kt < nk; kt += 2) {
;       LWRITE(1, 1);
;       __builtin_amdgcn_sched_barrier(0);
;       GLOAD(1, (kt + 3 < last ? kt + 3 : last));
;       __builtin_amdgcn_sched_barrier(0);
;       COMPUTE(0);
;       __syncthreads();
;       LWRITE(0, 0);
;       __builtin_amdgcn_sched_barrier(0);
;       GLOAD(0, (kt + 4 < last ? kt + 4 : last));
;       __builtin_amdgcn_sched_barrier(0);
;       COMPUTE(1);
;       __syncthreads();
;     }
.Lg6_swb0:
	s_waitcnt vmcnt(6)
	s_waitcnt lgkmcnt(0)
	s_barrier
	v_add_u32_e32 v232, s100, v230
	v_add_u32_e32 v233, s100, v231
	s_add_u32 s19, s99, s13
	s_setprio 1
	v_mfma_f32_16x16x32_bf16 v[0:3], v[128:131], v[144:147], v[0:3]
	v_mfma_f32_16x16x32_bf16 v[4:7], v[132:135], v[144:147], v[4:7]
	v_mfma_f32_16x16x32_bf16 v[8:11], v[136:139], v[144:147], v[8:11]
	v_mfma_f32_16x16x32_bf16 v[12:15], v[140:143], v[144:147], v[12:15]
	ds_read_b128 v[176:179], v233 offset:0
	ds_read_b128 v[180:183], v233 offset:1024
	s_add_u32 m0, s19, 0
	s_nop 0
	global_load_lds_dwordx4 v224, s[0:1]
	v_mfma_f32_16x16x32_bf16 v[16:19], v[128:131], v[148:151], v[16:19]
	v_mfma_f32_16x16x32_bf16 v[20:23], v[132:135], v[148:151], v[20:23]
	v_mfma_f32_16x16x32_bf16 v[24:27], v[136:139], v[148:151], v[24:27]
	v_mfma_f32_16x16x32_bf16 v[28:31], v[140:143], v[148:151], v[28:31]
	ds_read_b128 v[184:187], v233 offset:2048
	ds_read_b128 v[188:191], v233 offset:3072
	s_add_u32 m0, s19, 4096
	s_nop 0
	global_load_lds_dwordx4 v225, s[0:1]
	v_mfma_f32_16x16x32_bf16 v[32:35], v[128:131], v[152:155], v[32:35]
	v_mfma_f32_16x16x32_bf16 v[36:39], v[132:135], v[152:155], v[36:39]
	v_mfma_f32_16x16x32_bf16 v[40:43], v[136:139], v[152:155], v[40:43]
	v_mfma_f32_16x16x32_bf16 v[44:47], v[140:143], v[152:155], v[44:47]
	ds_read_b128 v[192:195], v232 offset:0
	ds_read_b128 v[196:199], v232 offset:1024
	s_add_u32 m0, s19, 8192
	s_nop 0
	global_load_lds_dwordx4 v226, s[0:1]
	v_mfma_f32_16x16x32_bf16 v[48:51], v[128:131], v[156:159], v[48:51]
	v_mfma_f32_16x16x32_bf16 v[52:55], v[132:135], v[156:159], v[52:55]
	v_mfma_f32_16x16x32_bf16 v[56:59], v[136:139], v[156:159], v[56:59]
	v_mfma_f32_16x16x32_bf16 v[60:63], v[140:143], v[156:159], v[60:63]
	ds_read_b128 v[200:203], v232 offset:2048
	ds_read_b128 v[204:207], v232 offset:3072
	s_add_u32 m0, s19, 12288
	s_nop 0
	global_load_lds_dwordx4 v227, s[0:1]
	v_mfma_f32_16x16x32_bf16 v[64:67], v[128:131], v[160:163], v[64:67]
	v_mfma_f32_16x16x32_bf16 v[68:71], v[132:135], v[160:163], v[68:71]
	v_mfma_f32_16x16x32_bf16 v[72:75], v[136:139], v[160:163], v[72:75]
	v_mfma_f32_16x16x32_bf16 v[76:79], v[140:143], v[160:163], v[76:79]
	ds_read_b128 v[208:211], v232 offset:4096
	s_add_u32 m0, s19, 16384
	s_nop 0
	global_load_lds_dwordx4 v228, s[2:3]
	v_mfma_f32_16x16x32_bf16 v[80:83], v[128:131], v[164:167], v[80:83]
	v_mfma_f32_16x16x32_bf16 v[84:87], v[132:135], v[164:167], v[84:87]
	v_mfma_f32_16x16x32_bf16 v[88:91], v[136:139], v[164:167], v[88:91]
	v_mfma_f32_16x16x32_bf16 v[92:95], v[140:143], v[164:167], v[92:95]
	ds_read_b128 v[212:215], v232 offset:5120
	s_add_u32 m0, s19, 20480
	s_nop 0
	global_load_lds_dwordx4 v229, s[2:3]
	s_setprio 0
	v_mfma_f32_16x16x32_bf16 v[96:99], v[128:131], v[168:171], v[96:99]
	v_mfma_f32_16x16x32_bf16 v[100:103], v[132:135], v[168:171], v[100:103]
	v_mfma_f32_16x16x32_bf16 v[104:107], v[136:139], v[168:171], v[104:107]
	v_mfma_f32_16x16x32_bf16 v[108:111], v[140:143], v[168:171], v[108:111]
	ds_read_b128 v[216:219], v232 offset:6144
	s_add_u32 s0, s0, 64
	s_addc_u32 s1, s1, 0
	s_add_u32 s2, s2, 64
	s_addc_u32 s3, s3, 0
	s_add_u32 s22, s22, 1
	s_add_u32 s99, s99, 24576
	s_cmp_eq_u32 s99, 73728
	s_cselect_b32 s99, 0, s99
	s_add_u32 s100, s100, 24576
	s_cmp_eq_u32 s100, 73728
	s_cselect_b32 s100, 0, s100
	v_mfma_f32_16x16x32_bf16 v[112:115], v[128:131], v[172:175], v[112:115]
	v_mfma_f32_16x16x32_bf16 v[116:119], v[132:135], v[172:175], v[116:119]
	v_mfma_f32_16x16x32_bf16 v[120:123], v[136:139], v[172:175], v[120:123]
	v_mfma_f32_16x16x32_bf16 v[124:127], v[140:143], v[172:175], v[124:127]
	ds_read_b128 v[220:223], v232 offset:7168
	s_cmp_eq_u32 s22, 16
	s_cbranch_scc1 .Lg6_sw1
.Lg6_swb1:
	s_waitcnt vmcnt(6)
	s_waitcnt lgkmcnt(0)
	s_barrier
	v_add_u32_e32 v232, s100, v230
	v_add_u32_e32 v233, s100, v231
	s_add_u32 s19, s99, s13
	s_setprio 1
	v_mfma_f32_16x16x32_bf16 v[0:3], v[176:179], v[192:195], v[0:3]
	v_mfma_f32_16x16x32_bf16 v[4:7], v[180:183], v[192:195], v[4:7]
	v_mfma_f32_16x16x32_bf16 v[8:11], v[184:187], v[192:195], v[8:11]
	v_mfma_f32_16x16x32_bf16 v[12:15], v[188:191], v[192:195], v[12:15]
	ds_read_b128 v[128:131], v233 offset:0
	ds_read_b128 v[132:135], v233 offset:1024
	s_add_u32 m0, s19, 0
	s_nop 0
	global_load_lds_dwordx4 v224, s[0:1]
	v_mfma_f32_16x16x32_bf16 v[16:19], v[176:179], v[196:199], v[16:19]
	v_mfma_f32_16x16x32_bf16 v[20:23], v[180:183], v[196:199], v[20:23]
	v_mfma_f32_16x16x32_bf16 v[24:27], v[184:187], v[196:199], v[24:27]
	v_mfma_f32_16x16x32_bf16 v[28:31], v[188:191], v[196:199], v[28:31]
	ds_read_b128 v[136:139], v233 offset:2048
	ds_read_b128 v[140:143], v233 offset:3072
	s_add_u32 m0, s19, 4096
	s_nop 0
	global_load_lds_dwordx4 v225, s[0:1]
	v_mfma_f32_16x16x32_bf16 v[32:35], v[176:179], v[200:203], v[32:35]
	v_mfma_f32_16x16x32_bf16 v[36:39], v[180:183], v[200:203], v[36:39]
	v_mfma_f32_16x16x32_bf16 v[40:43], v[184:187], v[200:203], v[40:43]
	v_mfma_f32_16x16x32_bf16 v[44:47], v[188:191], v[200:203], v[44:47]
	ds_read_b128 v[144:147], v232 offset:0
	ds_read_b128 v[148:151], v232 offset:1024
	s_add_u32 m0, s19, 8192
	s_nop 0
	global_load_lds_dwordx4 v226, s[0:1]
	v_mfma_f32_16x16x32_bf16 v[48:51], v[176:179], v[204:207], v[48:51]
	v_mfma_f32_16x16x32_bf16 v[52:55], v[180:183], v[204:207], v[52:55]
	v_mfma_f32_16x16x32_bf16 v[56:59], v[184:187], v[204:207], v[56:59]
	v_mfma_f32_16x16x32_bf16 v[60:63], v[188:191], v[204:207], v[60:63]
	ds_read_b128 v[152:155], v232 offset:2048
	ds_read_b128 v[156:159], v232 offset:3072
	s_add_u32 m0, s19, 12288
	s_nop 0
	global_load_lds_dwordx4 v227, s[0:1]
	v_mfma_f32_16x16x32_bf16 v[64:67], v[176:179], v[208:211], v[64:67]
; #define LWRITE(S, buf) do { bf16_t* sA_ = sbase + (buf) * BUF; bf16_t* sB_ = sA_ + 256 * PITCH; \
;     _Pragma("unroll") for (int i_ = 0; i_ < 4; ++i_) *(u32x4*)(sA_ + (sr + i_ * 64) * PITCH + scv * 8) = ra[S][i_]; \
;     _Pragma("unroll") for (int i_ = 0; i_ < 2; ++i_) *(u32x4*)(sB_ + (sr + i_ * 64) * PITCH + scv * 8) = rb[S][i_]; } while (0)
; template <class Epi>
; DI void gemm_tile(char* smem, const bf16_t* __restrict__ A0, int lda0, int ksplit, const bf16_t* __restrict__ A1, int lda1,
;                   const bf16_t* __restrict__ Bt, int K, int row0, int col0, const Epi& epi, int tid) {
;     ...
;     for (int kt = 0; kt < nk; kt += 2) {
;       LWRITE(1, 1);
;       __builtin_amdgcn_sched_barrier(0);
;       GLOAD(1, (kt + 3 < last ? kt + 3 : last));
;       __builtin_amdgcn_sched_barrier(0);
;       COMPUTE(0);
;       __syncthreads();
;       LWRITE(0, 0);
;       __builtin_amdgcn_sched_barrier(0);
;       GLOAD(0, (kt + 4 < last ? kt + 4 : last));
;       __builtin_amdgcn_sched_barrier(0);
;       COMPUTE(1);
;       __syncthreads();
;     }
	v_mfma_f32_16x16x32_bf16 v[68:71], v[180:183], v[208:211], v[68:71]
	v_mfma_f32_16x16x32_bf16 v[72:75], v[184:187], v[208:211], v[72:75]
	v_mfma_f32_16x16x32_bf16 v[76:79], v[188:191], v[208:211], v[76:79]
	ds_read_b128 v[160:163], v232 offset:4096
	s_add_u32 m0, s19, 16384
	s_nop 0
	global_load_lds_dwordx4 v228, s[2:3]
	v_mfma_f32_16x16x32_bf16 v[80:83], v[176:179], v[212:215], v[80:83]
	v_mfma_f32_16x16x32_bf16 v[84:87], v[180:183], v[212:215], v[84:87]
	v_mfma_f32_16x16x32_bf16 v[88:91], v[184:187], v[212:215], v[88:91]
	v_mfma_f32_16x16x32_bf16 v[92:95], v[188:191], v[212:215], v[92:95]
	ds_read_b128 v[164:167], v232 offset:5120
	s_add_u32 m0, s19, 20480
	s_nop 0
	global_load_lds_dwordx4 v229, s[2:3]
	s_setprio 0
	v_mfma_f32_16x16x32_bf16 v[96:99], v[176:179], v[216:219], v[96:99]
	v_mfma_f32_16x16x32_bf16 v[100:103], v[180:183], v[216:219], v[100:103]
	v_mfma_f32_16x16x32_bf16 v[104:107], v[184:187], v[216:219], v[104:107]
	v_mfma_f32_16x16x32_bf16 v[108:111], v[188:191], v[216:219], v[108:111]
	ds_read_b128 v[168:171], v232 offset:6144
	s_add_u32 s0, s0, 64
	s_addc_u32 s1, s1, 0
	s_add_u32 s2, s2, 64
	s_addc_u32 s3, s3, 0
	s_add_u32 s22, s22, 1
	s_add_u32 s99, s99, 24576
	s_cmp_eq_u32 s99, 73728
	s_cselect_b32 s99, 0, s99
	s_add_u32 s100, s100, 24576
	s_cmp_eq_u32 s100, 73728
	s_cselect_b32 s100, 0, s100
	v_mfma_f32_16x16x32_bf16 v[112:115], v[176:179], v[220:223], v[112:115]
	v_mfma_f32_16x16x32_bf16 v[116:119], v[180:183], v[220:223], v[116:119]
	v_mfma_f32_16x16x32_bf16 v[120:123], v[184:187], v[220:223], v[120:123]
	v_mfma_f32_16x16x32_bf16 v[124:127], v[188:191], v[220:223], v[124:127]
	ds_read_b128 v[172:175], v232 offset:7168
	s_add_u32 s101, s101, 2
	s_cmp_lt_u32 s101, 44
	s_cbranch_scc1 .Lg6_kloop
	s_cmp_eq_u32 s22, 16
	s_cbranch_scc1 .Lg6_sw2
.Lg6_swb2:
	s_waitcnt vmcnt(6)
	s_waitcnt lgkmcnt(0)
	s_barrier
	v_add_u32_e32 v232, s100, v230
	v_add_u32_e32 v233, s100, v231
	s_add_u32 s19, s99, s13
	s_setprio 1
	v_mfma_f32_16x16x32_bf16 v[0:3], v[128:131], v[144:147], v[0:3]
	v_mfma_f32_16x16x32_bf16 v[4:7], v[132:135], v[144:147], v[4:7]
	v_mfma_f32_16x16x32_bf16 v[8:11], v[136:139], v[144:147], v[8:11]
	v_mfma_f32_16x16x32_bf16 v[12:15], v[140:143], v[144:147], v[12:15]
	ds_read_b128 v[176:179], v233 offset:0
	ds_read_b128 v[180:183], v233 offset:1024
	s_add_u32 m0, s19, 0
	s_nop 0
	global_load_lds_dwordx4 v224, s[0:1]
	v_mfma_f32_16x16x32_bf16 v[16:19], v[128:131], v[148:151], v[16:19]
	v_mfma_f32_16x16x32_bf16 v[20:23], v[132:135], v[148:151], v[20:23]
	v_mfma_f32_16x16x32_bf16 v[24:27], v[136:139], v[148:151], v[24:27]
	v_mfma_f32_16x16x32_bf16 v[28:31], v[140:143], v[148:151], v[28:31]
	ds_read_b128 v[184:187], v233 offset:2048
	ds_read_b128 v[188:191], v233 offset:3072
	s_add_u32 m0, s19, 4096
	s_nop 0
	global_load_lds_dwordx4 v225, s[0:1]
	v_mfma_f32_16x16x32_bf16 v[32:35], v[128:131], v[152:155], v[32:35]
	v_mfma_f32_16x16x32_bf16 v[36:39], v[132:135], v[152:155], v[36:39]
	v_mfma_f32_16x16x32_bf16 v[40:43], v[136:139], v[152:155], v[40:43]
	v_mfma_f32_16x16x32_bf16 v[44:47], v[140:143], v[152:155], v[44:47]
	ds_read_b128 v[192:195], v232 offset:0
	ds_read_b128 v[196:199], v232 offset:1024
	s_add_u32 m0, s19, 8192
	s_nop 0
	global_load_lds_dwordx4 v226, s[0:1]
	v_mfma_f32_16x16x32_bf16 v[48:51], v[128:131], v[156:159], v[48:51]
	v_mfma_f32_16x16x32_bf16 v[52:55], v[132:135], v[156:159], v[52:55]
	v_mfma_f32_16x16x32_bf16 v[56:59], v[136:139], v[156:159], v[56:59]
	v_mfma_f32_16x16x32_bf16 v[60:63], v[140:143], v[156:159], v[60:63]
	ds_read_b128 v[200:203], v232 offset:2048
	ds_read_b128 v[204:207], v232 offset:3072
	s_add_u32 m0, s19, 12288
	s_nop 0
	global_load_lds_dwordx4 v227, s[0:1]
	v_mfma_f32_16x16x32_bf16 v[64:67], v[128:131], v[160:163], v[64:67]
	v_mfma_f32_16x16x32_bf16 v[68:71], v[132:135], v[160:163], v[68:71]
	v_mfma_f32_16x16x32_bf16 v[72:75], v[136:139], v[160:163], v[72:75]
	v_mfma_f32_16x16x32_bf16 v[76:79], v[140:143], v[160:163], v[76:79]
	ds_read_b128 v[208:211], v232 offset:4096
	s_add_u32 m0, s19, 16384
	s_nop 0
	global_load_lds_dwordx4 v228, s[2:3]
	v_mfma_f32_16x16x32_bf16 v[80:83], v[128:131], v[164:167], v[80:83]
	v_mfma_f32_16x16x32_bf16 v[84:87], v[132:135], v[164:167], v[84:87]
	v_mfma_f32_16x16x32_bf16 v[88:91], v[136:139], v[164:167], v[88:91]
	v_mfma_f32_16x16x32_bf16 v[92:95], v[140:143], v[164:167], v[92:95]
	ds_read_b128 v[212:215], v232 offset:5120
	s_add_u32 m0, s19, 20480
	s_nop 0
	global_load_lds_dwordx4 v229, s[2:3]
	s_setprio 0
	v_mfma_f32_16x16x32_bf16 v[96:99], v[128:131], v[168:171], v[96:99]
	v_mfma_f32_16x16x32_bf16 v[100:103], v[132:135], v[168:171], v[100:103]
	v_mfma_f32_16x16x32_bf16 v[104:107], v[136:139], v[168:171], v[104:107]
	v_mfma_f32_16x16x32_bf16 v[108:111], v[140:143], v[168:171], v[108:111]
	ds_read_b128 v[216:219], v232 offset:6144
	s_add_u32 s0, s0, 64
	s_addc_u32 s1, s1, 0
	s_add_u32 s2, s2, 64
	s_addc_u32 s3, s3, 0
	s_add_u32 s22, s22, 1
	s_add_u32 s99, s99, 24576
	s_cmp_eq_u32 s99, 73728
	s_cselect_b32 s99, 0, s99
	s_add_u32 s100, s100, 24576
	s_cmp_eq_u32 s100, 73728
	s_cselect_b32 s100, 0, s100
	v_mfma_f32_16x16x32_bf16 v[112:115], v[128:131], v[172:175], v[112:115]
	v_mfma_f32_16x16x32_bf16 v[116:119], v[132:135], v[172:175], v[116:119]
	v_mfma_f32_16x16x32_bf16 v[120:123], v[136:139], v[172:175], v[120:123]
	v_mfma_f32_16x16x32_bf16 v[124:127], v[140:143], v[172:175], v[124:127]
	ds_read_b128 v[220:223], v232 offset:7168
	s_waitcnt vmcnt(6)
	s_waitcnt lgkmcnt(0)
	s_barrier
; #define LWRITE(S, buf) do { bf16_t* sA_ = sbase + (buf) * BUF; bf16_t* sB_ = sA_ + 256 * PITCH; \
;     _Pragma("unroll") for (int i_ = 0; i_ < 4; ++i_) *(u32x4*)(sA_ + (sr + i_ * 64) * PITCH + scv * 8) = ra[S][i_]; \
;     _Pragma("unroll") for (int i_ = 0; i_ < 2; ++i_) *(u32x4*)(sB_ + (sr + i_ * 64) * PITCH + scv * 8) = rb[S][i_]; } while (0)
; template <class Epi>
; DI void gemm_tile(char* smem, const bf16_t* __restrict__ A0, int lda0, int ksplit, const bf16_t* __restrict__ A1, int lda1,
;                   const bf16_t* __restrict__ Bt, int K, int row0, int col0, const Epi& epi, int tid) {
;     ...
;     for (int kt = 0; kt < nk; kt += 2) {
;       LWRITE(1, 1);
;       __builtin_amdgcn_sched_barrier(0);
;       GLOAD(1, (kt + 3 < last ? kt + 3 : last));
;       __builtin_amdgcn_sched_barrier(0);
;       COMPUTE(0);
;       __syncthreads();
;       LWRITE(0, 0);
;       __builtin_amdgcn_sched_barrier(0);
;       GLOAD(0, (kt + 4 < last ? kt + 4 : last));
;       __builtin_amdgcn_sched_barrier(0);
;       COMPUTE(1);
;       __syncthreads();
;     }
	v_add_u32_e32 v232, s100, v230
	v_add_u32_e32 v233, s100, v231
	s_setprio 1
	v_mfma_f32_16x16x32_bf16 v[0:3], v[176:179], v[192:195], v[0:3]
	v_mfma_f32_16x16x32_bf16 v[4:7], v[180:183], v[192:195], v[4:7]
	v_mfma_f32_16x16x32_bf16 v[8:11], v[184:187], v[192:195], v[8:11]
	v_mfma_f32_16x16x32_bf16 v[12:15], v[188:191], v[192:195], v[12:15]
	ds_read_b128 v[128:131], v233 offset:0
	ds_read_b128 v[132:135], v233 offset:1024
	v_mfma_f32_16x16x32_bf16 v[16:19], v[176:179], v[196:199], v[16:19]
	v_mfma_f32_16x16x32_bf16 v[20:23], v[180:183], v[196:199], v[20:23]
	v_mfma_f32_16x16x32_bf16 v[24:27], v[184:187], v[196:199], v[24:27]
	v_mfma_f32_16x16x32_bf16 v[28:31], v[188:191], v[196:199], v[28:31]
	ds_read_b128 v[136:139], v233 offset:2048
	ds_read_b128 v[140:143], v233 offset:3072
	v_mfma_f32_16x16x32_bf16 v[32:35], v[176:179], v[200:203], v[32:35]
	v_mfma_f32_16x16x32_bf16 v[36:39], v[180:183], v[200:203], v[36:39]
	v_mfma_f32_16x16x32_bf16 v[40:43], v[184:187], v[200:203], v[40:43]
	v_mfma_f32_16x16x32_bf16 v[44:47], v[188:191], v[200:203], v[44:47]
	ds_read_b128 v[144:147], v232 offset:0
	ds_read_b128 v[148:151], v232 offset:1024
	v_mfma_f32_16x16x32_bf16 v[48:51], v[176:179], v[204:207], v[48:51]
	v_mfma_f32_16x16x32_bf16 v[52:55], v[180:183], v[204:207], v[52:55]
	v_mfma_f32_16x16x32_bf16 v[56:59], v[184:187], v[204:207], v[56:59]
	v_mfma_f32_16x16x32_bf16 v[60:63], v[188:191], v[204:207], v[60:63]
	ds_read_b128 v[152:155], v232 offset:2048
	ds_read_b128 v[156:159], v232 offset:3072
	v_mfma_f32_16x16x32_bf16 v[64:67], v[176:179], v[208:211], v[64:67]
	v_mfma_f32_16x16x32_bf16 v[68:71], v[180:183], v[208:211], v[68:71]
	v_mfma_f32_16x16x32_bf16 v[72:75], v[184:187], v[208:211], v[72:75]
	v_mfma_f32_16x16x32_bf16 v[76:79], v[188:191], v[208:211], v[76:79]
	ds_read_b128 v[160:163], v232 offset:4096
	v_mfma_f32_16x16x32_bf16 v[80:83], v[176:179], v[212:215], v[80:83]
	v_mfma_f32_16x16x32_bf16 v[84:87], v[180:183], v[212:215], v[84:87]
	v_mfma_f32_16x16x32_bf16 v[88:91], v[184:187], v[212:215], v[88:91]
	v_mfma_f32_16x16x32_bf16 v[92:95], v[188:191], v[212:215], v[92:95]
	ds_read_b128 v[164:167], v232 offset:5120
	s_setprio 0
	v_mfma_f32_16x16x32_bf16 v[96:99], v[176:179], v[216:219], v[96:99]
	v_mfma_f32_16x16x32_bf16 v[100:103], v[180:183], v[216:219], v[100:103]
	v_mfma_f32_16x16x32_bf16 v[104:107], v[184:187], v[216:219], v[104:107]
	v_mfma_f32_16x16x32_bf16 v[108:111], v[188:191], v[216:219], v[108:111]
	ds_read_b128 v[168:171], v232 offset:6144
	s_add_u32 s100, s100, 24576
	s_cmp_eq_u32 s100, 73728
	s_cselect_b32 s100, 0, s100
	v_mfma_f32_16x16x32_bf16 v[112:115], v[176:179], v[220:223], v[112:115]
	v_mfma_f32_16x16x32_bf16 v[116:119], v[180:183], v[220:223], v[116:119]
	v_mfma_f32_16x16x32_bf16 v[120:123], v[184:187], v[220:223], v[120:123]
	v_mfma_f32_16x16x32_bf16 v[124:127], v[188:191], v[220:223], v[124:127]
	ds_read_b128 v[172:175], v232 offset:7168
	s_waitcnt vmcnt(0)
	s_waitcnt lgkmcnt(0)
	s_barrier
; #define LWRITE(S, buf) do { bf16_t* sA_ = sbase + (buf) * BUF; bf16_t* sB_ = sA_ + 256 * PITCH; \
;     _Pragma("unroll") for (int i_ = 0; i_ < 4; ++i_) *(u32x4*)(sA_ + (sr + i_ * 64) * PITCH + scv * 8) = ra[S][i_]; \
;     _Pragma("unroll") for (int i_ = 0; i_ < 2; ++i_) *(u32x4*)(sB_ + (sr + i_ * 64) * PITCH + scv * 8) = rb[S][i_]; } while (0)
; template <class Epi>
; DI void gemm_tile(char* smem, const bf16_t* __restrict__ A0, int lda0, int ksplit, const bf16_t* __restrict__ A1, int lda1,
;                   const bf16_t* __restrict__ Bt, int K, int row0, int col0, const Epi& epi, int tid) {
;     ...
;     for (int kt = 0; kt < nk; kt += 2) {
;       LWRITE(1, 1);
;       __builtin_amdgcn_sched_barrier(0);
;       GLOAD(1, (kt + 3 < last ? kt + 3 : last));
;       __builtin_amdgcn_sched_barrier(0);
;       COMPUTE(0);
;       __syncthreads();
;       LWRITE(0, 0);
;       __builtin_amdgcn_sched_barrier(0);
;       GLOAD(0, (kt + 4 < last ? kt + 4 : last));
;       __builtin_amdgcn_sched_barrier(0);
;       COMPUTE(1);
;       __syncthreads();
;     }
	v_add_u32_e32 v232, s100, v230
	v_add_u32_e32 v233, s100, v231
	s_setprio 1
	v_mfma_f32_16x16x32_bf16 v[0:3], v[128:131], v[144:147], v[0:3]
	v_mfma_f32_16x16x32_bf16 v[4:7], v[132:135], v[144:147], v[4:7]
	v_mfma_f32_16x16x32_bf16 v[8:11], v[136:139], v[144:147], v[8:11]
	v_mfma_f32_16x16x32_bf16 v[12:15], v[140:143], v[144:147], v[12:15]
	ds_read_b128 v[176:179], v233 offset:0
	ds_read_b128 v[180:183], v233 offset:1024
	v_mfma_f32_16x16x32_bf16 v[16:19], v[128:131], v[148:151], v[16:19]
	v_mfma_f32_16x16x32_bf16 v[20:23], v[132:135], v[148:151], v[20:23]
	v_mfma_f32_16x16x32_bf16 v[24:27], v[136:139], v[148:151], v[24:27]
	v_mfma_f32_16x16x32_bf16 v[28:31], v[140:143], v[148:151], v[28:31]
	ds_read_b128 v[184:187], v233 offset:2048
	ds_read_b128 v[188:191], v233 offset:3072
	v_mfma_f32_16x16x32_bf16 v[32:35], v[128:131], v[152:155], v[32:35]
	v_mfma_f32_16x16x32_bf16 v[36:39], v[132:135], v[152:155], v[36:39]
	v_mfma_f32_16x16x32_bf16 v[40:43], v[136:139], v[152:155], v[40:43]
	v_mfma_f32_16x16x32_bf16 v[44:47], v[140:143], v[152:155], v[44:47]
	ds_read_b128 v[192:195], v232 offset:0
	ds_read_b128 v[196:199], v232 offset:1024
	v_mfma_f32_16x16x32_bf16 v[48:51], v[128:131], v[156:159], v[48:51]
	v_mfma_f32_16x16x32_bf16 v[52:55], v[132:135], v[156:159], v[52:55]
	v_mfma_f32_16x16x32_bf16 v[56:59], v[136:139], v[156:159], v[56:59]
	v_mfma_f32_16x16x32_bf16 v[60:63], v[140:143], v[156:159], v[60:63]
	ds_read_b128 v[200:203], v232 offset:2048
	ds_read_b128 v[204:207], v232 offset:3072
	v_mfma_f32_16x16x32_bf16 v[64:67], v[128:131], v[160:163], v[64:67]
	v_mfma_f32_16x16x32_bf16 v[68:71], v[132:135], v[160:163], v[68:71]
	v_mfma_f32_16x16x32_bf16 v[72:75], v[136:139], v[160:163], v[72:75]
	v_mfma_f32_16x16x32_bf16 v[76:79], v[140:143], v[160:163], v[76:79]
	ds_read_b128 v[208:211], v232 offset:4096
	v_mfma_f32_16x16x32_bf16 v[80:83], v[128:131], v[164:167], v[80:83]
	v_mfma_f32_16x16x32_bf16 v[84:87], v[132:135], v[164:167], v[84:87]
	v_mfma_f32_16x16x32_bf16 v[88:91], v[136:139], v[164:167], v[88:91]
	v_mfma_f32_16x16x32_bf16 v[92:95], v[140:143], v[164:167], v[92:95]
	ds_read_b128 v[212:215], v232 offset:5120
	s_setprio 0
	v_mfma_f32_16x16x32_bf16 v[96:99], v[128:131], v[168:171], v[96:99]
	v_mfma_f32_16x16x32_bf16 v[100:103], v[132:135], v[168:171], v[100:103]
	v_mfma_f32_16x16x32_bf16 v[104:107], v[136:139], v[168:171], v[104:107]
	v_mfma_f32_16x16x32_bf16 v[108:111], v[140:143], v[168:171], v[108:111]
	ds_read_b128 v[216:219], v232 offset:6144
	s_add_u32 s100, s100, 24576
	s_cmp_eq_u32 s100, 73728
	s_cselect_b32 s100, 0, s100
	v_mfma_f32_16x16x32_bf16 v[112:115], v[128:131], v[172:175], v[112:115]
	v_mfma_f32_16x16x32_bf16 v[116:119], v[132:135], v[172:175], v[116:119]
	v_mfma_f32_16x16x32_bf16 v[120:123], v[136:139], v[172:175], v[120:123]
	v_mfma_f32_16x16x32_bf16 v[124:127], v[140:143], v[172:175], v[124:127]
	ds_read_b128 v[220:223], v232 offset:7168
	s_waitcnt lgkmcnt(0)
	s_barrier
	s_setprio 1
	v_mfma_f32_16x16x32_bf16 v[0:3], v[176:179], v[192:195], v[0:3]
	v_mfma_f32_16x16x32_bf16 v[4:7], v[180:183], v[192:195], v[4:7]
	v_mfma_f32_16x16x32_bf16 v[8:11], v[184:187], v[192:195], v[8:11]
	v_mfma_f32_16x16x32_bf16 v[12:15], v[188:191], v[192:195], v[12:15]
	v_mfma_f32_16x16x32_bf16 v[16:19], v[176:179], v[196:199], v[16:19]
	v_mfma_f32_16x16x32_bf16 v[20:23], v[180:183], v[196:199], v[20:23]
	v_mfma_f32_16x16x32_bf16 v[24:27], v[184:187], v[196:199], v[24:27]
	v_mfma_f32_16x16x32_bf16 v[28:31], v[188:191], v[196:199], v[28:31]
	v_mfma_f32_16x16x32_bf16 v[32:35], v[176:179], v[200:203], v[32:35]
	v_mfma_f32_16x16x32_bf16 v[36:39], v[180:183], v[200:203], v[36:39]
	v_mfma_f32_16x16x32_bf16 v[40:43], v[184:187], v[200:203], v[40:43]
	v_mfma_f32_16x16x32_bf16 v[44:47], v[188:191], v[200:203], v[44:47]
	v_mfma_f32_16x16x32_bf16 v[48:51], v[176:179], v[204:207], v[48:51]
	v_mfma_f32_16x16x32_bf16 v[52:55], v[180:183], v[204:207], v[52:55]
	v_mfma_f32_16x16x32_bf16 v[56:59], v[184:187], v[204:207], v[56:59]
	v_mfma_f32_16x16x32_bf16 v[60:63], v[188:191], v[204:207], v[60:63]
	v_mfma_f32_16x16x32_bf16 v[64:67], v[176:179], v[208:211], v[64:67]
	v_mfma_f32_16x16x32_bf16 v[68:71], v[180:183], v[208:211], v[68:71]
	v_mfma_f32_16x16x32_bf16 v[72:75], v[184:187], v[208:211], v[72:75]
	v_mfma_f32_16x16x32_bf16 v[76:79], v[188:191], v[208:211], v[76:79]
	v_mfma_f32_16x16x32_bf16 v[80:83], v[176:179], v[212:215], v[80:83]
	v_mfma_f32_16x16x32_bf16 v[84:87], v[180:183], v[212:215], v[84:87]
	v_mfma_f32_16x16x32_bf16 v[88:91], v[184:187], v[212:215], v[88:91]
	v_mfma_f32_16x16x32_bf16 v[92:95], v[188:191], v[212:215], v[92:95]
	s_setprio 0
	v_mfma_f32_16x16x32_bf16 v[96:99], v[176:179], v[216:219], v[96:99]
	v_mfma_f32_16x16x32_bf16 v[100:103], v[180:183], v[216:219], v[100:103]
	v_mfma_f32_16x16x32_bf16 v[104:107], v[184:187], v[216:219], v[104:107]
	v_mfma_f32_16x16x32_bf16 v[108:111], v[188:191], v[216:219], v[108:111]
	v_mfma_f32_16x16x32_bf16 v[112:115], v[176:179], v[220:223], v[112:115]
	v_mfma_f32_16x16x32_bf16 v[116:119], v[180:183], v[220:223], v[116:119]
	v_mfma_f32_16x16x32_bf16 v[120:123], v[184:187], v[220:223], v[120:123]
	v_mfma_f32_16x16x32_bf16 v[124:127], v[188:191], v[220:223], v[124:127]
	s_branch .Lg6_epi

; #define LWRITE(S, buf) do { bf16_t* sA_ = sbase + (buf) * BUF; bf16_t* sB_ = sA_ + 256 * PITCH; \
;     _Pragma("unroll") for (int i_ = 0; i_ < 4; ++i_) *(u32x4*)(sA_ + (sr + i_ * 64) * PITCH + scv * 8) = ra[S][i_]; \
;     _Pragma("unroll") for (int i_ = 0; i_ < 2; ++i_) *(u32x4*)(sB_ + (sr + i_ * 64) * PITCH + scv * 8) = rb[S][i_]; } while (0)
; template <class Epi>
; DI void gemm_tile(char* smem, const bf16_t* __restrict__ A0, int lda0, int ksplit, const bf16_t* __restrict__ A1, int lda1,
;                   const bf16_t* __restrict__ Bt, int K, int row0, int col0, const Epi& epi, int tid) {
;     ...
;     for (int kt = 0; kt < nk; kt += 2) {
;       LWRITE(1, 1);
;       __builtin_amdgcn_sched_barrier(0);
;       GLOAD(1, (kt + 3 < last ? kt + 3 : last));
;       __builtin_amdgcn_sched_barrier(0);
;       COMPUTE(0);
;       __syncthreads();
;       LWRITE(0, 0);
;       __builtin_amdgcn_sched_barrier(0);
;       GLOAD(0, (kt + 4 < last ? kt + 4 : last));
;       __builtin_amdgcn_sched_barrier(0);
;       COMPUTE(1);
;       __syncthreads();
;     }
.Lg9_kloop:
	s_waitcnt vmcnt(6)
	s_waitcnt lgkmcnt(0)
	s_barrier
	v_add_u32_e32 v232, s98, v230
	v_add_u32_e32 v233, s98, v231
	s_add_u32 s9, s17, s101
	s_setprio 1
	v_mfma_f32_16x16x32_bf16 v[0:3], v[128:131], v[144:147], v[0:3]
	v_mfma_f32_16x16x32_bf16 v[4:7], v[132:135], v[144:147], v[4:7]
	v_mfma_f32_16x16x32_bf16 v[8:11], v[136:139], v[144:147], v[8:11]
	v_mfma_f32_16x16x32_bf16 v[12:15], v[140:143], v[144:147], v[12:15]
	ds_read_b128 v[176:179], v233 offset:0
	ds_read_b128 v[180:183], v233 offset:1024
	s_add_u32 m0, s9, 0
	s_nop 0
	global_load_lds_dwordx4 v224, s[0:1]
	v_mfma_f32_16x16x32_bf16 v[16:19], v[128:131], v[148:151], v[16:19]
	v_mfma_f32_16x16x32_bf16 v[20:23], v[132:135], v[148:151], v[20:23]
	v_mfma_f32_16x16x32_bf16 v[24:27], v[136:139], v[148:151], v[24:27]
	v_mfma_f32_16x16x32_bf16 v[28:31], v[140:143], v[148:151], v[28:31]
	ds_read_b128 v[184:187], v233 offset:2048
	ds_read_b128 v[188:191], v233 offset:3072
	s_add_u32 m0, s9, 4096
	s_nop 0
	global_load_lds_dwordx4 v225, s[0:1]
	v_mfma_f32_16x16x32_bf16 v[32:35], v[128:131], v[152:155], v[32:35]
	v_mfma_f32_16x16x32_bf16 v[36:39], v[132:135], v[152:155], v[36:39]
	v_mfma_f32_16x16x32_bf16 v[40:43], v[136:139], v[152:155], v[40:43]
	v_mfma_f32_16x16x32_bf16 v[44:47], v[140:143], v[152:155], v[44:47]
	ds_read_b128 v[192:195], v232 offset:0
	ds_read_b128 v[196:199], v232 offset:1024
	s_add_u32 m0, s9, 8192
	s_nop 0
	global_load_lds_dwordx4 v226, s[0:1]
	v_mfma_f32_16x16x32_bf16 v[48:51], v[128:131], v[156:159], v[48:51]
	v_mfma_f32_16x16x32_bf16 v[52:55], v[132:135], v[156:159], v[52:55]
	v_mfma_f32_16x16x32_bf16 v[56:59], v[136:139], v[156:159], v[56:59]
	v_mfma_f32_16x16x32_bf16 v[60:63], v[140:143], v[156:159], v[60:63]
	ds_read_b128 v[200:203], v232 offset:2048
	ds_read_b128 v[204:207], v232 offset:3072
	s_add_u32 m0, s9, 12288
	s_nop 0
	global_load_lds_dwordx4 v227, s[0:1]
	v_mfma_f32_16x16x32_bf16 v[64:67], v[128:131], v[160:163], v[64:67]
	v_mfma_f32_16x16x32_bf16 v[68:71], v[132:135], v[160:163], v[68:71]
	v_mfma_f32_16x16x32_bf16 v[72:75], v[136:139], v[160:163], v[72:75]
	v_mfma_f32_16x16x32_bf16 v[76:79], v[140:143], v[160:163], v[76:79]
	ds_read_b128 v[208:211], v232 offset:4096
	s_add_u32 m0, s9, 16384
	s_nop 0
	global_load_lds_dwordx4 v228, s[2:3]
	v_mfma_f32_16x16x32_bf16 v[80:83], v[128:131], v[164:167], v[80:83]
	v_mfma_f32_16x16x32_bf16 v[84:87], v[132:135], v[164:167], v[84:87]
	v_mfma_f32_16x16x32_bf16 v[88:91], v[136:139], v[164:167], v[88:91]
	v_mfma_f32_16x16x32_bf16 v[92:95], v[140:143], v[164:167], v[92:95]
	ds_read_b128 v[212:215], v232 offset:5120
	s_add_u32 m0, s9, 20480
	s_nop 0
	global_load_lds_dwordx4 v229, s[2:3]
	s_setprio 0
	v_mfma_f32_16x16x32_bf16 v[96:99], v[128:131], v[168:171], v[96:99]
	v_mfma_f32_16x16x32_bf16 v[100:103], v[132:135], v[168:171], v[100:103]
	v_mfma_f32_16x16x32_bf16 v[104:107], v[136:139], v[168:171], v[104:107]
	v_mfma_f32_16x16x32_bf16 v[108:111], v[140:143], v[168:171], v[108:111]
	ds_read_b128 v[216:219], v232 offset:6144
	s_add_u32 s0, s0, 64
	s_addc_u32 s1, s1, 0
	s_add_u32 s2, s2, 64
	s_addc_u32 s3, s3, 0
	s_add_u32 s100, s100, 1
	s_add_u32 s17, s17, 24576
	s_cmp_eq_u32 s17, 73728
	s_cselect_b32 s17, 0, s17
	s_add_u32 s98, s98, 24576
	s_cmp_eq_u32 s98, 73728
	s_cselect_b32 s98, 0, s98
	v_mfma_f32_16x16x32_bf16 v[112:115], v[128:131], v[172:175], v[112:115]
	v_mfma_f32_16x16x32_bf16 v[116:119], v[132:135], v[172:175], v[116:119]
	v_mfma_f32_16x16x32_bf16 v[120:123], v[136:139], v[172:175], v[120:123]
	v_mfma_f32_16x16x32_bf16 v[124:127], v[140:143], v[172:175], v[124:127]
	ds_read_b128 v[220:223], v232 offset:7168
	s_waitcnt vmcnt(6)
	s_waitcnt lgkmcnt(0)
	s_barrier
	v_add_u32_e32 v232, s98, v230
	v_add_u32_e32 v233, s98, v231
	s_add_u32 s9, s17, s101
	s_setprio 1
	v_mfma_f32_16x16x32_bf16 v[0:3], v[176:179], v[192:195], v[0:3]
	v_mfma_f32_16x16x32_bf16 v[4:7], v[180:183], v[192:195], v[4:7]
	v_mfma_f32_16x16x32_bf16 v[8:11], v[184:187], v[192:195], v[8:11]
	v_mfma_f32_16x16x32_bf16 v[12:15], v[188:191], v[192:195], v[12:15]
	ds_read_b128 v[128:131], v233 offset:0
	ds_read_b128 v[132:135], v233 offset:1024
	s_add_u32 m0, s9, 0
	s_nop 0
	global_load_lds_dwordx4 v224, s[0:1]
	v_mfma_f32_16x16x32_bf16 v[16:19], v[176:179], v[196:199], v[16:19]
	v_mfma_f32_16x16x32_bf16 v[20:23], v[180:183], v[196:199], v[20:23]
	v_mfma_f32_16x16x32_bf16 v[24:27], v[184:187], v[196:199], v[24:27]
	v_mfma_f32_16x16x32_bf16 v[28:31], v[188:191], v[196:199], v[28:31]
	ds_read_b128 v[136:139], v233 offset:2048
	ds_read_b128 v[140:143], v233 offset:3072
	s_add_u32 m0, s9, 4096
	s_nop 0
	global_load_lds_dwordx4 v225, s[0:1]
	v_mfma_f32_16x16x32_bf16 v[32:35], v[176:179], v[200:203], v[32:35]
	v_mfma_f32_16x16x32_bf16 v[36:39], v[180:183], v[200:203], v[36:39]
	v_mfma_f32_16x16x32_bf16 v[40:43], v[184:187], v[200:203], v[40:43]
	v_mfma_f32_16x16x32_bf16 v[44:47], v[188:191], v[200:203], v[44:47]
	ds_read_b128 v[144:147], v232 offset:0
	ds_read_b128 v[148:151], v232 offset:1024
	s_add_u32 m0, s9, 8192
	s_nop 0
	global_load_lds_dwordx4 v226, s[0:1]
	v_mfma_f32_16x16x32_bf16 v[48:51], v[176:179], v[204:207], v[48:51]
	v_mfma_f32_16x16x32_bf16 v[52:55], v[180:183], v[204:207], v[52:55]
	v_mfma_f32_16x16x32_bf16 v[56:59], v[184:187], v[204:207], v[56:59]
	v_mfma_f32_16x16x32_bf16 v[60:63], v[188:191], v[204:207], v[60:63]
	ds_read_b128 v[152:155], v232 offset:2048
	ds_read_b128 v[156:159], v232 offset:3072
	s_add_u32 m0, s9, 12288
	s_nop 0
	global_load_lds_dwordx4 v227, s[0:1]
	v_mfma_f32_16x16x32_bf16 v[64:67], v[176:179], v[208:211], v[64:67]
	v_mfma_f32_16x16x32_bf16 v[68:71], v[180:183], v[208:211], v[68:71]
; #define LWRITE(S, buf) do { bf16_t* sA_ = sbase + (buf) * BUF; bf16_t* sB_ = sA_ + 256 * PITCH; \
;     _Pragma("unroll") for (int i_ = 0; i_ < 4; ++i_) *(u32x4*)(sA_ + (sr + i_ * 64) * PITCH + scv * 8) = ra[S][i_]; \
;     _Pragma("unroll") for (int i_ = 0; i_ < 2; ++i_) *(u32x4*)(sB_ + (sr + i_ * 64) * PITCH + scv * 8) = rb[S][i_]; } while (0)
; template <class Epi>
; DI void gemm_tile(char* smem, const bf16_t* __restrict__ A0, int lda0, int ksplit, const bf16_t* __restrict__ A1, int lda1,
;                   const bf16_t* __restrict__ Bt, int K, int row0, int col0, const Epi& epi, int tid) {
;     ...
;     for (int kt = 0; kt < nk; kt += 2) {
;       LWRITE(1, 1);
;       __builtin_amdgcn_sched_barrier(0);
;       GLOAD(1, (kt + 3 < last ? kt + 3 : last));
;       __builtin_amdgcn_sched_barrier(0);
;       COMPUTE(0);
;       __syncthreads();
;       LWRITE(0, 0);
;       __builtin_amdgcn_sched_barrier(0);
;       GLOAD(0, (kt + 4 < last ? kt + 4 : last));
;       __builtin_amdgcn_sched_barrier(0);
;       COMPUTE(1);
;       __syncthreads();
;     }
	v_mfma_f32_16x16x32_bf16 v[72:75], v[184:187], v[208:211], v[72:75]
	v_mfma_f32_16x16x32_bf16 v[76:79], v[188:191], v[208:211], v[76:79]
	ds_read_b128 v[160:163], v232 offset:4096
	s_add_u32 m0, s9, 16384
	s_nop 0
	global_load_lds_dwordx4 v228, s[2:3]
	v_mfma_f32_16x16x32_bf16 v[80:83], v[176:179], v[212:215], v[80:83]
	v_mfma_f32_16x16x32_bf16 v[84:87], v[180:183], v[212:215], v[84:87]
	v_mfma_f32_16x16x32_bf16 v[88:91], v[184:187], v[212:215], v[88:91]
	v_mfma_f32_16x16x32_bf16 v[92:95], v[188:191], v[212:215], v[92:95]
	ds_read_b128 v[164:167], v232 offset:5120
	s_add_u32 m0, s9, 20480
	s_nop 0
	global_load_lds_dwordx4 v229, s[2:3]
	s_setprio 0
	v_mfma_f32_16x16x32_bf16 v[96:99], v[176:179], v[216:219], v[96:99]
	v_mfma_f32_16x16x32_bf16 v[100:103], v[180:183], v[216:219], v[100:103]
	v_mfma_f32_16x16x32_bf16 v[104:107], v[184:187], v[216:219], v[104:107]
	v_mfma_f32_16x16x32_bf16 v[108:111], v[188:191], v[216:219], v[108:111]
	ds_read_b128 v[168:171], v232 offset:6144
	s_add_u32 s0, s0, 64
	s_addc_u32 s1, s1, 0
	s_add_u32 s2, s2, 64
	s_addc_u32 s3, s3, 0
	s_add_u32 s100, s100, 1
	s_add_u32 s17, s17, 24576
	s_cmp_eq_u32 s17, 73728
	s_cselect_b32 s17, 0, s17
	s_add_u32 s98, s98, 24576
	s_cmp_eq_u32 s98, 73728
	s_cselect_b32 s98, 0, s98
	v_mfma_f32_16x16x32_bf16 v[112:115], v[176:179], v[220:223], v[112:115]
	v_mfma_f32_16x16x32_bf16 v[116:119], v[180:183], v[220:223], v[116:119]
	v_mfma_f32_16x16x32_bf16 v[120:123], v[184:187], v[220:223], v[120:123]
	v_mfma_f32_16x16x32_bf16 v[124:127], v[188:191], v[220:223], v[124:127]
	ds_read_b128 v[172:175], v232 offset:7168
	s_add_u32 s99, s99, 2
	s_cmp_lt_u32 s99, 124
	s_cbranch_scc1 .Lg9_kloop
	s_waitcnt vmcnt(6)
	s_waitcnt lgkmcnt(0)
	s_barrier
	v_add_u32_e32 v232, s98, v230
	v_add_u32_e32 v233, s98, v231
	s_add_u32 s9, s17, s101
	s_setprio 1
	v_mfma_f32_16x16x32_bf16 v[0:3], v[128:131], v[144:147], v[0:3]
	v_mfma_f32_16x16x32_bf16 v[4:7], v[132:135], v[144:147], v[4:7]
	v_mfma_f32_16x16x32_bf16 v[8:11], v[136:139], v[144:147], v[8:11]
	v_mfma_f32_16x16x32_bf16 v[12:15], v[140:143], v[144:147], v[12:15]
	ds_read_b128 v[176:179], v233 offset:0
	ds_read_b128 v[180:183], v233 offset:1024
	s_add_u32 m0, s9, 0
	s_nop 0
	global_load_lds_dwordx4 v224, s[0:1]
	v_mfma_f32_16x16x32_bf16 v[16:19], v[128:131], v[148:151], v[16:19]
	v_mfma_f32_16x16x32_bf16 v[20:23], v[132:135], v[148:151], v[20:23]
	v_mfma_f32_16x16x32_bf16 v[24:27], v[136:139], v[148:151], v[24:27]
	v_mfma_f32_16x16x32_bf16 v[28:31], v[140:143], v[148:151], v[28:31]
	ds_read_b128 v[184:187], v233 offset:2048
	ds_read_b128 v[188:191], v233 offset:3072
	s_add_u32 m0, s9, 4096
	s_nop 0
	global_load_lds_dwordx4 v225, s[0:1]
	v_mfma_f32_16x16x32_bf16 v[32:35], v[128:131], v[152:155], v[32:35]
	v_mfma_f32_16x16x32_bf16 v[36:39], v[132:135], v[152:155], v[36:39]
	v_mfma_f32_16x16x32_bf16 v[40:43], v[136:139], v[152:155], v[40:43]
	v_mfma_f32_16x16x32_bf16 v[44:47], v[140:143], v[152:155], v[44:47]
	ds_read_b128 v[192:195], v232 offset:0
	ds_read_b128 v[196:199], v232 offset:1024
	s_add_u32 m0, s9, 8192
	s_nop 0
	global_load_lds_dwordx4 v226, s[0:1]
	v_mfma_f32_16x16x32_bf16 v[48:51], v[128:131], v[156:159], v[48:51]
	v_mfma_f32_16x16x32_bf16 v[52:55], v[132:135], v[156:159], v[52:55]
	v_mfma_f32_16x16x32_bf16 v[56:59], v[136:139], v[156:159], v[56:59]
	v_mfma_f32_16x16x32_bf16 v[60:63], v[140:143], v[156:159], v[60:63]
	ds_read_b128 v[200:203], v232 offset:2048
	ds_read_b128 v[204:207], v232 offset:3072
	s_add_u32 m0, s9, 12288
	s_nop 0
	global_load_lds_dwordx4 v227, s[0:1]
	v_mfma_f32_16x16x32_bf16 v[64:67], v[128:131], v[160:163], v[64:67]
	v_mfma_f32_16x16x32_bf16 v[68:71], v[132:135], v[160:163], v[68:71]
	v_mfma_f32_16x16x32_bf16 v[72:75], v[136:139], v[160:163], v[72:75]
	v_mfma_f32_16x16x32_bf16 v[76:79], v[140:143], v[160:163], v[76:79]
	ds_read_b128 v[208:211], v232 offset:4096
	s_add_u32 m0, s9, 16384
	s_nop 0
	global_load_lds_dwordx4 v228, s[2:3]
	v_mfma_f32_16x16x32_bf16 v[80:83], v[128:131], v[164:167], v[80:83]
	v_mfma_f32_16x16x32_bf16 v[84:87], v[132:135], v[164:167], v[84:87]
	v_mfma_f32_16x16x32_bf16 v[88:91], v[136:139], v[164:167], v[88:91]
	v_mfma_f32_16x16x32_bf16 v[92:95], v[140:143], v[164:167], v[92:95]
	ds_read_b128 v[212:215], v232 offset:5120
	s_add_u32 m0, s9, 20480
	s_nop 0
	global_load_lds_dwordx4 v229, s[2:3]
	s_setprio 0
	v_mfma_f32_16x16x32_bf16 v[96:99], v[128:131], v[168:171], v[96:99]
	v_mfma_f32_16x16x32_bf16 v[100:103], v[132:135], v[168:171], v[100:103]
	v_mfma_f32_16x16x32_bf16 v[104:107], v[136:139], v[168:171], v[104:107]
	v_mfma_f32_16x16x32_bf16 v[108:111], v[140:143], v[168:171], v[108:111]
	ds_read_b128 v[216:219], v232 offset:6144
	s_add_u32 s0, s0, 64
	s_addc_u32 s1, s1, 0
	s_add_u32 s2, s2, 64
	s_addc_u32 s3, s3, 0
	s_add_u32 s100, s100, 1
	s_add_u32 s17, s17, 24576
	s_cmp_eq_u32 s17, 73728
	s_cselect_b32 s17, 0, s17
	s_add_u32 s98, s98, 24576
	s_cmp_eq_u32 s98, 73728
	s_cselect_b32 s98, 0, s98
	v_mfma_f32_16x16x32_bf16 v[112:115], v[128:131], v[172:175], v[112:115]
	v_mfma_f32_16x16x32_bf16 v[116:119], v[132:135], v[172:175], v[116:119]
	v_mfma_f32_16x16x32_bf16 v[120:123], v[136:139], v[172:175], v[120:123]
	v_mfma_f32_16x16x32_bf16 v[124:127], v[140:143], v[172:175], v[124:127]
	ds_read_b128 v[220:223], v232 offset:7168
	s_waitcnt vmcnt(6)
	s_waitcnt lgkmcnt(0)
	s_barrier
; #define LWRITE(S, buf) do { bf16_t* sA_ = sbase + (buf) * BUF; bf16_t* sB_ = sA_ + 256 * PITCH; \
;     _Pragma("unroll") for (int i_ = 0; i_ < 4; ++i_) *(u32x4*)(sA_ + (sr + i_ * 64) * PITCH + scv * 8) = ra[S][i_]; \
;     _Pragma("unroll") for (int i_ = 0; i_ < 2; ++i_) *(u32x4*)(sB_ + (sr + i_ * 64) * PITCH + scv * 8) = rb[S][i_]; } while (0)
; template <class Epi>
; DI void gemm_tile(char* smem, const bf16_t* __restrict__ A0, int lda0, int ksplit, const bf16_t* __restrict__ A1, int lda1,
;                   const bf16_t* __restrict__ Bt, int K, int row0, int col0, const Epi& epi, int tid) {
;     ...
;     for (int kt = 0; kt < nk; kt += 2) {
;       LWRITE(1, 1);
;       __builtin_amdgcn_sched_barrier(0);
;       GLOAD(1, (kt + 3 < last ? kt + 3 : last));
;       __builtin_amdgcn_sched_barrier(0);
;       COMPUTE(0);
;       __syncthreads();
;       LWRITE(0, 0);
;       __builtin_amdgcn_sched_barrier(0);
;       GLOAD(0, (kt + 4 < last ? kt + 4 : last));
;       __builtin_amdgcn_sched_barrier(0);
;       COMPUTE(1);
;       __syncthreads();
;     }
	v_add_u32_e32 v232, s98, v230
	v_add_u32_e32 v233, s98, v231
	s_setprio 1
	v_mfma_f32_16x16x32_bf16 v[0:3], v[176:179], v[192:195], v[0:3]
	v_mfma_f32_16x16x32_bf16 v[4:7], v[180:183], v[192:195], v[4:7]
	v_mfma_f32_16x16x32_bf16 v[8:11], v[184:187], v[192:195], v[8:11]
	v_mfma_f32_16x16x32_bf16 v[12:15], v[188:191], v[192:195], v[12:15]
	ds_read_b128 v[128:131], v233 offset:0
	ds_read_b128 v[132:135], v233 offset:1024
	v_mfma_f32_16x16x32_bf16 v[16:19], v[176:179], v[196:199], v[16:19]
	v_mfma_f32_16x16x32_bf16 v[20:23], v[180:183], v[196:199], v[20:23]
	v_mfma_f32_16x16x32_bf16 v[24:27], v[184:187], v[196:199], v[24:27]
	v_mfma_f32_16x16x32_bf16 v[28:31], v[188:191], v[196:199], v[28:31]
	ds_read_b128 v[136:139], v233 offset:2048
	ds_read_b128 v[140:143], v233 offset:3072
	v_mfma_f32_16x16x32_bf16 v[32:35], v[176:179], v[200:203], v[32:35]
	v_mfma_f32_16x16x32_bf16 v[36:39], v[180:183], v[200:203], v[36:39]
	v_mfma_f32_16x16x32_bf16 v[40:43], v[184:187], v[200:203], v[40:43]
	v_mfma_f32_16x16x32_bf16 v[44:47], v[188:191], v[200:203], v[44:47]
	ds_read_b128 v[144:147], v232 offset:0
	ds_read_b128 v[148:151], v232 offset:1024
	v_mfma_f32_16x16x32_bf16 v[48:51], v[176:179], v[204:207], v[48:51]
	v_mfma_f32_16x16x32_bf16 v[52:55], v[180:183], v[204:207], v[52:55]
	v_mfma_f32_16x16x32_bf16 v[56:59], v[184:187], v[204:207], v[56:59]
	v_mfma_f32_16x16x32_bf16 v[60:63], v[188:191], v[204:207], v[60:63]
	ds_read_b128 v[152:155], v232 offset:2048
	ds_read_b128 v[156:159], v232 offset:3072
	v_mfma_f32_16x16x32_bf16 v[64:67], v[176:179], v[208:211], v[64:67]
	v_mfma_f32_16x16x32_bf16 v[68:71], v[180:183], v[208:211], v[68:71]
	v_mfma_f32_16x16x32_bf16 v[72:75], v[184:187], v[208:211], v[72:75]
	v_mfma_f32_16x16x32_bf16 v[76:79], v[188:191], v[208:211], v[76:79]
	ds_read_b128 v[160:163], v232 offset:4096
	v_mfma_f32_16x16x32_bf16 v[80:83], v[176:179], v[212:215], v[80:83]
	v_mfma_f32_16x16x32_bf16 v[84:87], v[180:183], v[212:215], v[84:87]
	v_mfma_f32_16x16x32_bf16 v[88:91], v[184:187], v[212:215], v[88:91]
	v_mfma_f32_16x16x32_bf16 v[92:95], v[188:191], v[212:215], v[92:95]
	ds_read_b128 v[164:167], v232 offset:5120
	s_setprio 0
	v_mfma_f32_16x16x32_bf16 v[96:99], v[176:179], v[216:219], v[96:99]
	v_mfma_f32_16x16x32_bf16 v[100:103], v[180:183], v[216:219], v[100:103]
	v_mfma_f32_16x16x32_bf16 v[104:107], v[184:187], v[216:219], v[104:107]
	v_mfma_f32_16x16x32_bf16 v[108:111], v[188:191], v[216:219], v[108:111]
	ds_read_b128 v[168:171], v232 offset:6144
	s_add_u32 s98, s98, 24576
	s_cmp_eq_u32 s98, 73728
	s_cselect_b32 s98, 0, s98
	v_mfma_f32_16x16x32_bf16 v[112:115], v[176:179], v[220:223], v[112:115]
	v_mfma_f32_16x16x32_bf16 v[116:119], v[180:183], v[220:223], v[116:119]
	v_mfma_f32_16x16x32_bf16 v[120:123], v[184:187], v[220:223], v[120:123]
	v_mfma_f32_16x16x32_bf16 v[124:127], v[188:191], v[220:223], v[124:127]
	ds_read_b128 v[172:175], v232 offset:7168
	s_waitcnt vmcnt(0)
	s_waitcnt lgkmcnt(0)
	s_barrier
; #define LWRITE(S, buf) do { bf16_t* sA_ = sbase + (buf) * BUF; bf16_t* sB_ = sA_ + 256 * PITCH; \
;     _Pragma("unroll") for (int i_ = 0; i_ < 4; ++i_) *(u32x4*)(sA_ + (sr + i_ * 64) * PITCH + scv * 8) = ra[S][i_]; \
;     _Pragma("unroll") for (int i_ = 0; i_ < 2; ++i_) *(u32x4*)(sB_ + (sr + i_ * 64) * PITCH + scv * 8) = rb[S][i_]; } while (0)
; template <class Epi>
; DI void gemm_tile(char* smem, const bf16_t* __restrict__ A0, int lda0, int ksplit, const bf16_t* __restrict__ A1, int lda1,
;                   const bf16_t* __restrict__ Bt, int K, int row0, int col0, const Epi& epi, int tid) {
;     ...
;     for (int kt = 0; kt < nk; kt += 2) {
;       LWRITE(1, 1);
;       __builtin_amdgcn_sched_barrier(0);
;       GLOAD(1, (kt + 3 < last ? kt + 3 : last));
;       __builtin_amdgcn_sched_barrier(0);
;       COMPUTE(0);
;       __syncthreads();
;       LWRITE(0, 0);
;       __builtin_amdgcn_sched_barrier(0);
;       GLOAD(0, (kt + 4 < last ? kt + 4 : last));
;       __builtin_amdgcn_sched_barrier(0);
;       COMPUTE(1);
;       __syncthreads();
;     }
	v_add_u32_e32 v232, s98, v230
	v_add_u32_e32 v233, s98, v231
	s_setprio 1
	v_mfma_f32_16x16x32_bf16 v[0:3], v[128:131], v[144:147], v[0:3]
	v_mfma_f32_16x16x32_bf16 v[4:7], v[132:135], v[144:147], v[4:7]
	v_mfma_f32_16x16x32_bf16 v[8:11], v[136:139], v[144:147], v[8:11]
	v_mfma_f32_16x16x32_bf16 v[12:15], v[140:143], v[144:147], v[12:15]
	ds_read_b128 v[176:179], v233 offset:0
	ds_read_b128 v[180:183], v233 offset:1024
	v_mfma_f32_16x16x32_bf16 v[16:19], v[128:131], v[148:151], v[16:19]
	v_mfma_f32_16x16x32_bf16 v[20:23], v[132:135], v[148:151], v[20:23]
	v_mfma_f32_16x16x32_bf16 v[24:27], v[136:139], v[148:151], v[24:27]
	v_mfma_f32_16x16x32_bf16 v[28:31], v[140:143], v[148:151], v[28:31]
	ds_read_b128 v[184:187], v233 offset:2048
	ds_read_b128 v[188:191], v233 offset:3072
	v_mfma_f32_16x16x32_bf16 v[32:35], v[128:131], v[152:155], v[32:35]
	v_mfma_f32_16x16x32_bf16 v[36:39], v[132:135], v[152:155], v[36:39]
	v_mfma_f32_16x16x32_bf16 v[40:43], v[136:139], v[152:155], v[40:43]
	v_mfma_f32_16x16x32_bf16 v[44:47], v[140:143], v[152:155], v[44:47]
	ds_read_b128 v[192:195], v232 offset:0
	ds_read_b128 v[196:199], v232 offset:1024
	v_mfma_f32_16x16x32_bf16 v[48:51], v[128:131], v[156:159], v[48:51]
	v_mfma_f32_16x16x32_bf16 v[52:55], v[132:135], v[156:159], v[52:55]
	v_mfma_f32_16x16x32_bf16 v[56:59], v[136:139], v[156:159], v[56:59]
	v_mfma_f32_16x16x32_bf16 v[60:63], v[140:143], v[156:159], v[60:63]
	ds_read_b128 v[200:203], v232 offset:2048
	ds_read_b128 v[204:207], v232 offset:3072
	v_mfma_f32_16x16x32_bf16 v[64:67], v[128:131], v[160:163], v[64:67]
	v_mfma_f32_16x16x32_bf16 v[68:71], v[132:135], v[160:163], v[68:71]
	v_mfma_f32_16x16x32_bf16 v[72:75], v[136:139], v[160:163], v[72:75]
	v_mfma_f32_16x16x32_bf16 v[76:79], v[140:143], v[160:163], v[76:79]
	ds_read_b128 v[208:211], v232 offset:4096
	v_mfma_f32_16x16x32_bf16 v[80:83], v[128:131], v[164:167], v[80:83]
	v_mfma_f32_16x16x32_bf16 v[84:87], v[132:135], v[164:167], v[84:87]
	v_mfma_f32_16x16x32_bf16 v[88:91], v[136:139], v[164:167], v[88:91]
	v_mfma_f32_16x16x32_bf16 v[92:95], v[140:143], v[164:167], v[92:95]
	ds_read_b128 v[212:215], v232 offset:5120
	s_setprio 0
	v_mfma_f32_16x16x32_bf16 v[96:99], v[128:131], v[168:171], v[96:99]
	v_mfma_f32_16x16x32_bf16 v[100:103], v[132:135], v[168:171], v[100:103]
	v_mfma_f32_16x16x32_bf16 v[104:107], v[136:139], v[168:171], v[104:107]
	v_mfma_f32_16x16x32_bf16 v[108:111], v[140:143], v[168:171], v[108:111]
	ds_read_b128 v[216:219], v232 offset:6144
	s_add_u32 s98, s98, 24576
	s_cmp_eq_u32 s98, 73728
	s_cselect_b32 s98, 0, s98
	v_mfma_f32_16x16x32_bf16 v[112:115], v[128:131], v[172:175], v[112:115]
	v_mfma_f32_16x16x32_bf16 v[116:119], v[132:135], v[172:175], v[116:119]
	v_mfma_f32_16x16x32_bf16 v[120:123], v[136:139], v[172:175], v[120:123]
	v_mfma_f32_16x16x32_bf16 v[124:127], v[140:143], v[172:175], v[124:127]
	ds_read_b128 v[220:223], v232 offset:7168
	s_waitcnt lgkmcnt(0)
	s_barrier
	s_setprio 1
	v_mfma_f32_16x16x32_bf16 v[0:3], v[176:179], v[192:195], v[0:3]
	v_mfma_f32_16x16x32_bf16 v[4:7], v[180:183], v[192:195], v[4:7]
	v_mfma_f32_16x16x32_bf16 v[8:11], v[184:187], v[192:195], v[8:11]
	v_mfma_f32_16x16x32_bf16 v[12:15], v[188:191], v[192:195], v[12:15]
	v_mfma_f32_16x16x32_bf16 v[16:19], v[176:179], v[196:199], v[16:19]
	v_mfma_f32_16x16x32_bf16 v[20:23], v[180:183], v[196:199], v[20:23]
	v_mfma_f32_16x16x32_bf16 v[24:27], v[184:187], v[196:199], v[24:27]
	v_mfma_f32_16x16x32_bf16 v[28:31], v[188:191], v[196:199], v[28:31]
	v_mfma_f32_16x16x32_bf16 v[32:35], v[176:179], v[200:203], v[32:35]
	v_mfma_f32_16x16x32_bf16 v[36:39], v[180:183], v[200:203], v[36:39]
	v_mfma_f32_16x16x32_bf16 v[40:43], v[184:187], v[200:203], v[40:43]
	v_mfma_f32_16x16x32_bf16 v[44:47], v[188:191], v[200:203], v[44:47]
	v_mfma_f32_16x16x32_bf16 v[48:51], v[176:179], v[204:207], v[48:51]
	v_mfma_f32_16x16x32_bf16 v[52:55], v[180:183], v[204:207], v[52:55]
	v_mfma_f32_16x16x32_bf16 v[56:59], v[184:187], v[204:207], v[56:59]
	v_mfma_f32_16x16x32_bf16 v[60:63], v[188:191], v[204:207], v[60:63]
	v_mfma_f32_16x16x32_bf16 v[64:67], v[176:179], v[208:211], v[64:67]
	v_mfma_f32_16x16x32_bf16 v[68:71], v[180:183], v[208:211], v[68:71]
	v_mfma_f32_16x16x32_bf16 v[72:75], v[184:187], v[208:211], v[72:75]
	v_mfma_f32_16x16x32_bf16 v[76:79], v[188:191], v[208:211], v[76:79]
	v_mfma_f32_16x16x32_bf16 v[80:83], v[176:179], v[212:215], v[80:83]
	v_mfma_f32_16x16x32_bf16 v[84:87], v[180:183], v[212:215], v[84:87]
	v_mfma_f32_16x16x32_bf16 v[88:91], v[184:187], v[212:215], v[88:91]
	v_mfma_f32_16x16x32_bf16 v[92:95], v[188:191], v[212:215], v[92:95]
	s_setprio 0
	v_mfma_f32_16x16x32_bf16 v[96:99], v[176:179], v[216:219], v[96:99]
	v_mfma_f32_16x16x32_bf16 v[100:103], v[180:183], v[216:219], v[100:103]
	v_mfma_f32_16x16x32_bf16 v[104:107], v[184:187], v[216:219], v[104:107]
	v_mfma_f32_16x16x32_bf16 v[108:111], v[188:191], v[216:219], v[108:111]
	v_mfma_f32_16x16x32_bf16 v[112:115], v[176:179], v[220:223], v[112:115]
	v_mfma_f32_16x16x32_bf16 v[116:119], v[180:183], v[220:223], v[116:119]
	v_mfma_f32_16x16x32_bf16 v[120:123], v[184:187], v[220:223], v[120:123]
	v_mfma_f32_16x16x32_bf16 v[124:127], v[188:191], v[220:223], v[124:127]
	s_branch .Lg9_epi

; #define LWRITE(S, buf) do { bf16_t* sA_ = sbase + (buf) * BUF; bf16_t* sB_ = sA_ + 256 * PITCH; \
;     _Pragma("unroll") for (int i_ = 0; i_ < 4; ++i_) *(u32x4*)(sA_ + (sr + i_ * 64) * PITCH + scv * 8) = ra[S][i_]; \
;     _Pragma("unroll") for (int i_ = 0; i_ < 2; ++i_) *(u32x4*)(sB_ + (sr + i_ * 64) * PITCH + scv * 8) = rb[S][i_]; } while (0)
; template <class Epi>
; DI void gemm_tile(char* smem, const bf16_t* __restrict__ A0, int lda0, int ksplit, const bf16_t* __restrict__ A1, int lda1,
;                   const bf16_t* __restrict__ Bt, int K, int row0, int col0, const Epi& epi, int tid) {
;     ...
;     for (int kt = 0; kt < nk; kt += 2) {
;       LWRITE(1, 1);
;       __builtin_amdgcn_sched_barrier(0);
;       GLOAD(1, (kt + 3 < last ? kt + 3 : last));
;       __builtin_amdgcn_sched_barrier(0);
;       COMPUTE(0);
;       __syncthreads();
;       LWRITE(0, 0);
;       __builtin_amdgcn_sched_barrier(0);
;       GLOAD(0, (kt + 4 < last ? kt + 4 : last));
;       __builtin_amdgcn_sched_barrier(0);
;       COMPUTE(1);
;       __syncthreads();
;     }
.Lg14_kloop:
	s_waitcnt vmcnt(6)
	s_waitcnt lgkmcnt(0)
	s_barrier
	v_add_u32_e32 v232, s98, v230
	v_add_u32_e32 v233, s98, v231
	s_add_u32 s11, s19, s101
	s_setprio 1
	v_mfma_f32_16x16x32_bf16 v[0:3], v[128:131], v[144:147], v[0:3]
	v_mfma_f32_16x16x32_bf16 v[4:7], v[132:135], v[144:147], v[4:7]
	v_mfma_f32_16x16x32_bf16 v[8:11], v[136:139], v[144:147], v[8:11]
	v_mfma_f32_16x16x32_bf16 v[12:15], v[140:143], v[144:147], v[12:15]
	ds_read_b128 v[176:179], v233 offset:0
	ds_read_b128 v[180:183], v233 offset:1024
	s_add_u32 m0, s11, 0
	s_nop 0
	global_load_lds_dwordx4 v224, s[0:1]
	v_mfma_f32_16x16x32_bf16 v[16:19], v[128:131], v[148:151], v[16:19]
	v_mfma_f32_16x16x32_bf16 v[20:23], v[132:135], v[148:151], v[20:23]
	v_mfma_f32_16x16x32_bf16 v[24:27], v[136:139], v[148:151], v[24:27]
	v_mfma_f32_16x16x32_bf16 v[28:31], v[140:143], v[148:151], v[28:31]
	ds_read_b128 v[184:187], v233 offset:2048
	ds_read_b128 v[188:191], v233 offset:3072
	s_add_u32 m0, s11, 4096
	s_nop 0
	global_load_lds_dwordx4 v225, s[0:1]
	v_mfma_f32_16x16x32_bf16 v[32:35], v[128:131], v[152:155], v[32:35]
	v_mfma_f32_16x16x32_bf16 v[36:39], v[132:135], v[152:155], v[36:39]
	v_mfma_f32_16x16x32_bf16 v[40:43], v[136:139], v[152:155], v[40:43]
	v_mfma_f32_16x16x32_bf16 v[44:47], v[140:143], v[152:155], v[44:47]
	ds_read_b128 v[192:195], v232 offset:0
	ds_read_b128 v[196:199], v232 offset:1024
	s_add_u32 m0, s11, 8192
	s_nop 0
	global_load_lds_dwordx4 v226, s[0:1]
	v_mfma_f32_16x16x32_bf16 v[48:51], v[128:131], v[156:159], v[48:51]
	v_mfma_f32_16x16x32_bf16 v[52:55], v[132:135], v[156:159], v[52:55]
	v_mfma_f32_16x16x32_bf16 v[56:59], v[136:139], v[156:159], v[56:59]
	v_mfma_f32_16x16x32_bf16 v[60:63], v[140:143], v[156:159], v[60:63]
	ds_read_b128 v[200:203], v232 offset:2048
	ds_read_b128 v[204:207], v232 offset:3072
	s_add_u32 m0, s11, 12288
	s_nop 0
	global_load_lds_dwordx4 v227, s[0:1]
	v_mfma_f32_16x16x32_bf16 v[64:67], v[128:131], v[160:163], v[64:67]
	v_mfma_f32_16x16x32_bf16 v[68:71], v[132:135], v[160:163], v[68:71]
	v_mfma_f32_16x16x32_bf16 v[72:75], v[136:139], v[160:163], v[72:75]
	v_mfma_f32_16x16x32_bf16 v[76:79], v[140:143], v[160:163], v[76:79]
	ds_read_b128 v[208:211], v232 offset:4096
	s_add_u32 m0, s11, 16384
	s_nop 0
	global_load_lds_dwordx4 v228, s[2:3]
	v_mfma_f32_16x16x32_bf16 v[80:83], v[128:131], v[164:167], v[80:83]
	v_mfma_f32_16x16x32_bf16 v[84:87], v[132:135], v[164:167], v[84:87]
	v_mfma_f32_16x16x32_bf16 v[88:91], v[136:139], v[164:167], v[88:91]
	v_mfma_f32_16x16x32_bf16 v[92:95], v[140:143], v[164:167], v[92:95]
	ds_read_b128 v[212:215], v232 offset:5120
	s_add_u32 m0, s11, 20480
	s_nop 0
	global_load_lds_dwordx4 v229, s[2:3]
	s_setprio 0
	v_mfma_f32_16x16x32_bf16 v[96:99], v[128:131], v[168:171], v[96:99]
	v_mfma_f32_16x16x32_bf16 v[100:103], v[132:135], v[168:171], v[100:103]
	v_mfma_f32_16x16x32_bf16 v[104:107], v[136:139], v[168:171], v[104:107]
	v_mfma_f32_16x16x32_bf16 v[108:111], v[140:143], v[168:171], v[108:111]
	ds_read_b128 v[216:219], v232 offset:6144
	s_add_u32 s0, s0, 64
	s_addc_u32 s1, s1, 0
	s_add_u32 s2, s2, 64
	s_addc_u32 s3, s3, 0
	s_add_u32 s100, s100, 1
	s_add_u32 s19, s19, 24576
	s_cmp_eq_u32 s19, 73728
	s_cselect_b32 s19, 0, s19
	s_add_u32 s98, s98, 24576
	s_cmp_eq_u32 s98, 73728
	s_cselect_b32 s98, 0, s98
	v_mfma_f32_16x16x32_bf16 v[112:115], v[128:131], v[172:175], v[112:115]
	v_mfma_f32_16x16x32_bf16 v[116:119], v[132:135], v[172:175], v[116:119]
	v_mfma_f32_16x16x32_bf16 v[120:123], v[136:139], v[172:175], v[120:123]
	v_mfma_f32_16x16x32_bf16 v[124:127], v[140:143], v[172:175], v[124:127]
	ds_read_b128 v[220:223], v232 offset:7168
	s_waitcnt vmcnt(6)
	s_waitcnt lgkmcnt(0)
	s_barrier
	v_add_u32_e32 v232, s98, v230
	v_add_u32_e32 v233, s98, v231
	s_add_u32 s11, s19, s101
	s_setprio 1
	v_mfma_f32_16x16x32_bf16 v[0:3], v[176:179], v[192:195], v[0:3]
	v_mfma_f32_16x16x32_bf16 v[4:7], v[180:183], v[192:195], v[4:7]
	v_mfma_f32_16x16x32_bf16 v[8:11], v[184:187], v[192:195], v[8:11]
	v_mfma_f32_16x16x32_bf16 v[12:15], v[188:191], v[192:195], v[12:15]
	ds_read_b128 v[128:131], v233 offset:0
	ds_read_b128 v[132:135], v233 offset:1024
	s_add_u32 m0, s11, 0
	s_nop 0
	global_load_lds_dwordx4 v224, s[0:1]
	v_mfma_f32_16x16x32_bf16 v[16:19], v[176:179], v[196:199], v[16:19]
	v_mfma_f32_16x16x32_bf16 v[20:23], v[180:183], v[196:199], v[20:23]
	v_mfma_f32_16x16x32_bf16 v[24:27], v[184:187], v[196:199], v[24:27]
	v_mfma_f32_16x16x32_bf16 v[28:31], v[188:191], v[196:199], v[28:31]
	ds_read_b128 v[136:139], v233 offset:2048
	ds_read_b128 v[140:143], v233 offset:3072
	s_add_u32 m0, s11, 4096
	s_nop 0
	global_load_lds_dwordx4 v225, s[0:1]
	v_mfma_f32_16x16x32_bf16 v[32:35], v[176:179], v[200:203], v[32:35]
	v_mfma_f32_16x16x32_bf16 v[36:39], v[180:183], v[200:203], v[36:39]
	v_mfma_f32_16x16x32_bf16 v[40:43], v[184:187], v[200:203], v[40:43]
	v_mfma_f32_16x16x32_bf16 v[44:47], v[188:191], v[200:203], v[44:47]
	ds_read_b128 v[144:147], v232 offset:0
	ds_read_b128 v[148:151], v232 offset:1024
	s_add_u32 m0, s11, 8192
	s_nop 0
	global_load_lds_dwordx4 v226, s[0:1]
	v_mfma_f32_16x16x32_bf16 v[48:51], v[176:179], v[204:207], v[48:51]
	v_mfma_f32_16x16x32_bf16 v[52:55], v[180:183], v[204:207], v[52:55]
	v_mfma_f32_16x16x32_bf16 v[56:59], v[184:187], v[204:207], v[56:59]
	v_mfma_f32_16x16x32_bf16 v[60:63], v[188:191], v[204:207], v[60:63]
	ds_read_b128 v[152:155], v232 offset:2048
	ds_read_b128 v[156:159], v232 offset:3072
	s_add_u32 m0, s11, 12288
	s_nop 0
	global_load_lds_dwordx4 v227, s[0:1]
	v_mfma_f32_16x16x32_bf16 v[64:67], v[176:179], v[208:211], v[64:67]
	v_mfma_f32_16x16x32_bf16 v[68:71], v[180:183], v[208:211], v[68:71]
; #define LWRITE(S, buf) do { bf16_t* sA_ = sbase + (buf) * BUF; bf16_t* sB_ = sA_ + 256 * PITCH; \
;     _Pragma("unroll") for (int i_ = 0; i_ < 4; ++i_) *(u32x4*)(sA_ + (sr + i_ * 64) * PITCH + scv * 8) = ra[S][i_]; \
;     _Pragma("unroll") for (int i_ = 0; i_ < 2; ++i_) *(u32x4*)(sB_ + (sr + i_ * 64) * PITCH + scv * 8) = rb[S][i_]; } while (0)
; template <class Epi>
; DI void gemm_tile(char* smem, const bf16_t* __restrict__ A0, int lda0, int ksplit, const bf16_t* __restrict__ A1, int lda1,
;                   const bf16_t* __restrict__ Bt, int K, int row0, int col0, const Epi& epi, int tid) {
;     ...
;     for (int kt = 0; kt < nk; kt += 2) {
;       LWRITE(1, 1);
;       __builtin_amdgcn_sched_barrier(0);
;       GLOAD(1, (kt + 3 < last ? kt + 3 : last));
;       __builtin_amdgcn_sched_barrier(0);
;       COMPUTE(0);
;       __syncthreads();
;       LWRITE(0, 0);
;       __builtin_amdgcn_sched_barrier(0);
;       GLOAD(0, (kt + 4 < last ? kt + 4 : last));
;       __builtin_amdgcn_sched_barrier(0);
;       COMPUTE(1);
;       __syncthreads();
;     }
	v_mfma_f32_16x16x32_bf16 v[72:75], v[184:187], v[208:211], v[72:75]
	v_mfma_f32_16x16x32_bf16 v[76:79], v[188:191], v[208:211], v[76:79]
	ds_read_b128 v[160:163], v232 offset:4096
	s_add_u32 m0, s11, 16384
	s_nop 0
	global_load_lds_dwordx4 v228, s[2:3]
	v_mfma_f32_16x16x32_bf16 v[80:83], v[176:179], v[212:215], v[80:83]
	v_mfma_f32_16x16x32_bf16 v[84:87], v[180:183], v[212:215], v[84:87]
	v_mfma_f32_16x16x32_bf16 v[88:91], v[184:187], v[212:215], v[88:91]
	v_mfma_f32_16x16x32_bf16 v[92:95], v[188:191], v[212:215], v[92:95]
	ds_read_b128 v[164:167], v232 offset:5120
	s_add_u32 m0, s11, 20480
	s_nop 0
	global_load_lds_dwordx4 v229, s[2:3]
	s_setprio 0
	v_mfma_f32_16x16x32_bf16 v[96:99], v[176:179], v[216:219], v[96:99]
	v_mfma_f32_16x16x32_bf16 v[100:103], v[180:183], v[216:219], v[100:103]
	v_mfma_f32_16x16x32_bf16 v[104:107], v[184:187], v[216:219], v[104:107]
	v_mfma_f32_16x16x32_bf16 v[108:111], v[188:191], v[216:219], v[108:111]
	ds_read_b128 v[168:171], v232 offset:6144
	s_add_u32 s0, s0, 64
	s_addc_u32 s1, s1, 0
	s_add_u32 s2, s2, 64
	s_addc_u32 s3, s3, 0
	s_add_u32 s100, s100, 1
	s_add_u32 s19, s19, 24576
	s_cmp_eq_u32 s19, 73728
	s_cselect_b32 s19, 0, s19
	s_add_u32 s98, s98, 24576
	s_cmp_eq_u32 s98, 73728
	s_cselect_b32 s98, 0, s98
	v_mfma_f32_16x16x32_bf16 v[112:115], v[176:179], v[220:223], v[112:115]
	v_mfma_f32_16x16x32_bf16 v[116:119], v[180:183], v[220:223], v[116:119]
	v_mfma_f32_16x16x32_bf16 v[120:123], v[184:187], v[220:223], v[120:123]
	v_mfma_f32_16x16x32_bf16 v[124:127], v[188:191], v[220:223], v[124:127]
	ds_read_b128 v[172:175], v232 offset:7168
	s_add_u32 s99, s99, 2
	s_cmp_lt_u32 s99, 12
	s_cbranch_scc1 .Lg14_kloop
	s_waitcnt vmcnt(6)
	s_waitcnt lgkmcnt(0)
	s_barrier
	v_add_u32_e32 v232, s98, v230
	v_add_u32_e32 v233, s98, v231
	s_add_u32 s11, s19, s101
	s_setprio 1
	v_mfma_f32_16x16x32_bf16 v[0:3], v[128:131], v[144:147], v[0:3]
	v_mfma_f32_16x16x32_bf16 v[4:7], v[132:135], v[144:147], v[4:7]
	v_mfma_f32_16x16x32_bf16 v[8:11], v[136:139], v[144:147], v[8:11]
	v_mfma_f32_16x16x32_bf16 v[12:15], v[140:143], v[144:147], v[12:15]
	ds_read_b128 v[176:179], v233 offset:0
	ds_read_b128 v[180:183], v233 offset:1024
	s_add_u32 m0, s11, 0
	s_nop 0
	global_load_lds_dwordx4 v224, s[0:1]
	v_mfma_f32_16x16x32_bf16 v[16:19], v[128:131], v[148:151], v[16:19]
	v_mfma_f32_16x16x32_bf16 v[20:23], v[132:135], v[148:151], v[20:23]
	v_mfma_f32_16x16x32_bf16 v[24:27], v[136:139], v[148:151], v[24:27]
	v_mfma_f32_16x16x32_bf16 v[28:31], v[140:143], v[148:151], v[28:31]
	ds_read_b128 v[184:187], v233 offset:2048
	ds_read_b128 v[188:191], v233 offset:3072
	s_add_u32 m0, s11, 4096
	s_nop 0
	global_load_lds_dwordx4 v225, s[0:1]
	v_mfma_f32_16x16x32_bf16 v[32:35], v[128:131], v[152:155], v[32:35]
	v_mfma_f32_16x16x32_bf16 v[36:39], v[132:135], v[152:155], v[36:39]
	v_mfma_f32_16x16x32_bf16 v[40:43], v[136:139], v[152:155], v[40:43]
	v_mfma_f32_16x16x32_bf16 v[44:47], v[140:143], v[152:155], v[44:47]
	ds_read_b128 v[192:195], v232 offset:0
	ds_read_b128 v[196:199], v232 offset:1024
	s_add_u32 m0, s11, 8192
	s_nop 0
	global_load_lds_dwordx4 v226, s[0:1]
	v_mfma_f32_16x16x32_bf16 v[48:51], v[128:131], v[156:159], v[48:51]
	v_mfma_f32_16x16x32_bf16 v[52:55], v[132:135], v[156:159], v[52:55]
	v_mfma_f32_16x16x32_bf16 v[56:59], v[136:139], v[156:159], v[56:59]
	v_mfma_f32_16x16x32_bf16 v[60:63], v[140:143], v[156:159], v[60:63]
	ds_read_b128 v[200:203], v232 offset:2048
	ds_read_b128 v[204:207], v232 offset:3072
	s_add_u32 m0, s11, 12288
	s_nop 0
	global_load_lds_dwordx4 v227, s[0:1]
	v_mfma_f32_16x16x32_bf16 v[64:67], v[128:131], v[160:163], v[64:67]
	v_mfma_f32_16x16x32_bf16 v[68:71], v[132:135], v[160:163], v[68:71]
	v_mfma_f32_16x16x32_bf16 v[72:75], v[136:139], v[160:163], v[72:75]
	v_mfma_f32_16x16x32_bf16 v[76:79], v[140:143], v[160:163], v[76:79]
	ds_read_b128 v[208:211], v232 offset:4096
	s_add_u32 m0, s11, 16384
	s_nop 0
	global_load_lds_dwordx4 v228, s[2:3]
	v_mfma_f32_16x16x32_bf16 v[80:83], v[128:131], v[164:167], v[80:83]
	v_mfma_f32_16x16x32_bf16 v[84:87], v[132:135], v[164:167], v[84:87]
	v_mfma_f32_16x16x32_bf16 v[88:91], v[136:139], v[164:167], v[88:91]
	v_mfma_f32_16x16x32_bf16 v[92:95], v[140:143], v[164:167], v[92:95]
	ds_read_b128 v[212:215], v232 offset:5120
	s_add_u32 m0, s11, 20480
	s_nop 0
	global_load_lds_dwordx4 v229, s[2:3]
	s_setprio 0
	v_mfma_f32_16x16x32_bf16 v[96:99], v[128:131], v[168:171], v[96:99]
	v_mfma_f32_16x16x32_bf16 v[100:103], v[132:135], v[168:171], v[100:103]
	v_mfma_f32_16x16x32_bf16 v[104:107], v[136:139], v[168:171], v[104:107]
	v_mfma_f32_16x16x32_bf16 v[108:111], v[140:143], v[168:171], v[108:111]
	ds_read_b128 v[216:219], v232 offset:6144
	s_add_u32 s0, s0, 64
	s_addc_u32 s1, s1, 0
	s_add_u32 s2, s2, 64
	s_addc_u32 s3, s3, 0
	s_add_u32 s100, s100, 1
	s_add_u32 s19, s19, 24576
	s_cmp_eq_u32 s19, 73728
	s_cselect_b32 s19, 0, s19
	s_add_u32 s98, s98, 24576
	s_cmp_eq_u32 s98, 73728
	s_cselect_b32 s98, 0, s98
	v_mfma_f32_16x16x32_bf16 v[112:115], v[128:131], v[172:175], v[112:115]
	v_mfma_f32_16x16x32_bf16 v[116:119], v[132:135], v[172:175], v[116:119]
	v_mfma_f32_16x16x32_bf16 v[120:123], v[136:139], v[172:175], v[120:123]
	v_mfma_f32_16x16x32_bf16 v[124:127], v[140:143], v[172:175], v[124:127]
	ds_read_b128 v[220:223], v232 offset:7168
	s_waitcnt vmcnt(6)
	s_waitcnt lgkmcnt(0)
	s_barrier
; #define LWRITE(S, buf) do { bf16_t* sA_ = sbase + (buf) * BUF; bf16_t* sB_ = sA_ + 256 * PITCH; \
;     _Pragma("unroll") for (int i_ = 0; i_ < 4; ++i_) *(u32x4*)(sA_ + (sr + i_ * 64) * PITCH + scv * 8) = ra[S][i_]; \
;     _Pragma("unroll") for (int i_ = 0; i_ < 2; ++i_) *(u32x4*)(sB_ + (sr + i_ * 64) * PITCH + scv * 8) = rb[S][i_]; } while (0)
; template <class Epi>
; DI void gemm_tile(char* smem, const bf16_t* __restrict__ A0, int lda0, int ksplit, const bf16_t* __restrict__ A1, int lda1,
;                   const bf16_t* __restrict__ Bt, int K, int row0, int col0, const Epi& epi, int tid) {
;     ...
;     for (int kt = 0; kt < nk; kt += 2) {
;       LWRITE(1, 1);
;       __builtin_amdgcn_sched_barrier(0);
;       GLOAD(1, (kt + 3 < last ? kt + 3 : last));
;       __builtin_amdgcn_sched_barrier(0);
;       COMPUTE(0);
;       __syncthreads();
;       LWRITE(0, 0);
;       __builtin_amdgcn_sched_barrier(0);
;       GLOAD(0, (kt + 4 < last ? kt + 4 : last));
;       __builtin_amdgcn_sched_barrier(0);
;       COMPUTE(1);
;       __syncthreads();
;     }
	v_add_u32_e32 v232, s98, v230
	v_add_u32_e32 v233, s98, v231
	s_setprio 1
	v_mfma_f32_16x16x32_bf16 v[0:3], v[176:179], v[192:195], v[0:3]
	v_mfma_f32_16x16x32_bf16 v[4:7], v[180:183], v[192:195], v[4:7]
	v_mfma_f32_16x16x32_bf16 v[8:11], v[184:187], v[192:195], v[8:11]
	v_mfma_f32_16x16x32_bf16 v[12:15], v[188:191], v[192:195], v[12:15]
	ds_read_b128 v[128:131], v233 offset:0
	ds_read_b128 v[132:135], v233 offset:1024
	v_mfma_f32_16x16x32_bf16 v[16:19], v[176:179], v[196:199], v[16:19]
	v_mfma_f32_16x16x32_bf16 v[20:23], v[180:183], v[196:199], v[20:23]
	v_mfma_f32_16x16x32_bf16 v[24:27], v[184:187], v[196:199], v[24:27]
	v_mfma_f32_16x16x32_bf16 v[28:31], v[188:191], v[196:199], v[28:31]
	ds_read_b128 v[136:139], v233 offset:2048
	ds_read_b128 v[140:143], v233 offset:3072
	v_mfma_f32_16x16x32_bf16 v[32:35], v[176:179], v[200:203], v[32:35]
	v_mfma_f32_16x16x32_bf16 v[36:39], v[180:183], v[200:203], v[36:39]
	v_mfma_f32_16x16x32_bf16 v[40:43], v[184:187], v[200:203], v[40:43]
	v_mfma_f32_16x16x32_bf16 v[44:47], v[188:191], v[200:203], v[44:47]
	ds_read_b128 v[144:147], v232 offset:0
	ds_read_b128 v[148:151], v232 offset:1024
	v_mfma_f32_16x16x32_bf16 v[48:51], v[176:179], v[204:207], v[48:51]
	v_mfma_f32_16x16x32_bf16 v[52:55], v[180:183], v[204:207], v[52:55]
	v_mfma_f32_16x16x32_bf16 v[56:59], v[184:187], v[204:207], v[56:59]
	v_mfma_f32_16x16x32_bf16 v[60:63], v[188:191], v[204:207], v[60:63]
	ds_read_b128 v[152:155], v232 offset:2048
	ds_read_b128 v[156:159], v232 offset:3072
	v_mfma_f32_16x16x32_bf16 v[64:67], v[176:179], v[208:211], v[64:67]
	v_mfma_f32_16x16x32_bf16 v[68:71], v[180:183], v[208:211], v[68:71]
	v_mfma_f32_16x16x32_bf16 v[72:75], v[184:187], v[208:211], v[72:75]
	v_mfma_f32_16x16x32_bf16 v[76:79], v[188:191], v[208:211], v[76:79]
	ds_read_b128 v[160:163], v232 offset:4096
	v_mfma_f32_16x16x32_bf16 v[80:83], v[176:179], v[212:215], v[80:83]
	v_mfma_f32_16x16x32_bf16 v[84:87], v[180:183], v[212:215], v[84:87]
	v_mfma_f32_16x16x32_bf16 v[88:91], v[184:187], v[212:215], v[88:91]
	v_mfma_f32_16x16x32_bf16 v[92:95], v[188:191], v[212:215], v[92:95]
	ds_read_b128 v[164:167], v232 offset:5120
	s_setprio 0
	v_mfma_f32_16x16x32_bf16 v[96:99], v[176:179], v[216:219], v[96:99]
	v_mfma_f32_16x16x32_bf16 v[100:103], v[180:183], v[216:219], v[100:103]
	v_mfma_f32_16x16x32_bf16 v[104:107], v[184:187], v[216:219], v[104:107]
	v_mfma_f32_16x16x32_bf16 v[108:111], v[188:191], v[216:219], v[108:111]
	ds_read_b128 v[168:171], v232 offset:6144
	s_add_u32 s98, s98, 24576
	s_cmp_eq_u32 s98, 73728
	s_cselect_b32 s98, 0, s98
	v_mfma_f32_16x16x32_bf16 v[112:115], v[176:179], v[220:223], v[112:115]
	v_mfma_f32_16x16x32_bf16 v[116:119], v[180:183], v[220:223], v[116:119]
	v_mfma_f32_16x16x32_bf16 v[120:123], v[184:187], v[220:223], v[120:123]
	v_mfma_f32_16x16x32_bf16 v[124:127], v[188:191], v[220:223], v[124:127]
	ds_read_b128 v[172:175], v232 offset:7168
	s_waitcnt vmcnt(0)
	s_waitcnt lgkmcnt(0)
	s_barrier
; #define LWRITE(S, buf) do { bf16_t* sA_ = sbase + (buf) * BUF; bf16_t* sB_ = sA_ + 256 * PITCH; \
;     _Pragma("unroll") for (int i_ = 0; i_ < 4; ++i_) *(u32x4*)(sA_ + (sr + i_ * 64) * PITCH + scv * 8) = ra[S][i_]; \
;     _Pragma("unroll") for (int i_ = 0; i_ < 2; ++i_) *(u32x4*)(sB_ + (sr + i_ * 64) * PITCH + scv * 8) = rb[S][i_]; } while (0)
; template <class Epi>
; DI void gemm_tile(char* smem, const bf16_t* __restrict__ A0, int lda0, int ksplit, const bf16_t* __restrict__ A1, int lda1,
;                   const bf16_t* __restrict__ Bt, int K, int row0, int col0, const Epi& epi, int tid) {
;     ...
;     for (int kt = 0; kt < nk; kt += 2) {
;       LWRITE(1, 1);
;       __builtin_amdgcn_sched_barrier(0);
;       GLOAD(1, (kt + 3 < last ? kt + 3 : last));
;       __builtin_amdgcn_sched_barrier(0);
;       COMPUTE(0);
;       __syncthreads();
;       LWRITE(0, 0);
;       __builtin_amdgcn_sched_barrier(0);
;       GLOAD(0, (kt + 4 < last ? kt + 4 : last));
;       __builtin_amdgcn_sched_barrier(0);
;       COMPUTE(1);
;       __syncthreads();
;     }
	v_add_u32_e32 v232, s98, v230
	v_add_u32_e32 v233, s98, v231
	s_setprio 1
	v_mfma_f32_16x16x32_bf16 v[0:3], v[128:131], v[144:147], v[0:3]
	v_mfma_f32_16x16x32_bf16 v[4:7], v[132:135], v[144:147], v[4:7]
	v_mfma_f32_16x16x32_bf16 v[8:11], v[136:139], v[144:147], v[8:11]
	v_mfma_f32_16x16x32_bf16 v[12:15], v[140:143], v[144:147], v[12:15]
	ds_read_b128 v[176:179], v233 offset:0
	ds_read_b128 v[180:183], v233 offset:1024
	v_mfma_f32_16x16x32_bf16 v[16:19], v[128:131], v[148:151], v[16:19]
	v_mfma_f32_16x16x32_bf16 v[20:23], v[132:135], v[148:151], v[20:23]
	v_mfma_f32_16x16x32_bf16 v[24:27], v[136:139], v[148:151], v[24:27]
	v_mfma_f32_16x16x32_bf16 v[28:31], v[140:143], v[148:151], v[28:31]
	ds_read_b128 v[184:187], v233 offset:2048
	ds_read_b128 v[188:191], v233 offset:3072
	v_mfma_f32_16x16x32_bf16 v[32:35], v[128:131], v[152:155], v[32:35]
	v_mfma_f32_16x16x32_bf16 v[36:39], v[132:135], v[152:155], v[36:39]
	v_mfma_f32_16x16x32_bf16 v[40:43], v[136:139], v[152:155], v[40:43]
	v_mfma_f32_16x16x32_bf16 v[44:47], v[140:143], v[152:155], v[44:47]
	ds_read_b128 v[192:195], v232 offset:0
	ds_read_b128 v[196:199], v232 offset:1024
	v_mfma_f32_16x16x32_bf16 v[48:51], v[128:131], v[156:159], v[48:51]
	v_mfma_f32_16x16x32_bf16 v[52:55], v[132:135], v[156:159], v[52:55]
	v_mfma_f32_16x16x32_bf16 v[56:59], v[136:139], v[156:159], v[56:59]
	v_mfma_f32_16x16x32_bf16 v[60:63], v[140:143], v[156:159], v[60:63]
	ds_read_b128 v[200:203], v232 offset:2048
	ds_read_b128 v[204:207], v232 offset:3072
	v_mfma_f32_16x16x32_bf16 v[64:67], v[128:131], v[160:163], v[64:67]
	v_mfma_f32_16x16x32_bf16 v[68:71], v[132:135], v[160:163], v[68:71]
	v_mfma_f32_16x16x32_bf16 v[72:75], v[136:139], v[160:163], v[72:75]
	v_mfma_f32_16x16x32_bf16 v[76:79], v[140:143], v[160:163], v[76:79]
	ds_read_b128 v[208:211], v232 offset:4096
	v_mfma_f32_16x16x32_bf16 v[80:83], v[128:131], v[164:167], v[80:83]
	v_mfma_f32_16x16x32_bf16 v[84:87], v[132:135], v[164:167], v[84:87]
	v_mfma_f32_16x16x32_bf16 v[88:91], v[136:139], v[164:167], v[88:91]
	v_mfma_f32_16x16x32_bf16 v[92:95], v[140:143], v[164:167], v[92:95]
	ds_read_b128 v[212:215], v232 offset:5120
	s_setprio 0
	v_mfma_f32_16x16x32_bf16 v[96:99], v[128:131], v[168:171], v[96:99]
	v_mfma_f32_16x16x32_bf16 v[100:103], v[132:135], v[168:171], v[100:103]
	v_mfma_f32_16x16x32_bf16 v[104:107], v[136:139], v[168:171], v[104:107]
	v_mfma_f32_16x16x32_bf16 v[108:111], v[140:143], v[168:171], v[108:111]
	ds_read_b128 v[216:219], v232 offset:6144
	s_add_u32 s98, s98, 24576
	s_cmp_eq_u32 s98, 73728
	s_cselect_b32 s98, 0, s98
	v_mfma_f32_16x16x32_bf16 v[112:115], v[128:131], v[172:175], v[112:115]
	v_mfma_f32_16x16x32_bf16 v[116:119], v[132:135], v[172:175], v[116:119]
	v_mfma_f32_16x16x32_bf16 v[120:123], v[136:139], v[172:175], v[120:123]
	v_mfma_f32_16x16x32_bf16 v[124:127], v[140:143], v[172:175], v[124:127]
	ds_read_b128 v[220:223], v232 offset:7168
	s_waitcnt lgkmcnt(0)
	s_barrier
	s_setprio 1
	v_mfma_f32_16x16x32_bf16 v[0:3], v[176:179], v[192:195], v[0:3]
	v_mfma_f32_16x16x32_bf16 v[4:7], v[180:183], v[192:195], v[4:7]
	v_mfma_f32_16x16x32_bf16 v[8:11], v[184:187], v[192:195], v[8:11]
	v_mfma_f32_16x16x32_bf16 v[12:15], v[188:191], v[192:195], v[12:15]
	v_mfma_f32_16x16x32_bf16 v[16:19], v[176:179], v[196:199], v[16:19]
	v_mfma_f32_16x16x32_bf16 v[20:23], v[180:183], v[196:199], v[20:23]
	v_mfma_f32_16x16x32_bf16 v[24:27], v[184:187], v[196:199], v[24:27]
	v_mfma_f32_16x16x32_bf16 v[28:31], v[188:191], v[196:199], v[28:31]
	v_mfma_f32_16x16x32_bf16 v[32:35], v[176:179], v[200:203], v[32:35]
	v_mfma_f32_16x16x32_bf16 v[36:39], v[180:183], v[200:203], v[36:39]
	v_mfma_f32_16x16x32_bf16 v[40:43], v[184:187], v[200:203], v[40:43]
	v_mfma_f32_16x16x32_bf16 v[44:47], v[188:191], v[200:203], v[44:47]
	v_mfma_f32_16x16x32_bf16 v[48:51], v[176:179], v[204:207], v[48:51]
	v_mfma_f32_16x16x32_bf16 v[52:55], v[180:183], v[204:207], v[52:55]
	v_mfma_f32_16x16x32_bf16 v[56:59], v[184:187], v[204:207], v[56:59]
	v_mfma_f32_16x16x32_bf16 v[60:63], v[188:191], v[204:207], v[60:63]
	v_mfma_f32_16x16x32_bf16 v[64:67], v[176:179], v[208:211], v[64:67]
	v_mfma_f32_16x16x32_bf16 v[68:71], v[180:183], v[208:211], v[68:71]
	v_mfma_f32_16x16x32_bf16 v[72:75], v[184:187], v[208:211], v[72:75]
	v_mfma_f32_16x16x32_bf16 v[76:79], v[188:191], v[208:211], v[76:79]
	v_mfma_f32_16x16x32_bf16 v[80:83], v[176:179], v[212:215], v[80:83]
	v_mfma_f32_16x16x32_bf16 v[84:87], v[180:183], v[212:215], v[84:87]
	v_mfma_f32_16x16x32_bf16 v[88:91], v[184:187], v[212:215], v[88:91]
	v_mfma_f32_16x16x32_bf16 v[92:95], v[188:191], v[212:215], v[92:95]
	s_setprio 0
	v_mfma_f32_16x16x32_bf16 v[96:99], v[176:179], v[216:219], v[96:99]
	v_mfma_f32_16x16x32_bf16 v[100:103], v[180:183], v[216:219], v[100:103]
	v_mfma_f32_16x16x32_bf16 v[104:107], v[184:187], v[216:219], v[104:107]
	v_mfma_f32_16x16x32_bf16 v[108:111], v[188:191], v[216:219], v[108:111]
	v_mfma_f32_16x16x32_bf16 v[112:115], v[176:179], v[220:223], v[112:115]
	v_mfma_f32_16x16x32_bf16 v[116:119], v[180:183], v[220:223], v[116:119]
	v_mfma_f32_16x16x32_bf16 v[120:123], v[184:187], v[220:223], v[120:123]
	v_mfma_f32_16x16x32_bf16 v[124:127], v[188:191], v[220:223], v[124:127]
	s_branch .Lg14_epi
